# MLA: four row-sum accumulators instead of two (longer dependent distance)
# speedup vs baseline: 1.0061x; 1.0061x over previous
.Lmla_restart:
	s_lshr_b32 s17, s2, 4
	s_and_b32 s18, s2, 15
	s_mul_i32 s19, s17, 0xcc000
	s_add_u32 s4, s78, s19
	s_addc_u32 s5, s79, 0
	s_mul_i32 s19, s17, 0x88000
	s_add_u32 s19, s19, 0x1a00000
	s_add_u32 s10, s78, s19
	s_addc_u32 s11, s79, 0
	s_lshl_b32 s19, s17, 12
	s_lshl_b32 s20, s18, 8
	s_add_u32 s19, s19, s20
	s_mul_i32 s19, s19, 0xc0
	s_add_u32 s19, s19, 0x1400000
	s_add_u32 s12, s80, s19
	s_addc_u32 s13, s81, 0
	s_lshr_b32 s19, s17, 3
	s_lshl_b32 s19, s19, 12
	s_add_u32 s19, s19, s20
	s_lshl_b32 s19, s19, 10
	s_and_b32 s21, s17, 7
	s_lshl_b32 s21, s21, 7
	s_add_u32 s19, s19, s21
	s_add_u32 s19, s19, 0x7900000
	s_add_u32 s14, s80, s19
	s_addc_u32 s15, s81, 0
	global_load_dwordx4 v[98:101], v237, s[12:13] offset:0
	global_load_dwordx4 v[102:105], v237, s[12:13] offset:32
	global_load_dwordx4 v[106:109], v237, s[12:13] offset:64
	global_load_dwordx4 v[110:113], v237, s[12:13] offset:96
	global_load_dwordx4 v[114:117], v237, s[12:13] offset:128
	global_load_dwordx4 v[118:121], v237, s[12:13] offset:160
	global_load_dwordx4 v[34:37], v226, s[4:5]
	global_load_dwordx4 v[38:41], v227, s[4:5]
	global_load_dwordx4 v[42:45], v228, s[4:5]
	global_load_dwordx4 v[46:49], v229, s[10:11]
	s_add_u32 s4, s4, 0x6000
	s_addc_u32 s5, s5, 0
	global_load_dwordx4 v[50:53], v226, s[4:5]
	global_load_dwordx4 v[54:57], v227, s[4:5]
	global_load_dwordx4 v[58:61], v228, s[4:5]
	global_load_dwordx4 v[62:65], v229, s[10:11] offset:128
	global_load_dwordx4 v[216:219], v229, s[10:11] offset:256
	s_add_u32 s4, s4, 0x6000
	s_addc_u32 s5, s5, 0
	s_add_u32 s10, s10, 0x180
	s_addc_u32 s11, s11, 0
	v_mov_b32_e32 v2, 0
	v_mov_b32_e32 v3, 0
	v_mov_b32_e32 v4, 0
	v_mov_b32_e32 v5, 0
	v_mov_b32_e32 v6, 0
	v_mov_b32_e32 v7, 0
	v_mov_b32_e32 v8, 0
	v_mov_b32_e32 v9, 0
	v_mov_b32_e32 v10, 0
	v_mov_b32_e32 v11, 0
	v_mov_b32_e32 v12, 0
	v_mov_b32_e32 v13, 0
	v_mov_b32_e32 v14, 0
	v_mov_b32_e32 v15, 0
	v_mov_b32_e32 v16, 0
	v_mov_b32_e32 v17, 0
	v_mov_b32_e32 v18, 0
	v_mov_b32_e32 v19, 0
	v_mov_b32_e32 v20, 0
	v_mov_b32_e32 v21, 0
	v_mov_b32_e32 v22, 0
	v_mov_b32_e32 v23, 0
	v_mov_b32_e32 v24, 0
	v_mov_b32_e32 v25, 0
	v_mov_b32_e32 v26, 0
	v_mov_b32_e32 v27, 0
	v_mov_b32_e32 v28, 0
	v_mov_b32_e32 v29, 0
	v_mov_b32_e32 v30, 0
	v_mov_b32_e32 v31, 0
	v_mov_b32_e32 v32, 0
	v_mov_b32_e32 v33, 0
	v_mov_b32_e32 v122, 0
	v_mov_b32_e32 v123, 0
	v_mov_b32_e32 v124, 0
	v_mov_b32_e32 v125, 0
	v_mov_b32_e32 v126, 0
	v_mov_b32_e32 v127, 0
	v_mov_b32_e32 v128, 0
	v_mov_b32_e32 v129, 0
	v_mov_b32_e32 v130, 0
	v_mov_b32_e32 v131, 0
	v_mov_b32_e32 v132, 0
	v_mov_b32_e32 v133, 0
	v_mov_b32_e32 v134, 0
	v_mov_b32_e32 v135, 0
	v_mov_b32_e32 v136, 0
	v_mov_b32_e32 v137, 0
	v_mov_b32_e32 v230, 0
	v_mov_b32_e32 v231, 0
	v_mov_b32_e32 v232, 0
	v_mov_b32_e32 v240, 0
	v_mov_b32_e32 v241, 0
	s_waitcnt vmcnt(5)
	ds_write_b128 v222, v[34:37]
	ds_write_b128 v223, v[38:41]
	ds_write_b128 v224, v[42:45]
	ds_write_b64 v225, v[46:47]
	ds_write_b64 v225, v[48:49] offset:16
	s_waitcnt vmcnt(1)
	ds_write_b128 v222, v[50:53] offset:26624
	ds_write_b128 v223, v[54:57] offset:26624
	ds_write_b128 v224, v[58:61] offset:26624
	ds_write_b64 v225, v[62:63] offset:9216
	ds_write_b64 v225, v[64:65] offset:9232
	s_waitcnt lgkmcnt(0)
	s_barrier

.Lmla_loop:
	v_exp_f32_e32 v34, v34
	v_exp_f32_e32 v35, v35
	v_exp_f32_e32 v36, v36
	s_waitcnt lgkmcnt(4)
	v_mfma_f32_32x32x16_bf16 v[66:81], v[138:141], v[98:101], v[122:137]
	ds_read_b128 v[138:141], v220 offset:13408
	v_exp_f32_e32 v37, v37
	v_add_f32_e32 v231, v231, v34
	v_add_f32_e32 v232, v232, v35
	v_exp_f32_e32 v38, v38
	v_mfma_f32_32x32x16_bf16 v[82:97], v[142:145], v[98:101], v[122:137]
	ds_read_b128 v[142:145], v220 offset:20064
	v_exp_f32_e32 v39, v39
	v_add_f32_e32 v240, v240, v36
	v_add_f32_e32 v241, v241, v37
	s_waitcnt lgkmcnt(4)
	v_mfma_f32_32x32x16_bf16 v[66:81], v[146:149], v[102:105], v[66:81]
	ds_read_b128 v[146:149], v220 offset:13440
	global_load_dwordx4 v[200:203], v226, s[4:5]
	global_load_dwordx4 v[204:207], v227, s[4:5]
	global_load_dwordx4 v[208:211], v228, s[4:5]
	s_add_u32 s4, s4, 0x6000
	s_addc_u32 s5, s5, 0
	global_load_dwordx4 v[212:215], v229, s[10:11]
	s_add_u32 s10, s10, 0x80
	s_addc_u32 s11, s11, 0
	v_exp_f32_e32 v40, v40
	v_exp_f32_e32 v41, v41
	v_add_f32_e32 v231, v231, v38
	v_add_f32_e32 v232, v232, v39
	v_mfma_f32_32x32x16_bf16 v[82:97], v[150:153], v[102:105], v[82:97]
	ds_read_b128 v[150:153], v220 offset:20096
	v_add_f32_e32 v240, v240, v40
	v_add_f32_e32 v241, v241, v41
	v_cvt_pk_bf16_f32 v34, v34, v35
	v_cvt_pk_bf16_f32 v35, v36, v37
	v_cvt_pk_bf16_f32 v36, v38, v39
	s_waitcnt lgkmcnt(4)
	v_mfma_f32_32x32x16_bf16 v[66:81], v[154:157], v[106:109], v[66:81]
	ds_read_b128 v[154:157], v220 offset:13472
	v_cvt_pk_bf16_f32 v37, v40, v41
	v_exp_f32_e32 v42, v42
	v_exp_f32_e32 v43, v43
	v_mfma_f32_32x32x16_bf16 v[82:97], v[158:161], v[106:109], v[82:97]
	ds_read_b128 v[158:161], v220 offset:20128
	v_exp_f32_e32 v44, v44
	v_exp_f32_e32 v45, v45
	v_add_f32_e32 v231, v231, v42
	v_add_f32_e32 v232, v232, v43
	s_waitcnt lgkmcnt(4)
	v_mfma_f32_32x32x16_bf16 v[66:81], v[138:141], v[110:113], v[66:81]
	ds_read_b128 v[162:165], v221 offset:0
	v_exp_f32_e32 v46, v46
	v_exp_f32_e32 v47, v47
	v_add_f32_e32 v240, v240, v44
	v_mfma_f32_32x32x16_bf16 v[82:97], v[142:145], v[110:113], v[82:97]
	ds_read_b128 v[166:169], v221 offset:4608
	v_add_f32_e32 v241, v241, v45
	v_exp_f32_e32 v48, v48
	v_exp_f32_e32 v49, v49
	s_waitcnt lgkmcnt(4)
	v_mfma_f32_32x32x16_bf16 v[66:81], v[146:149], v[114:117], v[66:81]
	ds_read_b128 v[170:173], v221 offset:32
	v_add_f32_e32 v231, v231, v46
	v_add_f32_e32 v232, v232, v47
	v_add_f32_e32 v240, v240, v48
	v_add_f32_e32 v241, v241, v49
	v_cvt_pk_bf16_f32 v42, v42, v43
	v_cvt_pk_bf16_f32 v43, v44, v45
	v_mfma_f32_32x32x16_bf16 v[82:97], v[150:153], v[114:117], v[82:97]
	ds_read_b128 v[174:177], v221 offset:4640
	v_cvt_pk_bf16_f32 v44, v46, v47
	v_cvt_pk_bf16_f32 v45, v48, v49
	v_exp_f32_e32 v50, v50
	v_exp_f32_e32 v51, v51
	s_waitcnt lgkmcnt(4)
	v_mfma_f32_32x32x16_bf16 v[66:81], v[154:157], v[118:121], v[66:81]
	ds_read_b128 v[180:183], v221 offset:64
	v_exp_f32_e32 v52, v52
	v_exp_f32_e32 v53, v53
	v_mfma_f32_32x32x16_bf16 v[82:97], v[158:161], v[118:121], v[82:97]
	ds_read_b128 v[184:187], v221 offset:4672
	v_add_f32_e32 v231, v231, v50
	v_add_f32_e32 v232, v232, v51
	v_exp_f32_e32 v54, v54
	v_exp_f32_e32 v55, v55
	s_waitcnt lgkmcnt(4)
	v_mfma_f32_32x32x16_bf16 v[2:17], v[162:165], v[34:37], v[2:17]
	ds_read_b128 v[188:191], v221 offset:96
	v_add_f32_e32 v240, v240, v52
	v_add_f32_e32 v241, v241, v53
	v_exp_f32_e32 v56, v56
	v_exp_f32_e32 v57, v57
	v_mfma_f32_32x32x16_bf16 v[18:33], v[166:169], v[34:37], v[18:33]
	ds_read_b128 v[192:195], v221 offset:4704
	v_add_f32_e32 v231, v231, v54
	v_add_f32_e32 v232, v232, v55
	v_add_f32_e32 v240, v240, v56
	v_add_f32_e32 v241, v241, v57
	s_waitcnt lgkmcnt(4)
	v_mfma_f32_32x32x16_bf16 v[2:17], v[170:173], v[42:45], v[2:17]
	v_cvt_pk_bf16_f32 v50, v50, v51
	v_cvt_pk_bf16_f32 v51, v52, v53
	v_cvt_pk_bf16_f32 v52, v54, v55
	v_cvt_pk_bf16_f32 v53, v56, v57
	v_exp_f32_e32 v58, v58
	v_mfma_f32_32x32x16_bf16 v[18:33], v[174:177], v[42:45], v[18:33]
	s_waitcnt vmcnt(4)
	ds_write_b64 v225, v[216:217] offset:18432
	ds_write_b64 v225, v[218:219] offset:18448
	v_exp_f32_e32 v59, v59
	v_exp_f32_e32 v60, v60
	v_exp_f32_e32 v61, v61
	s_waitcnt lgkmcnt(4)
	v_mfma_f32_32x32x16_bf16 v[2:17], v[180:183], v[50:53], v[2:17]
	v_add_f32_e32 v231, v231, v58
	v_add_f32_e32 v232, v232, v59
	v_exp_f32_e32 v62, v62
	v_mfma_f32_32x32x16_bf16 v[18:33], v[184:187], v[50:53], v[18:33]
	v_exp_f32_e32 v63, v63
	v_add_f32_e32 v240, v240, v60
	v_add_f32_e32 v241, v241, v61
	v_exp_f32_e32 v64, v64
	v_exp_f32_e32 v65, v65
	v_add_f32_e32 v231, v231, v62
	v_add_f32_e32 v232, v232, v63
	v_add_f32_e32 v240, v240, v64
	v_add_f32_e32 v241, v241, v65
	v_cvt_pk_bf16_f32 v58, v58, v59
	v_cvt_pk_bf16_f32 v59, v60, v61
	v_cvt_pk_bf16_f32 v60, v62, v63
	v_cvt_pk_bf16_f32 v61, v64, v65
	s_waitcnt lgkmcnt(2)
	s_nop 0
	v_mfma_f32_32x32x16_bf16 v[2:17], v[188:191], v[58:61], v[2:17]
	v_mfma_f32_32x32x16_bf16 v[18:33], v[192:195], v[58:61], v[18:33]
	ds_read_b128 v[138:141], v220 offset:26624
	ds_read_b128 v[142:145], v220 offset:33280
	ds_read_b128 v[146:149], v220 offset:26656
	ds_read_b128 v[150:153], v220 offset:33312
	ds_read_b128 v[154:157], v220 offset:26688
	ds_read_b128 v[158:161], v220 offset:33344
	s_waitcnt lgkmcnt(6)
	s_barrier
	v_exp_f32_e32 v66, v66
	v_exp_f32_e32 v67, v67
	v_exp_f32_e32 v68, v68
	s_waitcnt lgkmcnt(4)
	v_mfma_f32_32x32x16_bf16 v[34:49], v[138:141], v[98:101], v[122:137]
	ds_read_b128 v[138:141], v220 offset:26720
	v_exp_f32_e32 v69, v69
	v_add_f32_e32 v231, v231, v66
	v_add_f32_e32 v232, v232, v67
	v_exp_f32_e32 v70, v70
	v_mfma_f32_32x32x16_bf16 v[50:65], v[142:145], v[98:101], v[122:137]
	ds_read_b128 v[142:145], v220 offset:33376
	v_exp_f32_e32 v71, v71
	v_add_f32_e32 v240, v240, v68
	v_add_f32_e32 v241, v241, v69
	s_waitcnt lgkmcnt(4)
	v_mfma_f32_32x32x16_bf16 v[34:49], v[146:149], v[102:105], v[34:49]
	ds_read_b128 v[146:149], v220 offset:26752
	global_load_dwordx4 v[216:219], v229, s[10:11]
	s_add_u32 s10, s10, 0x80
	s_addc_u32 s11, s11, 0
	v_exp_f32_e32 v72, v72
	v_exp_f32_e32 v73, v73
	v_add_f32_e32 v231, v231, v70
	v_add_f32_e32 v232, v232, v71
	v_mfma_f32_32x32x16_bf16 v[50:65], v[150:153], v[102:105], v[50:65]
	ds_read_b128 v[150:153], v220 offset:33408
	v_add_f32_e32 v240, v240, v72
	v_add_f32_e32 v241, v241, v73
	v_cvt_pk_bf16_f32 v66, v66, v67
	v_cvt_pk_bf16_f32 v67, v68, v69
	v_cvt_pk_bf16_f32 v68, v70, v71
	s_waitcnt lgkmcnt(4)
	v_mfma_f32_32x32x16_bf16 v[34:49], v[154:157], v[106:109], v[34:49]
	ds_read_b128 v[154:157], v220 offset:26784
	v_cvt_pk_bf16_f32 v69, v72, v73
	v_exp_f32_e32 v74, v74
	v_exp_f32_e32 v75, v75
	v_mfma_f32_32x32x16_bf16 v[50:65], v[158:161], v[106:109], v[50:65]
	ds_read_b128 v[158:161], v220 offset:33440
	v_exp_f32_e32 v76, v76
	v_exp_f32_e32 v77, v77
	v_add_f32_e32 v231, v231, v74
	v_add_f32_e32 v232, v232, v75
	s_waitcnt lgkmcnt(4)
	v_mfma_f32_32x32x16_bf16 v[34:49], v[138:141], v[110:113], v[34:49]
	ds_read_b128 v[162:165], v221 offset:9216
	v_exp_f32_e32 v78, v78
	v_exp_f32_e32 v79, v79
	v_add_f32_e32 v240, v240, v76
	v_mfma_f32_32x32x16_bf16 v[50:65], v[142:145], v[110:113], v[50:65]
	ds_read_b128 v[166:169], v221 offset:13824
	v_add_f32_e32 v241, v241, v77
	v_exp_f32_e32 v80, v80
	v_exp_f32_e32 v81, v81
	s_waitcnt lgkmcnt(4)
	v_mfma_f32_32x32x16_bf16 v[34:49], v[146:149], v[114:117], v[34:49]
	ds_read_b128 v[170:173], v221 offset:9248
	v_add_f32_e32 v231, v231, v78
	v_add_f32_e32 v232, v232, v79
	v_add_f32_e32 v240, v240, v80
	v_add_f32_e32 v241, v241, v81
	v_cvt_pk_bf16_f32 v74, v74, v75
	v_cvt_pk_bf16_f32 v75, v76, v77
	v_mfma_f32_32x32x16_bf16 v[50:65], v[150:153], v[114:117], v[50:65]
	ds_read_b128 v[174:177], v221 offset:13856
	v_cvt_pk_bf16_f32 v76, v78, v79
	v_cvt_pk_bf16_f32 v77, v80, v81
	v_exp_f32_e32 v82, v82
	v_exp_f32_e32 v83, v83
	s_waitcnt lgkmcnt(4)
	v_mfma_f32_32x32x16_bf16 v[34:49], v[154:157], v[118:121], v[34:49]
	ds_read_b128 v[180:183], v221 offset:9280
	v_exp_f32_e32 v84, v84
	v_exp_f32_e32 v85, v85
	v_mfma_f32_32x32x16_bf16 v[50:65], v[158:161], v[118:121], v[50:65]
	ds_read_b128 v[184:187], v221 offset:13888
	v_add_f32_e32 v231, v231, v82
	v_add_f32_e32 v232, v232, v83
	v_exp_f32_e32 v86, v86
	v_exp_f32_e32 v87, v87
	s_waitcnt lgkmcnt(4)
	v_mfma_f32_32x32x16_bf16 v[2:17], v[162:165], v[66:69], v[2:17]
	ds_read_b128 v[188:191], v221 offset:9312
	v_add_f32_e32 v240, v240, v84
	v_add_f32_e32 v241, v241, v85
	v_exp_f32_e32 v88, v88
	v_exp_f32_e32 v89, v89
	v_mfma_f32_32x32x16_bf16 v[18:33], v[166:169], v[66:69], v[18:33]
	ds_read_b128 v[192:195], v221 offset:13920
	v_add_f32_e32 v231, v231, v86
	v_add_f32_e32 v232, v232, v87
	v_add_f32_e32 v240, v240, v88
	v_add_f32_e32 v241, v241, v89
	s_waitcnt lgkmcnt(4)
	v_mfma_f32_32x32x16_bf16 v[2:17], v[170:173], v[74:77], v[2:17]
	v_cvt_pk_bf16_f32 v82, v82, v83
	v_cvt_pk_bf16_f32 v83, v84, v85
	v_cvt_pk_bf16_f32 v84, v86, v87
	v_cvt_pk_bf16_f32 v85, v88, v89
	v_exp_f32_e32 v90, v90
	v_mfma_f32_32x32x16_bf16 v[18:33], v[174:177], v[74:77], v[18:33]
	s_waitcnt vmcnt(1)
	ds_write_b128 v222, v[200:203] offset:0
	ds_write_b128 v223, v[204:207] offset:0
	ds_write_b128 v224, v[208:211] offset:0
	ds_write_b64 v225, v[212:213] offset:27648
	ds_write_b64 v225, v[214:215] offset:27664
	v_exp_f32_e32 v91, v91
	v_exp_f32_e32 v92, v92
	v_exp_f32_e32 v93, v93
	s_waitcnt lgkmcnt(7)
	v_mfma_f32_32x32x16_bf16 v[2:17], v[180:183], v[82:85], v[2:17]
	v_add_f32_e32 v231, v231, v90
	v_add_f32_e32 v232, v232, v91
	v_exp_f32_e32 v94, v94
	v_mfma_f32_32x32x16_bf16 v[18:33], v[184:187], v[82:85], v[18:33]
	v_exp_f32_e32 v95, v95
	v_add_f32_e32 v240, v240, v92
	v_add_f32_e32 v241, v241, v93
	v_exp_f32_e32 v96, v96
	v_exp_f32_e32 v97, v97
	v_add_f32_e32 v231, v231, v94
	v_add_f32_e32 v232, v232, v95
	v_add_f32_e32 v240, v240, v96
	v_add_f32_e32 v241, v241, v97
	v_cvt_pk_bf16_f32 v90, v90, v91
	v_cvt_pk_bf16_f32 v91, v92, v93
	v_cvt_pk_bf16_f32 v92, v94, v95
	v_cvt_pk_bf16_f32 v93, v96, v97
	s_waitcnt lgkmcnt(5)
	s_nop 0
	v_mfma_f32_32x32x16_bf16 v[2:17], v[188:191], v[90:93], v[2:17]
	v_mfma_f32_32x32x16_bf16 v[18:33], v[192:195], v[90:93], v[18:33]
	ds_read_b128 v[138:141], v220 offset:39936
	ds_read_b128 v[142:145], v220 offset:46592
	ds_read_b128 v[146:149], v220 offset:39968
	ds_read_b128 v[150:153], v220 offset:46624
	ds_read_b128 v[154:157], v220 offset:40000
	ds_read_b128 v[158:161], v220 offset:46656
	s_waitcnt lgkmcnt(6)
	s_barrier
	v_exp_f32_e32 v34, v34
	v_exp_f32_e32 v35, v35
	v_exp_f32_e32 v36, v36
	s_waitcnt lgkmcnt(4)
	v_mfma_f32_32x32x16_bf16 v[66:81], v[138:141], v[98:101], v[122:137]
	ds_read_b128 v[138:141], v220 offset:40032
	v_exp_f32_e32 v37, v37
	v_add_f32_e32 v231, v231, v34
	v_add_f32_e32 v232, v232, v35
	v_exp_f32_e32 v38, v38
	v_mfma_f32_32x32x16_bf16 v[82:97], v[142:145], v[98:101], v[122:137]
	ds_read_b128 v[142:145], v220 offset:46688
	v_exp_f32_e32 v39, v39
	v_add_f32_e32 v240, v240, v36
	v_add_f32_e32 v241, v241, v37
	s_waitcnt lgkmcnt(4)
	v_mfma_f32_32x32x16_bf16 v[66:81], v[146:149], v[102:105], v[66:81]
	ds_read_b128 v[146:149], v220 offset:40064
	global_load_dwordx4 v[200:203], v226, s[4:5]
	global_load_dwordx4 v[204:207], v227, s[4:5]
	global_load_dwordx4 v[208:211], v228, s[4:5]
	s_add_u32 s4, s4, 0x6000
	s_addc_u32 s5, s5, 0
	global_load_dwordx4 v[212:215], v229, s[10:11]
	s_add_u32 s10, s10, 0x80
	s_addc_u32 s11, s11, 0
	v_exp_f32_e32 v40, v40
	v_exp_f32_e32 v41, v41
	v_add_f32_e32 v231, v231, v38
	v_add_f32_e32 v232, v232, v39
	v_mfma_f32_32x32x16_bf16 v[82:97], v[150:153], v[102:105], v[82:97]
	ds_read_b128 v[150:153], v220 offset:46720
	v_add_f32_e32 v240, v240, v40
	v_add_f32_e32 v241, v241, v41
	v_cvt_pk_bf16_f32 v34, v34, v35
	v_cvt_pk_bf16_f32 v35, v36, v37
	v_cvt_pk_bf16_f32 v36, v38, v39
	s_waitcnt lgkmcnt(4)
	v_mfma_f32_32x32x16_bf16 v[66:81], v[154:157], v[106:109], v[66:81]
	ds_read_b128 v[154:157], v220 offset:40096
	v_cvt_pk_bf16_f32 v37, v40, v41
	v_exp_f32_e32 v42, v42
	v_exp_f32_e32 v43, v43
	v_mfma_f32_32x32x16_bf16 v[82:97], v[158:161], v[106:109], v[82:97]
	ds_read_b128 v[158:161], v220 offset:46752
	v_exp_f32_e32 v44, v44
	v_exp_f32_e32 v45, v45
	v_add_f32_e32 v231, v231, v42
	v_add_f32_e32 v232, v232, v43
	s_waitcnt lgkmcnt(4)
	v_mfma_f32_32x32x16_bf16 v[66:81], v[138:141], v[110:113], v[66:81]
	ds_read_b128 v[162:165], v221 offset:18432
	v_exp_f32_e32 v46, v46
	v_exp_f32_e32 v47, v47
	v_add_f32_e32 v240, v240, v44
	v_mfma_f32_32x32x16_bf16 v[82:97], v[142:145], v[110:113], v[82:97]
	ds_read_b128 v[166:169], v221 offset:23040
	v_add_f32_e32 v241, v241, v45
	v_exp_f32_e32 v48, v48
	v_exp_f32_e32 v49, v49
	s_waitcnt lgkmcnt(4)
	v_mfma_f32_32x32x16_bf16 v[66:81], v[146:149], v[114:117], v[66:81]
	ds_read_b128 v[170:173], v221 offset:18464
	v_add_f32_e32 v231, v231, v46
	v_add_f32_e32 v232, v232, v47
	v_add_f32_e32 v240, v240, v48
	v_add_f32_e32 v241, v241, v49
	v_cvt_pk_bf16_f32 v42, v42, v43
	v_cvt_pk_bf16_f32 v43, v44, v45
	v_mfma_f32_32x32x16_bf16 v[82:97], v[150:153], v[114:117], v[82:97]
	ds_read_b128 v[174:177], v221 offset:23072
	v_cvt_pk_bf16_f32 v44, v46, v47
	v_cvt_pk_bf16_f32 v45, v48, v49
	v_exp_f32_e32 v50, v50
	v_exp_f32_e32 v51, v51
	s_waitcnt lgkmcnt(4)
	v_mfma_f32_32x32x16_bf16 v[66:81], v[154:157], v[118:121], v[66:81]
	ds_read_b128 v[180:183], v221 offset:18496
	v_exp_f32_e32 v52, v52
	v_exp_f32_e32 v53, v53
	v_mfma_f32_32x32x16_bf16 v[82:97], v[158:161], v[118:121], v[82:97]
	ds_read_b128 v[184:187], v221 offset:23104
	v_add_f32_e32 v231, v231, v50
	v_add_f32_e32 v232, v232, v51
	v_exp_f32_e32 v54, v54
	v_exp_f32_e32 v55, v55
	s_waitcnt lgkmcnt(4)
	v_mfma_f32_32x32x16_bf16 v[2:17], v[162:165], v[34:37], v[2:17]
	ds_read_b128 v[188:191], v221 offset:18528
	v_add_f32_e32 v240, v240, v52
	v_add_f32_e32 v241, v241, v53
	v_exp_f32_e32 v56, v56
	v_exp_f32_e32 v57, v57
	v_mfma_f32_32x32x16_bf16 v[18:33], v[166:169], v[34:37], v[18:33]
	ds_read_b128 v[192:195], v221 offset:23136
	v_add_f32_e32 v231, v231, v54
	v_add_f32_e32 v232, v232, v55
	v_add_f32_e32 v240, v240, v56
	v_add_f32_e32 v241, v241, v57
	s_waitcnt lgkmcnt(4)
	v_mfma_f32_32x32x16_bf16 v[2:17], v[170:173], v[42:45], v[2:17]
	v_cvt_pk_bf16_f32 v50, v50, v51
	v_cvt_pk_bf16_f32 v51, v52, v53
	v_cvt_pk_bf16_f32 v52, v54, v55
	v_cvt_pk_bf16_f32 v53, v56, v57
	v_exp_f32_e32 v58, v58
	v_mfma_f32_32x32x16_bf16 v[18:33], v[174:177], v[42:45], v[18:33]
	s_waitcnt vmcnt(4)
	ds_write_b64 v225, v[216:217] offset:0
	ds_write_b64 v225, v[218:219] offset:16
	v_exp_f32_e32 v59, v59
	v_exp_f32_e32 v60, v60
	v_exp_f32_e32 v61, v61
	s_waitcnt lgkmcnt(4)
	v_mfma_f32_32x32x16_bf16 v[2:17], v[180:183], v[50:53], v[2:17]
	v_add_f32_e32 v231, v231, v58
	v_add_f32_e32 v232, v232, v59
	v_exp_f32_e32 v62, v62
	v_mfma_f32_32x32x16_bf16 v[18:33], v[184:187], v[50:53], v[18:33]
	v_exp_f32_e32 v63, v63
	v_add_f32_e32 v240, v240, v60
	v_add_f32_e32 v241, v241, v61
	v_exp_f32_e32 v64, v64
	v_exp_f32_e32 v65, v65
	v_add_f32_e32 v231, v231, v62
	v_add_f32_e32 v232, v232, v63
	v_add_f32_e32 v240, v240, v64
	v_add_f32_e32 v241, v241, v65
	v_cvt_pk_bf16_f32 v58, v58, v59
	v_cvt_pk_bf16_f32 v59, v60, v61
	v_cvt_pk_bf16_f32 v60, v62, v63
	v_cvt_pk_bf16_f32 v61, v64, v65
	s_waitcnt lgkmcnt(2)
	s_nop 0
	v_mfma_f32_32x32x16_bf16 v[2:17], v[188:191], v[58:61], v[2:17]
	v_mfma_f32_32x32x16_bf16 v[18:33], v[192:195], v[58:61], v[18:33]
	ds_read_b128 v[138:141], v220 offset:0
	ds_read_b128 v[142:145], v220 offset:6656
	ds_read_b128 v[146:149], v220 offset:32
	ds_read_b128 v[150:153], v220 offset:6688
	ds_read_b128 v[154:157], v220 offset:64
	ds_read_b128 v[158:161], v220 offset:6720
	s_waitcnt lgkmcnt(6)
	s_barrier
	v_exp_f32_e32 v66, v66
	v_exp_f32_e32 v67, v67
	v_exp_f32_e32 v68, v68
	s_waitcnt lgkmcnt(4)
	v_mfma_f32_32x32x16_bf16 v[34:49], v[138:141], v[98:101], v[122:137]
	ds_read_b128 v[138:141], v220 offset:96
	v_exp_f32_e32 v69, v69
	v_add_f32_e32 v231, v231, v66
	v_add_f32_e32 v232, v232, v67
	v_exp_f32_e32 v70, v70
	v_mfma_f32_32x32x16_bf16 v[50:65], v[142:145], v[98:101], v[122:137]
	ds_read_b128 v[142:145], v220 offset:6752
	v_exp_f32_e32 v71, v71
	v_add_f32_e32 v240, v240, v68
	v_add_f32_e32 v241, v241, v69
	s_waitcnt lgkmcnt(4)
	v_mfma_f32_32x32x16_bf16 v[34:49], v[146:149], v[102:105], v[34:49]
	ds_read_b128 v[146:149], v220 offset:128
	global_load_dwordx4 v[216:219], v229, s[10:11]
	s_add_u32 s10, s10, 0x80
	s_addc_u32 s11, s11, 0
	v_exp_f32_e32 v72, v72
	v_exp_f32_e32 v73, v73
	v_add_f32_e32 v231, v231, v70
	v_add_f32_e32 v232, v232, v71
	v_mfma_f32_32x32x16_bf16 v[50:65], v[150:153], v[102:105], v[50:65]
	ds_read_b128 v[150:153], v220 offset:6784
	v_add_f32_e32 v240, v240, v72
	v_add_f32_e32 v241, v241, v73
	v_cvt_pk_bf16_f32 v66, v66, v67
	v_cvt_pk_bf16_f32 v67, v68, v69
	v_cvt_pk_bf16_f32 v68, v70, v71
	s_waitcnt lgkmcnt(4)
	v_mfma_f32_32x32x16_bf16 v[34:49], v[154:157], v[106:109], v[34:49]
	ds_read_b128 v[154:157], v220 offset:160
	v_cvt_pk_bf16_f32 v69, v72, v73
	v_exp_f32_e32 v74, v74
	v_exp_f32_e32 v75, v75
	v_mfma_f32_32x32x16_bf16 v[50:65], v[158:161], v[106:109], v[50:65]
	ds_read_b128 v[158:161], v220 offset:6816
	v_exp_f32_e32 v76, v76
	v_exp_f32_e32 v77, v77
	v_add_f32_e32 v231, v231, v74
	v_add_f32_e32 v232, v232, v75
	s_waitcnt lgkmcnt(4)
	v_mfma_f32_32x32x16_bf16 v[34:49], v[138:141], v[110:113], v[34:49]
	ds_read_b128 v[162:165], v221 offset:27648
	v_exp_f32_e32 v78, v78
	v_exp_f32_e32 v79, v79
	v_add_f32_e32 v240, v240, v76
	v_mfma_f32_32x32x16_bf16 v[50:65], v[142:145], v[110:113], v[50:65]
	ds_read_b128 v[166:169], v221 offset:32256
	v_add_f32_e32 v241, v241, v77
	v_exp_f32_e32 v80, v80
	v_exp_f32_e32 v81, v81
	s_waitcnt lgkmcnt(4)
	v_mfma_f32_32x32x16_bf16 v[34:49], v[146:149], v[114:117], v[34:49]
	ds_read_b128 v[170:173], v221 offset:27680
	v_add_f32_e32 v231, v231, v78
	v_add_f32_e32 v232, v232, v79
	v_add_f32_e32 v240, v240, v80
	v_add_f32_e32 v241, v241, v81
	v_cvt_pk_bf16_f32 v74, v74, v75
	v_cvt_pk_bf16_f32 v75, v76, v77
	v_mfma_f32_32x32x16_bf16 v[50:65], v[150:153], v[114:117], v[50:65]
	ds_read_b128 v[174:177], v221 offset:32288
	v_cvt_pk_bf16_f32 v76, v78, v79
	v_cvt_pk_bf16_f32 v77, v80, v81
	v_exp_f32_e32 v82, v82
	v_exp_f32_e32 v83, v83
	s_waitcnt lgkmcnt(4)
	v_mfma_f32_32x32x16_bf16 v[34:49], v[154:157], v[118:121], v[34:49]
	ds_read_b128 v[180:183], v221 offset:27712
	v_exp_f32_e32 v84, v84
	v_exp_f32_e32 v85, v85
	v_mfma_f32_32x32x16_bf16 v[50:65], v[158:161], v[118:121], v[50:65]
	ds_read_b128 v[184:187], v221 offset:32320
	v_add_f32_e32 v231, v231, v82
	v_add_f32_e32 v232, v232, v83
	v_exp_f32_e32 v86, v86
	v_exp_f32_e32 v87, v87
	s_waitcnt lgkmcnt(4)
	v_mfma_f32_32x32x16_bf16 v[2:17], v[162:165], v[66:69], v[2:17]
	ds_read_b128 v[188:191], v221 offset:27744
	v_add_f32_e32 v240, v240, v84
	v_add_f32_e32 v241, v241, v85
	v_exp_f32_e32 v88, v88
	v_exp_f32_e32 v89, v89
	v_mfma_f32_32x32x16_bf16 v[18:33], v[166:169], v[66:69], v[18:33]
	ds_read_b128 v[192:195], v221 offset:32352
	v_add_f32_e32 v231, v231, v86
	v_add_f32_e32 v232, v232, v87
	v_add_f32_e32 v240, v240, v88
	v_add_f32_e32 v241, v241, v89
	s_waitcnt lgkmcnt(4)
	v_mfma_f32_32x32x16_bf16 v[2:17], v[170:173], v[74:77], v[2:17]
	v_cvt_pk_bf16_f32 v82, v82, v83
	v_cvt_pk_bf16_f32 v83, v84, v85
	v_cvt_pk_bf16_f32 v84, v86, v87
	v_cvt_pk_bf16_f32 v85, v88, v89
	v_exp_f32_e32 v90, v90
	v_mfma_f32_32x32x16_bf16 v[18:33], v[174:177], v[74:77], v[18:33]
	s_waitcnt vmcnt(1)
	ds_write_b128 v222, v[200:203] offset:26624
	ds_write_b128 v223, v[204:207] offset:26624
	ds_write_b128 v224, v[208:211] offset:26624
	ds_write_b64 v225, v[212:213] offset:9216
	ds_write_b64 v225, v[214:215] offset:9232
	v_exp_f32_e32 v91, v91
	v_exp_f32_e32 v92, v92
	v_exp_f32_e32 v93, v93
	s_waitcnt lgkmcnt(7)
	v_mfma_f32_32x32x16_bf16 v[2:17], v[180:183], v[82:85], v[2:17]
	v_add_f32_e32 v231, v231, v90
	v_add_f32_e32 v232, v232, v91
	v_exp_f32_e32 v94, v94
	v_mfma_f32_32x32x16_bf16 v[18:33], v[184:187], v[82:85], v[18:33]
	v_exp_f32_e32 v95, v95
	v_add_f32_e32 v240, v240, v92
	v_add_f32_e32 v241, v241, v93
	v_exp_f32_e32 v96, v96
	v_exp_f32_e32 v97, v97
	v_add_f32_e32 v231, v231, v94
	v_add_f32_e32 v232, v232, v95
	v_add_f32_e32 v240, v240, v96
	v_add_f32_e32 v241, v241, v97
	v_cvt_pk_bf16_f32 v90, v90, v91
	v_cvt_pk_bf16_f32 v91, v92, v93
	v_cvt_pk_bf16_f32 v92, v94, v95
	v_cvt_pk_bf16_f32 v93, v96, v97
	s_waitcnt lgkmcnt(5)
	s_nop 0
	v_mfma_f32_32x32x16_bf16 v[2:17], v[188:191], v[90:93], v[2:17]
	v_mfma_f32_32x32x16_bf16 v[18:33], v[192:195], v[90:93], v[18:33]
	ds_read_b128 v[138:141], v220 offset:13312
	ds_read_b128 v[142:145], v220 offset:19968
	ds_read_b128 v[146:149], v220 offset:13344
	ds_read_b128 v[150:153], v220 offset:20000
	ds_read_b128 v[154:157], v220 offset:13376
	ds_read_b128 v[158:161], v220 offset:20032
	s_waitcnt lgkmcnt(6)
	s_barrier
	s_add_i32 s16, s16, -1
	s_cmp_lg_u32 s16, 0
	s_cbranch_scc1 .Lmla_loop
	v_exp_f32_e32 v34, v34
	v_exp_f32_e32 v35, v35
	v_exp_f32_e32 v36, v36
	s_waitcnt lgkmcnt(4)
	v_mfma_f32_32x32x16_bf16 v[66:81], v[138:141], v[98:101], v[122:137]
	ds_read_b128 v[138:141], v220 offset:13408
	v_exp_f32_e32 v37, v37
	v_add_f32_e32 v231, v231, v34
	v_add_f32_e32 v232, v232, v35
	v_exp_f32_e32 v38, v38
	v_mfma_f32_32x32x16_bf16 v[82:97], v[142:145], v[98:101], v[122:137]
	ds_read_b128 v[142:145], v220 offset:20064
	v_exp_f32_e32 v39, v39
	v_add_f32_e32 v240, v240, v36
	v_add_f32_e32 v241, v241, v37
	s_waitcnt lgkmcnt(4)
	v_mfma_f32_32x32x16_bf16 v[66:81], v[146:149], v[102:105], v[66:81]
	ds_read_b128 v[146:149], v220 offset:13440
	global_load_dwordx4 v[212:215], v229, s[10:11]
	s_add_u32 s10, s10, 0x80
	s_addc_u32 s11, s11, 0
	v_exp_f32_e32 v40, v40
	v_exp_f32_e32 v41, v41
	v_add_f32_e32 v231, v231, v38
	v_add_f32_e32 v232, v232, v39
	v_mfma_f32_32x32x16_bf16 v[82:97], v[150:153], v[102:105], v[82:97]
	ds_read_b128 v[150:153], v220 offset:20096
	v_add_f32_e32 v240, v240, v40
	v_add_f32_e32 v241, v241, v41
	v_cvt_pk_bf16_f32 v34, v34, v35
	v_cvt_pk_bf16_f32 v35, v36, v37
	v_cvt_pk_bf16_f32 v36, v38, v39
	s_waitcnt lgkmcnt(4)
	v_mfma_f32_32x32x16_bf16 v[66:81], v[154:157], v[106:109], v[66:81]
	ds_read_b128 v[154:157], v220 offset:13472
	v_cvt_pk_bf16_f32 v37, v40, v41
	v_exp_f32_e32 v42, v42
	v_exp_f32_e32 v43, v43
	v_mfma_f32_32x32x16_bf16 v[82:97], v[158:161], v[106:109], v[82:97]
	ds_read_b128 v[158:161], v220 offset:20128
	v_exp_f32_e32 v44, v44
	v_exp_f32_e32 v45, v45
	v_add_f32_e32 v231, v231, v42
	v_add_f32_e32 v232, v232, v43
	s_waitcnt lgkmcnt(4)
	v_mfma_f32_32x32x16_bf16 v[66:81], v[138:141], v[110:113], v[66:81]
	ds_read_b128 v[162:165], v221 offset:0
	v_exp_f32_e32 v46, v46
	v_exp_f32_e32 v47, v47
	v_add_f32_e32 v240, v240, v44
	v_mfma_f32_32x32x16_bf16 v[82:97], v[142:145], v[110:113], v[82:97]
	ds_read_b128 v[166:169], v221 offset:4608
	v_add_f32_e32 v241, v241, v45
	v_exp_f32_e32 v48, v48
	v_exp_f32_e32 v49, v49
	s_waitcnt lgkmcnt(4)
	v_mfma_f32_32x32x16_bf16 v[66:81], v[146:149], v[114:117], v[66:81]
	ds_read_b128 v[170:173], v221 offset:32
	v_add_f32_e32 v231, v231, v46
	v_add_f32_e32 v232, v232, v47
	v_add_f32_e32 v240, v240, v48
	v_add_f32_e32 v241, v241, v49
	v_cvt_pk_bf16_f32 v42, v42, v43
	v_cvt_pk_bf16_f32 v43, v44, v45
	v_mfma_f32_32x32x16_bf16 v[82:97], v[150:153], v[114:117], v[82:97]
	ds_read_b128 v[174:177], v221 offset:4640
	v_cvt_pk_bf16_f32 v44, v46, v47
	v_cvt_pk_bf16_f32 v45, v48, v49
	v_exp_f32_e32 v50, v50
	v_exp_f32_e32 v51, v51
	s_waitcnt lgkmcnt(4)
	v_mfma_f32_32x32x16_bf16 v[66:81], v[154:157], v[118:121], v[66:81]
	ds_read_b128 v[180:183], v221 offset:64
	v_exp_f32_e32 v52, v52
	v_exp_f32_e32 v53, v53
	v_mfma_f32_32x32x16_bf16 v[82:97], v[158:161], v[118:121], v[82:97]
	ds_read_b128 v[184:187], v221 offset:4672
	v_add_f32_e32 v231, v231, v50
	v_add_f32_e32 v232, v232, v51
	v_exp_f32_e32 v54, v54
	v_exp_f32_e32 v55, v55
	s_waitcnt lgkmcnt(4)
	v_mfma_f32_32x32x16_bf16 v[2:17], v[162:165], v[34:37], v[2:17]
	ds_read_b128 v[188:191], v221 offset:96
	v_add_f32_e32 v240, v240, v52
	v_add_f32_e32 v241, v241, v53
	v_exp_f32_e32 v56, v56
	v_exp_f32_e32 v57, v57
	v_mfma_f32_32x32x16_bf16 v[18:33], v[166:169], v[34:37], v[18:33]
	ds_read_b128 v[192:195], v221 offset:4704
	v_add_f32_e32 v231, v231, v54
	v_add_f32_e32 v232, v232, v55
	v_add_f32_e32 v240, v240, v56
	v_add_f32_e32 v241, v241, v57
	s_waitcnt lgkmcnt(4)
	v_mfma_f32_32x32x16_bf16 v[2:17], v[170:173], v[42:45], v[2:17]
	v_cvt_pk_bf16_f32 v50, v50, v51
	v_cvt_pk_bf16_f32 v51, v52, v53
	v_cvt_pk_bf16_f32 v52, v54, v55
	v_cvt_pk_bf16_f32 v53, v56, v57
	v_exp_f32_e32 v58, v58
	v_mfma_f32_32x32x16_bf16 v[18:33], v[174:177], v[42:45], v[18:33]
	s_waitcnt vmcnt(1)
	ds_write_b64 v225, v[216:217] offset:18432
	ds_write_b64 v225, v[218:219] offset:18448
	v_exp_f32_e32 v59, v59
	v_exp_f32_e32 v60, v60
	v_exp_f32_e32 v61, v61
	s_waitcnt lgkmcnt(4)
	v_mfma_f32_32x32x16_bf16 v[2:17], v[180:183], v[50:53], v[2:17]
	v_add_f32_e32 v231, v231, v58
	v_add_f32_e32 v232, v232, v59
	v_exp_f32_e32 v62, v62
	v_mfma_f32_32x32x16_bf16 v[18:33], v[184:187], v[50:53], v[18:33]
	v_exp_f32_e32 v63, v63
	v_add_f32_e32 v240, v240, v60
	v_add_f32_e32 v241, v241, v61
	v_exp_f32_e32 v64, v64
	v_exp_f32_e32 v65, v65
	v_add_f32_e32 v231, v231, v62
	v_add_f32_e32 v232, v232, v63
	v_add_f32_e32 v240, v240, v64
	v_add_f32_e32 v241, v241, v65
	v_cvt_pk_bf16_f32 v58, v58, v59
	v_cvt_pk_bf16_f32 v59, v60, v61
	v_cvt_pk_bf16_f32 v60, v62, v63
	v_cvt_pk_bf16_f32 v61, v64, v65
	s_waitcnt lgkmcnt(2)
	s_nop 0
	v_mfma_f32_32x32x16_bf16 v[2:17], v[188:191], v[58:61], v[2:17]
	v_mfma_f32_32x32x16_bf16 v[18:33], v[192:195], v[58:61], v[18:33]
	ds_read_b128 v[138:141], v220 offset:26624
	ds_read_b128 v[142:145], v220 offset:33280
	ds_read_b128 v[146:149], v220 offset:26656
	ds_read_b128 v[150:153], v220 offset:33312
	ds_read_b128 v[154:157], v220 offset:26688
	ds_read_b128 v[158:161], v220 offset:33344
	s_waitcnt lgkmcnt(6)
	s_barrier
	v_exp_f32_e32 v66, v66
	v_exp_f32_e32 v67, v67
	v_exp_f32_e32 v68, v68
	s_waitcnt lgkmcnt(4)
	v_mfma_f32_32x32x16_bf16 v[34:49], v[138:141], v[98:101], v[122:137]
	ds_read_b128 v[138:141], v220 offset:26720
	v_exp_f32_e32 v69, v69
	v_add_f32_e32 v231, v231, v66
	v_add_f32_e32 v232, v232, v67
	v_exp_f32_e32 v70, v70
	v_mfma_f32_32x32x16_bf16 v[50:65], v[142:145], v[98:101], v[122:137]
	ds_read_b128 v[142:145], v220 offset:33376
	v_exp_f32_e32 v71, v71
	v_add_f32_e32 v240, v240, v68
	v_add_f32_e32 v241, v241, v69
	s_waitcnt lgkmcnt(4)
	v_mfma_f32_32x32x16_bf16 v[34:49], v[146:149], v[102:105], v[34:49]
	ds_read_b128 v[146:149], v220 offset:26752
	v_exp_f32_e32 v72, v72
	v_exp_f32_e32 v73, v73
	v_add_f32_e32 v231, v231, v70
	v_add_f32_e32 v232, v232, v71
	v_mfma_f32_32x32x16_bf16 v[50:65], v[150:153], v[102:105], v[50:65]
	ds_read_b128 v[150:153], v220 offset:33408
	v_add_f32_e32 v240, v240, v72
	v_add_f32_e32 v241, v241, v73
	v_cvt_pk_bf16_f32 v66, v66, v67
	v_cvt_pk_bf16_f32 v67, v68, v69
	v_cvt_pk_bf16_f32 v68, v70, v71
	s_waitcnt lgkmcnt(4)
	v_mfma_f32_32x32x16_bf16 v[34:49], v[154:157], v[106:109], v[34:49]
	ds_read_b128 v[154:157], v220 offset:26784
	v_cvt_pk_bf16_f32 v69, v72, v73
	v_exp_f32_e32 v74, v74
	v_exp_f32_e32 v75, v75
	v_mfma_f32_32x32x16_bf16 v[50:65], v[158:161], v[106:109], v[50:65]
	ds_read_b128 v[158:161], v220 offset:33440
	v_exp_f32_e32 v76, v76
	v_exp_f32_e32 v77, v77
	v_add_f32_e32 v231, v231, v74
	v_add_f32_e32 v232, v232, v75
	s_waitcnt lgkmcnt(4)
	v_mfma_f32_32x32x16_bf16 v[34:49], v[138:141], v[110:113], v[34:49]
	ds_read_b128 v[162:165], v221 offset:9216
	v_exp_f32_e32 v78, v78
	v_exp_f32_e32 v79, v79
	v_add_f32_e32 v240, v240, v76
	v_mfma_f32_32x32x16_bf16 v[50:65], v[142:145], v[110:113], v[50:65]
	ds_read_b128 v[166:169], v221 offset:13824
	v_add_f32_e32 v241, v241, v77
	v_exp_f32_e32 v80, v80
	v_exp_f32_e32 v81, v81
	s_waitcnt lgkmcnt(4)
	v_mfma_f32_32x32x16_bf16 v[34:49], v[146:149], v[114:117], v[34:49]
	ds_read_b128 v[170:173], v221 offset:9248
	v_add_f32_e32 v231, v231, v78
	v_add_f32_e32 v232, v232, v79
	v_add_f32_e32 v240, v240, v80
	v_add_f32_e32 v241, v241, v81
	v_cvt_pk_bf16_f32 v74, v74, v75
	v_cvt_pk_bf16_f32 v75, v76, v77
	v_mfma_f32_32x32x16_bf16 v[50:65], v[150:153], v[114:117], v[50:65]
	ds_read_b128 v[174:177], v221 offset:13856
	v_cvt_pk_bf16_f32 v76, v78, v79
	v_cvt_pk_bf16_f32 v77, v80, v81
	v_exp_f32_e32 v82, v82
	v_exp_f32_e32 v83, v83
	s_waitcnt lgkmcnt(4)
	v_mfma_f32_32x32x16_bf16 v[34:49], v[154:157], v[118:121], v[34:49]
	ds_read_b128 v[180:183], v221 offset:9280
	v_exp_f32_e32 v84, v84
	v_exp_f32_e32 v85, v85
	v_mfma_f32_32x32x16_bf16 v[50:65], v[158:161], v[118:121], v[50:65]
	ds_read_b128 v[184:187], v221 offset:13888
	v_add_f32_e32 v231, v231, v82
	v_add_f32_e32 v232, v232, v83
	v_exp_f32_e32 v86, v86
	v_exp_f32_e32 v87, v87
	s_waitcnt lgkmcnt(4)
	v_mfma_f32_32x32x16_bf16 v[2:17], v[162:165], v[66:69], v[2:17]
	ds_read_b128 v[188:191], v221 offset:9312
	v_add_f32_e32 v240, v240, v84
	v_add_f32_e32 v241, v241, v85
	v_exp_f32_e32 v88, v88
	v_exp_f32_e32 v89, v89
	v_mfma_f32_32x32x16_bf16 v[18:33], v[166:169], v[66:69], v[18:33]
	ds_read_b128 v[192:195], v221 offset:13920
	v_add_f32_e32 v231, v231, v86
	v_add_f32_e32 v232, v232, v87
	v_add_f32_e32 v240, v240, v88
	v_add_f32_e32 v241, v241, v89
	s_waitcnt lgkmcnt(4)
	v_mfma_f32_32x32x16_bf16 v[2:17], v[170:173], v[74:77], v[2:17]
	v_cvt_pk_bf16_f32 v82, v82, v83
	v_cvt_pk_bf16_f32 v83, v84, v85
	v_cvt_pk_bf16_f32 v84, v86, v87
	v_cvt_pk_bf16_f32 v85, v88, v89
	v_exp_f32_e32 v90, v90
	v_mfma_f32_32x32x16_bf16 v[18:33], v[174:177], v[74:77], v[18:33]
	s_waitcnt vmcnt(0)
	ds_write_b64 v225, v[212:213] offset:27648
	ds_write_b64 v225, v[214:215] offset:27664
	v_exp_f32_e32 v91, v91
	v_exp_f32_e32 v92, v92
	v_exp_f32_e32 v93, v93
	s_waitcnt lgkmcnt(4)
	v_mfma_f32_32x32x16_bf16 v[2:17], v[180:183], v[82:85], v[2:17]
	v_add_f32_e32 v231, v231, v90
	v_add_f32_e32 v232, v232, v91
	v_exp_f32_e32 v94, v94
	v_mfma_f32_32x32x16_bf16 v[18:33], v[184:187], v[82:85], v[18:33]
	v_exp_f32_e32 v95, v95
	v_add_f32_e32 v240, v240, v92
	v_add_f32_e32 v241, v241, v93
	v_exp_f32_e32 v96, v96
	v_exp_f32_e32 v97, v97
	v_add_f32_e32 v231, v231, v94
	v_add_f32_e32 v232, v232, v95
	v_add_f32_e32 v240, v240, v96
	v_add_f32_e32 v241, v241, v97
	v_cvt_pk_bf16_f32 v90, v90, v91
	v_cvt_pk_bf16_f32 v91, v92, v93
	v_cvt_pk_bf16_f32 v92, v94, v95
	v_cvt_pk_bf16_f32 v93, v96, v97
	s_waitcnt lgkmcnt(2)
	s_nop 0
	v_mfma_f32_32x32x16_bf16 v[2:17], v[188:191], v[90:93], v[2:17]
	v_mfma_f32_32x32x16_bf16 v[18:33], v[192:195], v[90:93], v[18:33]
	ds_read_b128 v[138:141], v220 offset:39936
	ds_read_b128 v[142:145], v220 offset:46592
	ds_read_b128 v[146:149], v220 offset:39968
	ds_read_b128 v[150:153], v220 offset:46624
	ds_read_b128 v[154:157], v220 offset:40000
	ds_read_b128 v[158:161], v220 offset:46656
	s_waitcnt lgkmcnt(6)
	s_barrier
	global_load_dwordx2 v[200:201], v236, s[14:15] offset:0
	global_load_dwordx2 v[202:203], v236, s[14:15] offset:16
	global_load_dwordx2 v[204:205], v236, s[14:15] offset:32
	global_load_dwordx2 v[206:207], v236, s[14:15] offset:48
	global_load_dwordx2 v[208:209], v236, s[14:15] offset:64
	global_load_dwordx2 v[210:211], v236, s[14:15] offset:80
	global_load_dwordx2 v[212:213], v236, s[14:15] offset:96
	global_load_dwordx2 v[214:215], v236, s[14:15] offset:112
	v_exp_f32_e32 v34, v34
	v_exp_f32_e32 v35, v35
	v_exp_f32_e32 v36, v36
	s_waitcnt lgkmcnt(4)
	v_mfma_f32_32x32x16_bf16 v[66:81], v[138:141], v[98:101], v[122:137]
	ds_read_b128 v[138:141], v220 offset:40032
	v_exp_f32_e32 v37, v37
	v_add_f32_e32 v231, v231, v34
	v_add_f32_e32 v232, v232, v35
	v_exp_f32_e32 v38, v38
	v_mfma_f32_32x32x16_bf16 v[82:97], v[142:145], v[98:101], v[122:137]
	ds_read_b128 v[142:145], v220 offset:46688
	v_exp_f32_e32 v39, v39
	v_add_f32_e32 v240, v240, v36
	v_add_f32_e32 v241, v241, v37
	s_waitcnt lgkmcnt(4)
	v_mfma_f32_32x32x16_bf16 v[66:81], v[146:149], v[102:105], v[66:81]
	ds_read_b128 v[146:149], v220 offset:40064
	v_exp_f32_e32 v40, v40
	v_exp_f32_e32 v41, v41
	v_add_f32_e32 v231, v231, v38
	v_add_f32_e32 v232, v232, v39
	v_mfma_f32_32x32x16_bf16 v[82:97], v[150:153], v[102:105], v[82:97]
	ds_read_b128 v[150:153], v220 offset:46720
	v_add_f32_e32 v240, v240, v40
	v_add_f32_e32 v241, v241, v41
	v_cvt_pk_bf16_f32 v34, v34, v35
	v_cvt_pk_bf16_f32 v35, v36, v37
	v_cvt_pk_bf16_f32 v36, v38, v39
	s_waitcnt lgkmcnt(4)
	v_mfma_f32_32x32x16_bf16 v[66:81], v[154:157], v[106:109], v[66:81]
	ds_read_b128 v[154:157], v220 offset:40096
	v_cvt_pk_bf16_f32 v37, v40, v41
	v_exp_f32_e32 v42, v42
	v_exp_f32_e32 v43, v43
	v_mfma_f32_32x32x16_bf16 v[82:97], v[158:161], v[106:109], v[82:97]
	ds_read_b128 v[158:161], v220 offset:46752
	v_exp_f32_e32 v44, v44
	v_exp_f32_e32 v45, v45
	v_add_f32_e32 v231, v231, v42
	v_add_f32_e32 v232, v232, v43
	s_waitcnt lgkmcnt(4)
	v_mfma_f32_32x32x16_bf16 v[66:81], v[138:141], v[110:113], v[66:81]
	ds_read_b128 v[162:165], v221 offset:18432
	v_exp_f32_e32 v46, v46
	v_exp_f32_e32 v47, v47
	v_add_f32_e32 v240, v240, v44
	v_mfma_f32_32x32x16_bf16 v[82:97], v[142:145], v[110:113], v[82:97]
	ds_read_b128 v[166:169], v221 offset:23040
	v_add_f32_e32 v241, v241, v45
	v_exp_f32_e32 v48, v48
	v_exp_f32_e32 v49, v49
	s_waitcnt lgkmcnt(4)
	v_mfma_f32_32x32x16_bf16 v[66:81], v[146:149], v[114:117], v[66:81]
	ds_read_b128 v[170:173], v221 offset:18464
	v_add_f32_e32 v231, v231, v46
	v_add_f32_e32 v232, v232, v47
	v_add_f32_e32 v240, v240, v48
	v_add_f32_e32 v241, v241, v49
	v_cvt_pk_bf16_f32 v42, v42, v43
	v_cvt_pk_bf16_f32 v43, v44, v45
	v_mfma_f32_32x32x16_bf16 v[82:97], v[150:153], v[114:117], v[82:97]
	ds_read_b128 v[174:177], v221 offset:23072
	v_cvt_pk_bf16_f32 v44, v46, v47
	v_cvt_pk_bf16_f32 v45, v48, v49
	v_exp_f32_e32 v50, v50
	v_exp_f32_e32 v51, v51
	s_waitcnt lgkmcnt(4)
	v_mfma_f32_32x32x16_bf16 v[66:81], v[154:157], v[118:121], v[66:81]
	ds_read_b128 v[180:183], v221 offset:18496
	v_exp_f32_e32 v52, v52
	v_exp_f32_e32 v53, v53
	v_mfma_f32_32x32x16_bf16 v[82:97], v[158:161], v[118:121], v[82:97]
	ds_read_b128 v[184:187], v221 offset:23104
	v_add_f32_e32 v231, v231, v50
	v_add_f32_e32 v232, v232, v51
	v_exp_f32_e32 v54, v54
	v_exp_f32_e32 v55, v55
	s_waitcnt lgkmcnt(4)
	v_mfma_f32_32x32x16_bf16 v[2:17], v[162:165], v[34:37], v[2:17]
	ds_read_b128 v[188:191], v221 offset:18528
	v_add_f32_e32 v240, v240, v52
	v_add_f32_e32 v241, v241, v53
	v_exp_f32_e32 v56, v56
	v_exp_f32_e32 v57, v57
	v_mfma_f32_32x32x16_bf16 v[18:33], v[166:169], v[34:37], v[18:33]
	ds_read_b128 v[192:195], v221 offset:23136
	v_add_f32_e32 v231, v231, v54
	v_add_f32_e32 v232, v232, v55
	v_add_f32_e32 v240, v240, v56
	v_add_f32_e32 v241, v241, v57
	s_waitcnt lgkmcnt(4)
	v_mfma_f32_32x32x16_bf16 v[2:17], v[170:173], v[42:45], v[2:17]
	v_cvt_pk_bf16_f32 v50, v50, v51
	v_cvt_pk_bf16_f32 v51, v52, v53
	v_cvt_pk_bf16_f32 v52, v54, v55
	v_cvt_pk_bf16_f32 v53, v56, v57
	v_exp_f32_e32 v58, v58
	v_mfma_f32_32x32x16_bf16 v[18:33], v[174:177], v[42:45], v[18:33]
	v_exp_f32_e32 v59, v59
	v_exp_f32_e32 v60, v60
	v_exp_f32_e32 v61, v61
	s_waitcnt lgkmcnt(2)
	v_mfma_f32_32x32x16_bf16 v[2:17], v[180:183], v[50:53], v[2:17]
	v_add_f32_e32 v231, v231, v58
	v_add_f32_e32 v232, v232, v59
	v_exp_f32_e32 v62, v62
	v_mfma_f32_32x32x16_bf16 v[18:33], v[184:187], v[50:53], v[18:33]
	v_exp_f32_e32 v63, v63
	v_add_f32_e32 v240, v240, v60
	v_add_f32_e32 v241, v241, v61
	v_exp_f32_e32 v64, v64
	v_exp_f32_e32 v65, v65
	v_add_f32_e32 v231, v231, v62
	v_add_f32_e32 v232, v232, v63
	v_add_f32_e32 v240, v240, v64
	v_add_f32_e32 v241, v241, v65
	v_cvt_pk_bf16_f32 v58, v58, v59
	v_cvt_pk_bf16_f32 v59, v60, v61
	v_cvt_pk_bf16_f32 v60, v62, v63
	v_cvt_pk_bf16_f32 v61, v64, v65
	s_waitcnt lgkmcnt(0)
	s_nop 0
	v_mfma_f32_32x32x16_bf16 v[2:17], v[188:191], v[58:61], v[2:17]
	v_mfma_f32_32x32x16_bf16 v[18:33], v[192:195], v[58:61], v[18:33]
	s_waitcnt lgkmcnt(0)
	s_barrier
	s_mov_b64 s[24:25], s[14:15]
	s_add_i32 s2, s2, s88
	s_cmpk_lt_i32 s2, 0x200
	s_cbranch_scc0 .Lmla_nopf
	s_lshr_b32 s17, s2, 4
	s_and_b32 s18, s2, 15
	s_mul_i32 s19, s17, 0xcc000
	s_add_u32 s4, s78, s19
	s_addc_u32 s5, s79, 0
	s_mul_i32 s19, s17, 0x88000
	s_add_u32 s19, s19, 0x1a00000
	s_add_u32 s10, s78, s19
	s_addc_u32 s11, s79, 0
	s_lshl_b32 s19, s17, 12
	s_lshl_b32 s20, s18, 8
	s_add_u32 s19, s19, s20
	s_mul_i32 s19, s19, 0xc0
	s_add_u32 s19, s19, 0x1400000
	s_add_u32 s12, s80, s19
	s_addc_u32 s13, s81, 0
	s_lshr_b32 s19, s17, 3
	s_lshl_b32 s19, s19, 12
	s_add_u32 s19, s19, s20
	s_lshl_b32 s19, s19, 10
	s_and_b32 s21, s17, 7
	s_lshl_b32 s21, s21, 7
	s_add_u32 s19, s19, s21
	s_add_u32 s19, s19, 0x7900000
	s_add_u32 s14, s80, s19
	s_addc_u32 s15, s81, 0
	global_load_dwordx4 v[98:101], v237, s[12:13] offset:0
	global_load_dwordx4 v[102:105], v237, s[12:13] offset:32
	global_load_dwordx4 v[106:109], v237, s[12:13] offset:64
	global_load_dwordx4 v[110:113], v237, s[12:13] offset:96
	global_load_dwordx4 v[114:117], v237, s[12:13] offset:128
	global_load_dwordx4 v[118:121], v237, s[12:13] offset:160
	global_load_dwordx4 v[34:37], v226, s[4:5]
	global_load_dwordx4 v[38:41], v227, s[4:5]
	global_load_dwordx4 v[42:45], v228, s[4:5]
	global_load_dwordx4 v[46:49], v229, s[10:11]
	s_add_u32 s4, s4, 0x6000
	s_addc_u32 s5, s5, 0
	global_load_dwordx4 v[50:53], v226, s[4:5]
	global_load_dwordx4 v[54:57], v227, s[4:5]
	global_load_dwordx4 v[58:61], v228, s[4:5]
	global_load_dwordx4 v[62:65], v229, s[10:11] offset:128
	global_load_dwordx4 v[216:219], v229, s[10:11] offset:256
	s_add_u32 s4, s4, 0x6000
	s_addc_u32 s5, s5, 0
	s_add_u32 s10, s10, 0x180
	s_addc_u32 s11, s11, 0
.Lmla_nopf:
	ds_read_b128 v[162:165], v221 offset:27648
	ds_read_b128 v[166:169], v221 offset:32256
	ds_read_b128 v[170:173], v221 offset:27680
	v_exp_f32_e32 v66, v66
	v_exp_f32_e32 v67, v67
	v_exp_f32_e32 v68, v68
	v_exp_f32_e32 v69, v69
	v_add_f32_e32 v231, v231, v66
	v_add_f32_e32 v232, v232, v67
	v_exp_f32_e32 v70, v70
	v_exp_f32_e32 v71, v71
	v_add_f32_e32 v240, v240, v68
	v_add_f32_e32 v241, v241, v69
	v_exp_f32_e32 v72, v72
	v_exp_f32_e32 v73, v73
	v_add_f32_e32 v231, v231, v70
	v_add_f32_e32 v232, v232, v71
	v_add_f32_e32 v240, v240, v72
	v_add_f32_e32 v241, v241, v73
	v_cvt_pk_bf16_f32 v66, v66, v67
	v_cvt_pk_bf16_f32 v67, v68, v69
	v_cvt_pk_bf16_f32 v68, v70, v71
	v_cvt_pk_bf16_f32 v69, v72, v73
	s_waitcnt lgkmcnt(1)
	s_nop 0
	v_mfma_f32_32x32x16_bf16 v[2:17], v[162:165], v[66:69], v[2:17]
	ds_read_b128 v[174:177], v221 offset:32288
	v_mfma_f32_32x32x16_bf16 v[18:33], v[166:169], v[66:69], v[18:33]
	ds_read_b128 v[180:183], v221 offset:27712
	v_exp_f32_e32 v74, v74
	v_exp_f32_e32 v75, v75
	v_exp_f32_e32 v76, v76
	v_exp_f32_e32 v77, v77
	v_add_f32_e32 v231, v231, v74
	v_add_f32_e32 v232, v232, v75
	v_exp_f32_e32 v78, v78
	v_exp_f32_e32 v79, v79
	v_add_f32_e32 v240, v240, v76
	v_add_f32_e32 v241, v241, v77
	v_exp_f32_e32 v80, v80
	v_exp_f32_e32 v81, v81
	v_add_f32_e32 v231, v231, v78
	v_add_f32_e32 v232, v232, v79
	v_add_f32_e32 v240, v240, v80
	v_add_f32_e32 v241, v241, v81
	v_cvt_pk_bf16_f32 v74, v74, v75
	v_cvt_pk_bf16_f32 v75, v76, v77
	v_cvt_pk_bf16_f32 v76, v78, v79
	v_cvt_pk_bf16_f32 v77, v80, v81
	s_waitcnt lgkmcnt(1)
	s_nop 0
	v_mfma_f32_32x32x16_bf16 v[2:17], v[170:173], v[74:77], v[2:17]
	ds_read_b128 v[184:187], v221 offset:32320
	v_mfma_f32_32x32x16_bf16 v[18:33], v[174:177], v[74:77], v[18:33]
	ds_read_b128 v[188:191], v221 offset:27744
	v_exp_f32_e32 v82, v82
	v_exp_f32_e32 v83, v83
	v_exp_f32_e32 v84, v84
	v_exp_f32_e32 v85, v85
	v_add_f32_e32 v231, v231, v82
	v_add_f32_e32 v232, v232, v83
	v_exp_f32_e32 v86, v86
	v_exp_f32_e32 v87, v87
	v_add_f32_e32 v240, v240, v84
	v_add_f32_e32 v241, v241, v85
	v_exp_f32_e32 v88, v88
	v_exp_f32_e32 v89, v89
	v_add_f32_e32 v231, v231, v86
	v_add_f32_e32 v232, v232, v87
	v_add_f32_e32 v240, v240, v88
	v_add_f32_e32 v241, v241, v89
	v_cvt_pk_bf16_f32 v82, v82, v83
	v_cvt_pk_bf16_f32 v83, v84, v85
	v_cvt_pk_bf16_f32 v84, v86, v87
	v_cvt_pk_bf16_f32 v85, v88, v89
	s_waitcnt lgkmcnt(1)
	s_nop 0
	v_mfma_f32_32x32x16_bf16 v[2:17], v[180:183], v[82:85], v[2:17]
	ds_read_b128 v[192:195], v221 offset:32352
	v_mfma_f32_32x32x16_bf16 v[18:33], v[184:187], v[82:85], v[18:33]
	v_exp_f32_e32 v90, v90
	v_exp_f32_e32 v91, v91
	v_exp_f32_e32 v92, v92
	v_exp_f32_e32 v93, v93
	v_add_f32_e32 v231, v231, v90
	v_add_f32_e32 v232, v232, v91
	v_exp_f32_e32 v94, v94
	v_exp_f32_e32 v95, v95
	v_add_f32_e32 v240, v240, v92
	v_add_f32_e32 v241, v241, v93
	v_exp_f32_e32 v96, v96
	v_exp_f32_e32 v97, v97
	v_add_f32_e32 v231, v231, v94
	v_add_f32_e32 v232, v232, v95
	v_add_f32_e32 v240, v240, v96
	v_add_f32_e32 v241, v241, v97
	v_cvt_pk_bf16_f32 v90, v90, v91
	v_cvt_pk_bf16_f32 v91, v92, v93
	v_cvt_pk_bf16_f32 v92, v94, v95
	v_cvt_pk_bf16_f32 v93, v96, v97
	s_waitcnt lgkmcnt(0)
	s_nop 0
	v_mfma_f32_32x32x16_bf16 v[2:17], v[188:191], v[90:93], v[2:17]
	v_mfma_f32_32x32x16_bf16 v[18:33], v[192:195], v[90:93], v[18:33]
	s_waitcnt lgkmcnt(0)
	s_barrier
	v_add_f32_e32 v231, v231, v240
	v_add_f32_e32 v232, v232, v241
	v_add_f32_e32 v231, v231, v232
	v_mov_b32_e32 v235, v231
	s_nop 1
	v_permlane32_swap_b32_e32 v231, v235
	v_add_f32_e32 v234, v231, v235
	v_mov_b32_e32 v233, v234
	v_div_scale_f32 v235, s[22:23], v234, v234, 1.0
	v_rcp_f32_e32 v179, v235
	v_div_scale_f32 v196, vcc, 1.0, v234, 1.0
	v_fma_f32 v197, -v235, v179, 1.0
	v_fmac_f32_e32 v179, v197, v179
	v_mul_f32_e32 v197, v196, v179
	v_fma_f32 v199, -v235, v197, v196
	v_fmac_f32_e32 v197, v199, v179
	v_fma_f32 v235, -v235, v197, v196
	v_div_fmas_f32 v235, v235, v179, v197
	v_div_fixup_f32 v234, v235, v234, 1.0
	s_nop 15
	v_mul_f32_e32 v2, v2, v234
	v_mul_f32_e32 v3, v3, v234
	v_mul_f32_e32 v4, v4, v234
	v_mul_f32_e32 v5, v5, v234
	v_mul_f32_e32 v6, v6, v234
	v_mul_f32_e32 v7, v7, v234
	v_mul_f32_e32 v8, v8, v234
	v_mul_f32_e32 v9, v9, v234
	v_mul_f32_e32 v10, v10, v234
	v_mul_f32_e32 v11, v11, v234
	v_mul_f32_e32 v12, v12, v234
	v_mul_f32_e32 v13, v13, v234
	v_mul_f32_e32 v14, v14, v234
	v_mul_f32_e32 v15, v15, v234
	v_mul_f32_e32 v16, v16, v234
	v_mul_f32_e32 v17, v17, v234
	v_mul_f32_e32 v18, v18, v234
	v_mul_f32_e32 v19, v19, v234
	v_mul_f32_e32 v20, v20, v234
	v_mul_f32_e32 v21, v21, v234
	v_mul_f32_e32 v22, v22, v234
	v_mul_f32_e32 v23, v23, v234
	v_mul_f32_e32 v24, v24, v234
	v_mul_f32_e32 v25, v25, v234
	v_mul_f32_e32 v26, v26, v234
	v_mul_f32_e32 v27, v27, v234
	v_mul_f32_e32 v28, v28, v234
	v_mul_f32_e32 v29, v29, v234
	v_mul_f32_e32 v30, v30, v234
	v_mul_f32_e32 v31, v31, v234
	v_mul_f32_e32 v32, v32, v234
	v_mul_f32_e32 v33, v33, v234
	v_mov_b32_e32 v235, 0
	v_fmac_f32_e32 v235, 0, v2
	v_fmac_f32_e32 v235, 0, v3
	v_fmac_f32_e32 v235, 0, v4
	v_fmac_f32_e32 v235, 0, v5
	v_fmac_f32_e32 v235, 0, v6
	v_fmac_f32_e32 v235, 0, v7
	v_fmac_f32_e32 v235, 0, v8
	v_fmac_f32_e32 v235, 0, v9
	v_fmac_f32_e32 v235, 0, v10
	v_fmac_f32_e32 v235, 0, v11
	v_fmac_f32_e32 v235, 0, v12
	v_fmac_f32_e32 v235, 0, v13
	v_fmac_f32_e32 v235, 0, v14
	v_fmac_f32_e32 v235, 0, v15
	v_fmac_f32_e32 v235, 0, v16
	v_fmac_f32_e32 v235, 0, v17
	v_fmac_f32_e32 v235, 0, v18
	v_fmac_f32_e32 v235, 0, v19
	v_fmac_f32_e32 v235, 0, v20
	v_fmac_f32_e32 v235, 0, v21
	v_fmac_f32_e32 v235, 0, v22
	v_fmac_f32_e32 v235, 0, v23
	v_fmac_f32_e32 v235, 0, v24
	v_fmac_f32_e32 v235, 0, v25
	v_fmac_f32_e32 v235, 0, v26
	v_fmac_f32_e32 v235, 0, v27
	v_fmac_f32_e32 v235, 0, v28
	v_fmac_f32_e32 v235, 0, v29
	v_fmac_f32_e32 v235, 0, v30
	v_fmac_f32_e32 v235, 0, v31
	v_fmac_f32_e32 v235, 0, v32
	v_fmac_f32_e32 v235, 0, v33
	v_fmac_f32_e32 v235, 0, v233
	v_cmp_u_f32_e32 vcc, v235, v235
	s_cmp_lg_u64 vcc, 0
	s_cselect_b32 s26, 1, 0
	v_mov_b32_e32 v179, 0x186a0
	v_mov_b32_e32 v196, s26
	ds_or_b32 v179, v196
	s_waitcnt lgkmcnt(0)
	s_barrier
	ds_read_b32 v196, v179
	s_waitcnt lgkmcnt(0)
	v_readfirstlane_b32 s26, v196
	s_barrier
	v_mov_b32_e32 v196, 0
	ds_write_b32 v179, v196
	s_cmp_lg_u32 s26, 0
	s_cbranch_scc1 .Lmla_redo
	s_cmpk_lt_i32 s2, 0x200
	s_cbranch_scc1 .Lmla_zw15
	s_waitcnt vmcnt(0)
	s_branch .Lmla_zw

.Lmla_zw:
	v_lshlrev_b32_e32 v179, 16, v200
	v_and_b32_e32 v196, 0xffff0000, v200
	v_lshlrev_b32_e32 v197, 16, v201
	v_and_b32_e32 v199, 0xffff0000, v201
	v_mul_f32_e32 v2, v2, v179
	v_mul_f32_e32 v3, v3, v196
	v_mul_f32_e32 v4, v4, v197
	v_mul_f32_e32 v5, v5, v199
	v_cvt_pk_bf16_f32 v200, v2, v3
	v_cvt_pk_bf16_f32 v201, v4, v5
	global_store_dwordx2 v236, v[200:201], s[24:25] offset:0
	v_lshlrev_b32_e32 v179, 16, v202
	v_and_b32_e32 v196, 0xffff0000, v202
	v_lshlrev_b32_e32 v197, 16, v203
	v_and_b32_e32 v199, 0xffff0000, v203
	v_mul_f32_e32 v6, v6, v179
	v_mul_f32_e32 v7, v7, v196
	v_mul_f32_e32 v8, v8, v197
	v_mul_f32_e32 v9, v9, v199
	v_cvt_pk_bf16_f32 v202, v6, v7
	v_cvt_pk_bf16_f32 v203, v8, v9
	global_store_dwordx2 v236, v[202:203], s[24:25] offset:16
	v_lshlrev_b32_e32 v179, 16, v204
	v_and_b32_e32 v196, 0xffff0000, v204
	v_lshlrev_b32_e32 v197, 16, v205
	v_and_b32_e32 v199, 0xffff0000, v205
	v_mul_f32_e32 v10, v10, v179
	v_mul_f32_e32 v11, v11, v196
	v_mul_f32_e32 v12, v12, v197
	v_mul_f32_e32 v13, v13, v199
	v_cvt_pk_bf16_f32 v204, v10, v11
	v_cvt_pk_bf16_f32 v205, v12, v13
	global_store_dwordx2 v236, v[204:205], s[24:25] offset:32
	v_lshlrev_b32_e32 v179, 16, v206
	v_and_b32_e32 v196, 0xffff0000, v206
	v_lshlrev_b32_e32 v197, 16, v207
	v_and_b32_e32 v199, 0xffff0000, v207
	v_mul_f32_e32 v14, v14, v179
	v_mul_f32_e32 v15, v15, v196
	v_mul_f32_e32 v16, v16, v197
	v_mul_f32_e32 v17, v17, v199
	v_cvt_pk_bf16_f32 v206, v14, v15
	v_cvt_pk_bf16_f32 v207, v16, v17
	global_store_dwordx2 v236, v[206:207], s[24:25] offset:48
	v_lshlrev_b32_e32 v179, 16, v208
	v_and_b32_e32 v196, 0xffff0000, v208
	v_lshlrev_b32_e32 v197, 16, v209
	v_and_b32_e32 v199, 0xffff0000, v209
	v_mul_f32_e32 v18, v18, v179
	v_mul_f32_e32 v19, v19, v196
	v_mul_f32_e32 v20, v20, v197
	v_mul_f32_e32 v21, v21, v199
	v_cvt_pk_bf16_f32 v208, v18, v19
	v_cvt_pk_bf16_f32 v209, v20, v21
	global_store_dwordx2 v236, v[208:209], s[24:25] offset:64
	v_lshlrev_b32_e32 v179, 16, v210
	v_and_b32_e32 v196, 0xffff0000, v210
	v_lshlrev_b32_e32 v197, 16, v211
	v_and_b32_e32 v199, 0xffff0000, v211
	v_mul_f32_e32 v22, v22, v179
	v_mul_f32_e32 v23, v23, v196
	v_mul_f32_e32 v24, v24, v197
	v_mul_f32_e32 v25, v25, v199
	v_cvt_pk_bf16_f32 v210, v22, v23
	v_cvt_pk_bf16_f32 v211, v24, v25
	global_store_dwordx2 v236, v[210:211], s[24:25] offset:80
	v_lshlrev_b32_e32 v179, 16, v212
	v_and_b32_e32 v196, 0xffff0000, v212
	v_lshlrev_b32_e32 v197, 16, v213
	v_and_b32_e32 v199, 0xffff0000, v213
	v_mul_f32_e32 v26, v26, v179
	v_mul_f32_e32 v27, v27, v196
	v_mul_f32_e32 v28, v28, v197
	v_mul_f32_e32 v29, v29, v199
	v_cvt_pk_bf16_f32 v212, v26, v27
	v_cvt_pk_bf16_f32 v213, v28, v29
	global_store_dwordx2 v236, v[212:213], s[24:25] offset:96
	v_lshlrev_b32_e32 v179, 16, v214
	v_and_b32_e32 v196, 0xffff0000, v214
	v_lshlrev_b32_e32 v197, 16, v215
	v_and_b32_e32 v199, 0xffff0000, v215
	v_mul_f32_e32 v30, v30, v179
	v_mul_f32_e32 v31, v31, v196
	v_mul_f32_e32 v32, v32, v197
	v_mul_f32_e32 v33, v33, v199
	v_cvt_pk_bf16_f32 v214, v30, v31
	v_cvt_pk_bf16_f32 v215, v32, v33
	global_store_dwordx2 v236, v[214:215], s[24:25] offset:112
	s_cmpk_lt_i32 s2, 0x200
	s_cbranch_scc0 .Lmla_exit
	v_mov_b32_e32 v2, 0
	v_mov_b32_e32 v3, 0
	v_mov_b32_e32 v4, 0
	v_mov_b32_e32 v5, 0
	v_mov_b32_e32 v6, 0
	v_mov_b32_e32 v7, 0
	v_mov_b32_e32 v8, 0
	v_mov_b32_e32 v9, 0
	v_mov_b32_e32 v10, 0
	v_mov_b32_e32 v11, 0
	v_mov_b32_e32 v12, 0
	v_mov_b32_e32 v13, 0
	v_mov_b32_e32 v14, 0
	v_mov_b32_e32 v15, 0
	v_mov_b32_e32 v16, 0
	v_mov_b32_e32 v17, 0
	v_mov_b32_e32 v18, 0
	v_mov_b32_e32 v19, 0
	v_mov_b32_e32 v20, 0
	v_mov_b32_e32 v21, 0
	v_mov_b32_e32 v22, 0
	v_mov_b32_e32 v23, 0
	v_mov_b32_e32 v24, 0
	v_mov_b32_e32 v25, 0
	v_mov_b32_e32 v26, 0
	v_mov_b32_e32 v27, 0
	v_mov_b32_e32 v28, 0
	v_mov_b32_e32 v29, 0
	v_mov_b32_e32 v30, 0
	v_mov_b32_e32 v31, 0
	v_mov_b32_e32 v32, 0
	v_mov_b32_e32 v33, 0
	v_mov_b32_e32 v122, 0
	v_mov_b32_e32 v123, 0
	v_mov_b32_e32 v124, 0
	v_mov_b32_e32 v125, 0
	v_mov_b32_e32 v126, 0
	v_mov_b32_e32 v127, 0
	v_mov_b32_e32 v128, 0
	v_mov_b32_e32 v129, 0
	v_mov_b32_e32 v130, 0
	v_mov_b32_e32 v131, 0
	v_mov_b32_e32 v132, 0
	v_mov_b32_e32 v133, 0
	v_mov_b32_e32 v134, 0
	v_mov_b32_e32 v135, 0
	v_mov_b32_e32 v136, 0
	v_mov_b32_e32 v137, 0
	v_mov_b32_e32 v230, 0
	v_mov_b32_e32 v231, 0
	v_mov_b32_e32 v232, 0
	v_mov_b32_e32 v240, 0
	v_mov_b32_e32 v241, 0
	s_waitcnt vmcnt(13)
	ds_write_b128 v222, v[34:37]
	ds_write_b128 v223, v[38:41]
	ds_write_b128 v224, v[42:45]
	ds_write_b64 v225, v[46:47]
	ds_write_b64 v225, v[48:49] offset:16
	s_waitcnt vmcnt(9)
	ds_write_b128 v222, v[50:53] offset:26624
	ds_write_b128 v223, v[54:57] offset:26624
	ds_write_b128 v224, v[58:61] offset:26624
	ds_write_b64 v225, v[62:63] offset:9216
	ds_write_b64 v225, v[64:65] offset:9232
	s_waitcnt lgkmcnt(0)
	s_barrier
	s_branch .Lmla_body
.Lmla_redo:
	s_sub_i32 s2, s2, s88
	s_waitcnt vmcnt(0)
	s_lshr_b32 s17, s2, 4
	s_and_b32 s18, s2, 15
	s_mul_i32 s19, s17, 0xcc000
	s_add_u32 s4, s78, s19
	s_addc_u32 s5, s79, 0
	s_mul_i32 s19, s17, 0x88000
	s_add_u32 s19, s19, 0x1a00000
	s_add_u32 s10, s78, s19
	s_addc_u32 s11, s79, 0
	s_lshl_b32 s19, s17, 12
	s_lshl_b32 s20, s18, 8
	s_add_u32 s19, s19, s20
	s_mul_i32 s19, s19, 0xc0
	s_add_u32 s19, s19, 0x1400000
	s_add_u32 s12, s80, s19
	s_addc_u32 s13, s81, 0
	s_lshr_b32 s19, s17, 3
	s_lshl_b32 s19, s19, 12
	s_add_u32 s19, s19, s20
	s_lshl_b32 s19, s19, 10
	s_and_b32 s21, s17, 7
	s_lshl_b32 s21, s21, 7
	s_add_u32 s19, s19, s21
	s_add_u32 s19, s19, 0x7900000
	s_add_u32 s14, s80, s19
	s_addc_u32 s15, s81, 0
	global_load_dwordx4 v[98:101], v237, s[12:13] offset:0
	global_load_dwordx4 v[102:105], v237, s[12:13] offset:32
	global_load_dwordx4 v[106:109], v237, s[12:13] offset:64
	global_load_dwordx4 v[110:113], v237, s[12:13] offset:96
	global_load_dwordx4 v[114:117], v237, s[12:13] offset:128
	global_load_dwordx4 v[118:121], v237, s[12:13] offset:160
	global_load_dwordx4 v[200:203], v226, s[4:5]
	global_load_dwordx4 v[204:207], v227, s[4:5]
	global_load_dwordx4 v[208:211], v228, s[4:5]
	global_load_dwordx4 v[66:69], v229, s[10:11]
	s_add_u32 s4, s4, 0x6000
	s_addc_u32 s5, s5, 0
	global_load_dwordx4 v[70:73], v226, s[4:5]
	global_load_dwordx4 v[74:77], v227, s[4:5]
	global_load_dwordx4 v[78:81], v228, s[4:5]
	global_load_dwordx4 v[82:85], v229, s[10:11] offset:128
	global_load_dwordx4 v[216:219], v229, s[10:11] offset:256
	s_add_u32 s4, s4, 0x6000
	s_addc_u32 s5, s5, 0
	s_add_u32 s10, s10, 0x180
	s_addc_u32 s11, s11, 0
	v_mov_b32_e32 v2, 0
	v_mov_b32_e32 v3, 0
	v_mov_b32_e32 v4, 0
	v_mov_b32_e32 v5, 0
	v_mov_b32_e32 v6, 0
	v_mov_b32_e32 v7, 0
	v_mov_b32_e32 v8, 0
	v_mov_b32_e32 v9, 0
	v_mov_b32_e32 v10, 0
	v_mov_b32_e32 v11, 0
	v_mov_b32_e32 v12, 0
	v_mov_b32_e32 v13, 0
	v_mov_b32_e32 v14, 0
	v_mov_b32_e32 v15, 0
	v_mov_b32_e32 v16, 0
	v_mov_b32_e32 v17, 0
	v_mov_b32_e32 v18, 0
	v_mov_b32_e32 v19, 0
	v_mov_b32_e32 v20, 0
	v_mov_b32_e32 v21, 0
	v_mov_b32_e32 v22, 0
	v_mov_b32_e32 v23, 0
	v_mov_b32_e32 v24, 0
	v_mov_b32_e32 v25, 0
	v_mov_b32_e32 v26, 0
	v_mov_b32_e32 v27, 0
	v_mov_b32_e32 v28, 0
	v_mov_b32_e32 v29, 0
	v_mov_b32_e32 v30, 0
	v_mov_b32_e32 v31, 0
	v_mov_b32_e32 v32, 0
	v_mov_b32_e32 v33, 0
	v_mov_b32_e32 v122, 0
	v_mov_b32_e32 v123, 0
	v_mov_b32_e32 v124, 0
	v_mov_b32_e32 v125, 0
	v_mov_b32_e32 v126, 0
	v_mov_b32_e32 v127, 0
	v_mov_b32_e32 v128, 0
	v_mov_b32_e32 v129, 0
	v_mov_b32_e32 v130, 0
	v_mov_b32_e32 v131, 0
	v_mov_b32_e32 v132, 0
	v_mov_b32_e32 v133, 0
	v_mov_b32_e32 v134, 0
	v_mov_b32_e32 v135, 0
	v_mov_b32_e32 v136, 0
	v_mov_b32_e32 v137, 0
	v_mov_b32_e32 v230, 0
	v_mov_b32_e32 v231, 0
	v_mov_b32_e32 v232, 0
	v_mov_b32_e32 v240, 0
	v_mov_b32_e32 v241, 0
	s_waitcnt vmcnt(5)
	ds_write_b128 v222, v[200:203]
	ds_write_b128 v223, v[204:207]
	ds_write_b128 v224, v[208:211]
	ds_write_b64 v225, v[66:67]
	ds_write_b64 v225, v[68:69] offset:16
	s_waitcnt vmcnt(1)
	ds_write_b128 v222, v[70:73] offset:26624
	ds_write_b128 v223, v[74:77] offset:26624
	ds_write_b128 v224, v[78:81] offset:26624
	ds_write_b64 v225, v[82:83] offset:9216
	ds_write_b64 v225, v[84:85] offset:9232
	s_waitcnt lgkmcnt(0)
	s_barrier
	ds_read_b128 v[138:141], v220 offset:0
	ds_read_b128 v[142:145], v220 offset:6656
	ds_read_b128 v[146:149], v220 offset:32
	ds_read_b128 v[150:153], v220 offset:6688
	ds_read_b128 v[154:157], v220 offset:64
	ds_read_b128 v[158:161], v220 offset:6720
	ds_read_b128 v[66:69], v220 offset:96
	ds_read_b128 v[70:73], v220 offset:6752
	ds_read_b128 v[74:77], v220 offset:128
	ds_read_b128 v[78:81], v220 offset:6784
	ds_read_b128 v[82:85], v220 offset:160
	ds_read_b128 v[86:89], v220 offset:6816
	s_waitcnt lgkmcnt(11)
	v_mfma_f32_32x32x16_bf16 v[34:49], v[138:141], v[98:101], v[122:137]
	s_waitcnt lgkmcnt(10)
	v_mfma_f32_32x32x16_bf16 v[50:65], v[142:145], v[98:101], v[122:137]
	s_waitcnt lgkmcnt(9)
	v_mfma_f32_32x32x16_bf16 v[34:49], v[146:149], v[102:105], v[34:49]
	s_waitcnt lgkmcnt(8)
	v_mfma_f32_32x32x16_bf16 v[50:65], v[150:153], v[102:105], v[50:65]
	s_waitcnt lgkmcnt(7)
	v_mfma_f32_32x32x16_bf16 v[34:49], v[154:157], v[106:109], v[34:49]
	s_waitcnt lgkmcnt(6)
	v_mfma_f32_32x32x16_bf16 v[50:65], v[158:161], v[106:109], v[50:65]
	s_waitcnt lgkmcnt(5)
	v_mfma_f32_32x32x16_bf16 v[34:49], v[66:69], v[110:113], v[34:49]
	s_waitcnt lgkmcnt(4)
	v_mfma_f32_32x32x16_bf16 v[50:65], v[70:73], v[110:113], v[50:65]
	s_waitcnt lgkmcnt(3)
	v_mfma_f32_32x32x16_bf16 v[34:49], v[74:77], v[114:117], v[34:49]
	s_waitcnt lgkmcnt(2)
	v_mfma_f32_32x32x16_bf16 v[50:65], v[78:81], v[114:117], v[50:65]
	s_waitcnt lgkmcnt(1)
	v_mfma_f32_32x32x16_bf16 v[34:49], v[82:85], v[118:121], v[34:49]
	s_waitcnt lgkmcnt(0)
	v_mfma_f32_32x32x16_bf16 v[50:65], v[86:89], v[118:121], v[50:65]
	s_nop 15
	v_max3_f32 v234, v34, v35, v36
	v_max3_f32 v235, v50, v51, v52
	v_max3_f32 v234, v234, v37, v38
	v_max3_f32 v235, v235, v53, v54
	v_max3_f32 v234, v234, v39, v40
	v_max3_f32 v235, v235, v55, v56
	v_max3_f32 v234, v234, v41, v42
	v_max3_f32 v235, v235, v57, v58
	v_max3_f32 v234, v234, v43, v44
	v_max3_f32 v235, v235, v59, v60
	v_max3_f32 v234, v234, v45, v46
	v_max3_f32 v235, v235, v61, v62
	v_max3_f32 v234, v234, v47, v48
	v_max3_f32 v235, v235, v63, v64
	v_max3_f32 v234, v234, v49, v65
	v_max_f32_e32 v234, v234, v235
	v_mov_b32_e32 v235, v234
	s_nop 1
	v_permlane32_swap_b32_e32 v234, v235
	v_max_f32_e32 v233, v234, v235
	s_nop 15
	v_add_f32_e32 v230, v230, v233
	v_sub_f32_e32 v34, v34, v233
	v_sub_f32_e32 v35, v35, v233
	v_sub_f32_e32 v36, v36, v233
	v_sub_f32_e32 v37, v37, v233
	v_sub_f32_e32 v38, v38, v233
	v_sub_f32_e32 v39, v39, v233
	v_sub_f32_e32 v40, v40, v233
	v_sub_f32_e32 v41, v41, v233
	v_sub_f32_e32 v42, v42, v233
	v_sub_f32_e32 v43, v43, v233
	v_sub_f32_e32 v44, v44, v233
	v_sub_f32_e32 v45, v45, v233
	v_sub_f32_e32 v46, v46, v233
	v_sub_f32_e32 v47, v47, v233
	v_sub_f32_e32 v48, v48, v233
	v_sub_f32_e32 v49, v49, v233
	v_sub_f32_e32 v50, v50, v233
	v_sub_f32_e32 v51, v51, v233
	v_sub_f32_e32 v52, v52, v233
	v_sub_f32_e32 v53, v53, v233
	v_sub_f32_e32 v54, v54, v233
	v_sub_f32_e32 v55, v55, v233
	v_sub_f32_e32 v56, v56, v233
	v_sub_f32_e32 v57, v57, v233
	v_sub_f32_e32 v58, v58, v233
	v_sub_f32_e32 v59, v59, v233
	v_sub_f32_e32 v60, v60, v233
	v_sub_f32_e32 v61, v61, v233
	v_sub_f32_e32 v62, v62, v233
	v_sub_f32_e32 v63, v63, v233
	v_sub_f32_e32 v64, v64, v233
	v_sub_f32_e32 v65, v65, v233
	v_sub_f32_e32 v122, 0, v230
	v_mov_b32_e32 v123, v122
	v_mov_b32_e32 v124, v122
	v_mov_b32_e32 v125, v122
	v_mov_b32_e32 v126, v122
	v_mov_b32_e32 v127, v122
	v_mov_b32_e32 v128, v122
	v_mov_b32_e32 v129, v122
	v_mov_b32_e32 v130, v122
	v_mov_b32_e32 v131, v122
	v_mov_b32_e32 v132, v122
	v_mov_b32_e32 v133, v122
	v_mov_b32_e32 v134, v122
	v_mov_b32_e32 v135, v122
	v_mov_b32_e32 v136, v122
	v_mov_b32_e32 v137, v122
	ds_read_b128 v[138:141], v220 offset:13312
	ds_read_b128 v[142:145], v220 offset:19968
	ds_read_b128 v[146:149], v220 offset:13344
	ds_read_b128 v[150:153], v220 offset:20000
	ds_read_b128 v[154:157], v220 offset:13376
	ds_read_b128 v[158:161], v220 offset:20032
	s_movk_i32 s16, 16
.Lmls_loop:
	v_exp_f32_e32 v34, v34
	v_exp_f32_e32 v35, v35
	v_exp_f32_e32 v36, v36
	v_exp_f32_e32 v37, v37
	s_waitcnt lgkmcnt(4)
	v_mfma_f32_32x32x16_bf16 v[66:81], v[138:141], v[98:101], v[122:137]
	ds_read_b128 v[138:141], v220 offset:13408
	v_add_f32_e32 v231, v231, v34
	v_add_f32_e32 v232, v232, v35
	v_exp_f32_e32 v38, v38
	v_exp_f32_e32 v39, v39
	v_mfma_f32_32x32x16_bf16 v[82:97], v[142:145], v[98:101], v[122:137]
	ds_read_b128 v[142:145], v220 offset:20064
	v_add_f32_e32 v240, v240, v36
	v_add_f32_e32 v241, v241, v37
	v_exp_f32_e32 v40, v40
	v_exp_f32_e32 v41, v41
	s_waitcnt lgkmcnt(4)
	v_mfma_f32_32x32x16_bf16 v[66:81], v[146:149], v[102:105], v[66:81]
	ds_read_b128 v[146:149], v220 offset:13440
	global_load_dwordx4 v[200:203], v226, s[4:5]
	global_load_dwordx4 v[204:207], v227, s[4:5]
	global_load_dwordx4 v[208:211], v228, s[4:5]
	s_add_u32 s4, s4, 0x6000
	s_addc_u32 s5, s5, 0
	global_load_dwordx4 v[212:215], v229, s[10:11]
	s_add_u32 s10, s10, 0x80
	s_addc_u32 s11, s11, 0
	v_add_f32_e32 v231, v231, v38
	v_add_f32_e32 v232, v232, v39
	v_add_f32_e32 v240, v240, v40
	v_add_f32_e32 v241, v241, v41
	v_cvt_pk_bf16_f32 v34, v34, v35
	v_cvt_pk_bf16_f32 v35, v36, v37
	v_mfma_f32_32x32x16_bf16 v[82:97], v[150:153], v[102:105], v[82:97]
	ds_read_b128 v[150:153], v220 offset:20096
	v_cvt_pk_bf16_f32 v36, v38, v39
	v_cvt_pk_bf16_f32 v37, v40, v41
	v_exp_f32_e32 v42, v42
	v_exp_f32_e32 v43, v43
	s_waitcnt lgkmcnt(4)
	v_mfma_f32_32x32x16_bf16 v[66:81], v[154:157], v[106:109], v[66:81]
	ds_read_b128 v[154:157], v220 offset:13472
	v_exp_f32_e32 v44, v44
	v_exp_f32_e32 v45, v45
	v_add_f32_e32 v231, v231, v42
	v_add_f32_e32 v232, v232, v43
	v_mfma_f32_32x32x16_bf16 v[82:97], v[158:161], v[106:109], v[82:97]
	ds_read_b128 v[158:161], v220 offset:20128
	v_exp_f32_e32 v46, v46
	v_exp_f32_e32 v47, v47
	v_add_f32_e32 v240, v240, v44
	v_add_f32_e32 v241, v241, v45
	v_exp_f32_e32 v48, v48
	s_waitcnt lgkmcnt(4)
	v_mfma_f32_32x32x16_bf16 v[66:81], v[138:141], v[110:113], v[66:81]
	ds_read_b128 v[162:165], v221 offset:0
	v_exp_f32_e32 v49, v49
	v_add_f32_e32 v231, v231, v46
	v_add_f32_e32 v232, v232, v47
	v_add_f32_e32 v240, v240, v48
	v_mfma_f32_32x32x16_bf16 v[82:97], v[142:145], v[110:113], v[82:97]
	ds_read_b128 v[166:169], v221 offset:4608
	v_add_f32_e32 v241, v241, v49
	v_cvt_pk_bf16_f32 v42, v42, v43
	v_cvt_pk_bf16_f32 v43, v44, v45
	v_cvt_pk_bf16_f32 v44, v46, v47
	v_cvt_pk_bf16_f32 v45, v48, v49
	v_exp_f32_e32 v50, v50
	s_waitcnt lgkmcnt(4)
	v_mfma_f32_32x32x16_bf16 v[66:81], v[146:149], v[114:117], v[66:81]
	ds_read_b128 v[170:173], v221 offset:32
	v_exp_f32_e32 v51, v51
	v_exp_f32_e32 v52, v52
	v_exp_f32_e32 v53, v53
	v_mfma_f32_32x32x16_bf16 v[82:97], v[150:153], v[114:117], v[82:97]
	ds_read_b128 v[174:177], v221 offset:4640
	v_add_f32_e32 v231, v231, v50
	v_add_f32_e32 v232, v232, v51
	v_exp_f32_e32 v54, v54
	v_exp_f32_e32 v55, v55
	s_waitcnt lgkmcnt(4)
	v_mfma_f32_32x32x16_bf16 v[66:81], v[154:157], v[118:121], v[66:81]
	ds_read_b128 v[180:183], v221 offset:64
	v_add_f32_e32 v240, v240, v52
	v_add_f32_e32 v241, v241, v53
	v_exp_f32_e32 v56, v56
	v_exp_f32_e32 v57, v57
	v_mfma_f32_32x32x16_bf16 v[82:97], v[158:161], v[118:121], v[82:97]
	ds_read_b128 v[184:187], v221 offset:4672
	v_add_f32_e32 v231, v231, v54
	v_add_f32_e32 v232, v232, v55
	v_add_f32_e32 v240, v240, v56
	v_add_f32_e32 v241, v241, v57
	v_cvt_pk_bf16_f32 v50, v50, v51
	v_cvt_pk_bf16_f32 v51, v52, v53
	v_cvt_pk_bf16_f32 v52, v54, v55
	s_waitcnt lgkmcnt(4)
	v_mfma_f32_32x32x16_bf16 v[2:17], v[162:165], v[34:37], v[2:17]
	ds_read_b128 v[188:191], v221 offset:96
	v_cvt_pk_bf16_f32 v53, v56, v57
	v_exp_f32_e32 v58, v58
	v_exp_f32_e32 v59, v59
	v_exp_f32_e32 v60, v60
	v_mfma_f32_32x32x16_bf16 v[18:33], v[166:169], v[34:37], v[18:33]
	ds_read_b128 v[192:195], v221 offset:4704
	v_exp_f32_e32 v61, v61
	v_add_f32_e32 v231, v231, v58
	v_add_f32_e32 v232, v232, v59
	v_exp_f32_e32 v62, v62
	s_waitcnt lgkmcnt(4)
	v_mfma_f32_32x32x16_bf16 v[2:17], v[170:173], v[42:45], v[2:17]
	v_exp_f32_e32 v63, v63
	v_add_f32_e32 v240, v240, v60
	v_add_f32_e32 v241, v241, v61
	v_exp_f32_e32 v64, v64
	v_mfma_f32_32x32x16_bf16 v[18:33], v[174:177], v[42:45], v[18:33]
	s_waitcnt vmcnt(4)
	ds_write_b64 v225, v[216:217] offset:18432
	ds_write_b64 v225, v[218:219] offset:18448
	v_exp_f32_e32 v65, v65
	v_add_f32_e32 v231, v231, v62
	v_add_f32_e32 v232, v232, v63
	v_add_f32_e32 v240, v240, v64
	v_add_f32_e32 v241, v241, v65
	s_waitcnt lgkmcnt(4)
	v_mfma_f32_32x32x16_bf16 v[2:17], v[180:183], v[50:53], v[2:17]
	v_cvt_pk_bf16_f32 v58, v58, v59
	v_cvt_pk_bf16_f32 v59, v60, v61
	v_cvt_pk_bf16_f32 v60, v62, v63
	v_cvt_pk_bf16_f32 v61, v64, v65
	v_max3_f32 v234, v66, v67, v68
	v_max3_f32 v235, v82, v83, v84
	v_mfma_f32_32x32x16_bf16 v[18:33], v[184:187], v[50:53], v[18:33]
	v_max3_f32 v234, v234, v69, v70
	v_max3_f32 v235, v235, v85, v86
	v_max3_f32 v234, v234, v71, v72
	v_max3_f32 v235, v235, v87, v88
	v_max3_f32 v234, v234, v73, v74
	v_max3_f32 v235, v235, v89, v90
	v_max3_f32 v234, v234, v75, v76
	s_waitcnt lgkmcnt(2)
	v_mfma_f32_32x32x16_bf16 v[2:17], v[188:191], v[58:61], v[2:17]
	v_max3_f32 v235, v235, v91, v92
	v_max3_f32 v234, v234, v77, v78
	v_max3_f32 v235, v235, v93, v94
	v_max3_f32 v234, v234, v79, v80
	v_max3_f32 v235, v235, v95, v96
	v_max3_f32 v234, v234, v81, v97
	v_mfma_f32_32x32x16_bf16 v[18:33], v[192:195], v[58:61], v[18:33]
	v_max_f32_e32 v234, v234, v235
	v_mov_b32_e32 v235, v234
	s_nop 1
	v_permlane32_swap_b32_e32 v234, v235
	v_max_f32_e32 v233, v234, v235
	v_cmp_lt_f32_e32 vcc, 4.0, v233
	s_cbranch_vccz .Lmls_nr_p0
	s_nop 15
	v_max_f32_e32 v234, 0, v233
	v_exp_f32_e64 v235, -v234
	v_add_f32_e32 v230, v230, v234
	v_sub_f32_e32 v66, v66, v234
	v_sub_f32_e32 v67, v67, v234
	v_sub_f32_e32 v68, v68, v234
	v_sub_f32_e32 v69, v69, v234
	v_sub_f32_e32 v70, v70, v234
	v_sub_f32_e32 v71, v71, v234
	v_sub_f32_e32 v72, v72, v234
	v_sub_f32_e32 v73, v73, v234
	v_sub_f32_e32 v74, v74, v234
	v_sub_f32_e32 v75, v75, v234
	v_sub_f32_e32 v76, v76, v234
	v_sub_f32_e32 v77, v77, v234
	v_sub_f32_e32 v78, v78, v234
	v_sub_f32_e32 v79, v79, v234
	v_sub_f32_e32 v80, v80, v234
	v_sub_f32_e32 v81, v81, v234
	v_sub_f32_e32 v82, v82, v234
	v_sub_f32_e32 v83, v83, v234
	v_sub_f32_e32 v84, v84, v234
	v_sub_f32_e32 v85, v85, v234
	v_sub_f32_e32 v86, v86, v234
	v_sub_f32_e32 v87, v87, v234
	v_sub_f32_e32 v88, v88, v234
	v_sub_f32_e32 v89, v89, v234
	v_sub_f32_e32 v90, v90, v234
	v_sub_f32_e32 v91, v91, v234
	v_sub_f32_e32 v92, v92, v234
	v_sub_f32_e32 v93, v93, v234
	v_sub_f32_e32 v94, v94, v234
	v_sub_f32_e32 v95, v95, v234
	v_sub_f32_e32 v96, v96, v234
	v_sub_f32_e32 v97, v97, v234
	v_mul_f32_e32 v231, v231, v235
	v_mul_f32_e32 v232, v232, v235
	v_mul_f32_e32 v240, v240, v235
	v_mul_f32_e32 v241, v241, v235
	v_mul_f32_e32 v2, v2, v235
	v_mul_f32_e32 v3, v3, v235
	v_mul_f32_e32 v4, v4, v235
	v_mul_f32_e32 v5, v5, v235
	v_mul_f32_e32 v6, v6, v235
	v_mul_f32_e32 v7, v7, v235
	v_mul_f32_e32 v8, v8, v235
	v_mul_f32_e32 v9, v9, v235
	v_mul_f32_e32 v10, v10, v235
	v_mul_f32_e32 v11, v11, v235
	v_mul_f32_e32 v12, v12, v235
	v_mul_f32_e32 v13, v13, v235
	v_mul_f32_e32 v14, v14, v235
	v_mul_f32_e32 v15, v15, v235
	v_mul_f32_e32 v16, v16, v235
	v_mul_f32_e32 v17, v17, v235
	v_mul_f32_e32 v18, v18, v235
	v_mul_f32_e32 v19, v19, v235
	v_mul_f32_e32 v20, v20, v235
	v_mul_f32_e32 v21, v21, v235
	v_mul_f32_e32 v22, v22, v235
	v_mul_f32_e32 v23, v23, v235
	v_mul_f32_e32 v24, v24, v235
	v_mul_f32_e32 v25, v25, v235
	v_mul_f32_e32 v26, v26, v235
	v_mul_f32_e32 v27, v27, v235
	v_mul_f32_e32 v28, v28, v235
	v_mul_f32_e32 v29, v29, v235
	v_mul_f32_e32 v30, v30, v235
	v_mul_f32_e32 v31, v31, v235
	v_mul_f32_e32 v32, v32, v235
	v_mul_f32_e32 v33, v33, v235
	v_sub_f32_e32 v122, 0, v230
	v_mov_b32_e32 v123, v122
	v_mov_b32_e32 v124, v122
	v_mov_b32_e32 v125, v122
	v_mov_b32_e32 v126, v122
	v_mov_b32_e32 v127, v122
	v_mov_b32_e32 v128, v122
	v_mov_b32_e32 v129, v122
	v_mov_b32_e32 v130, v122
	v_mov_b32_e32 v131, v122
	v_mov_b32_e32 v132, v122
	v_mov_b32_e32 v133, v122
	v_mov_b32_e32 v134, v122
	v_mov_b32_e32 v135, v122
	v_mov_b32_e32 v136, v122
	v_mov_b32_e32 v137, v122
.Lmls_nr_p0:
	ds_read_b128 v[138:141], v220 offset:26624
	ds_read_b128 v[142:145], v220 offset:33280
	ds_read_b128 v[146:149], v220 offset:26656
	ds_read_b128 v[150:153], v220 offset:33312
	ds_read_b128 v[154:157], v220 offset:26688
	ds_read_b128 v[158:161], v220 offset:33344
	s_waitcnt lgkmcnt(6)
	s_barrier
	v_exp_f32_e32 v66, v66
	v_exp_f32_e32 v67, v67
	v_exp_f32_e32 v68, v68
	v_exp_f32_e32 v69, v69
	s_waitcnt lgkmcnt(4)
	v_mfma_f32_32x32x16_bf16 v[34:49], v[138:141], v[98:101], v[122:137]
	ds_read_b128 v[138:141], v220 offset:26720
	v_add_f32_e32 v231, v231, v66
	v_add_f32_e32 v232, v232, v67
	v_exp_f32_e32 v70, v70
	v_exp_f32_e32 v71, v71
	v_mfma_f32_32x32x16_bf16 v[50:65], v[142:145], v[98:101], v[122:137]
	ds_read_b128 v[142:145], v220 offset:33376
	v_add_f32_e32 v240, v240, v68
	v_add_f32_e32 v241, v241, v69
	v_exp_f32_e32 v72, v72
	v_exp_f32_e32 v73, v73
	s_waitcnt lgkmcnt(4)
	v_mfma_f32_32x32x16_bf16 v[34:49], v[146:149], v[102:105], v[34:49]
	ds_read_b128 v[146:149], v220 offset:26752
	global_load_dwordx4 v[216:219], v229, s[10:11]
	s_add_u32 s10, s10, 0x80
	s_addc_u32 s11, s11, 0
	v_add_f32_e32 v231, v231, v70
	v_add_f32_e32 v232, v232, v71
	v_add_f32_e32 v240, v240, v72
	v_add_f32_e32 v241, v241, v73
	v_cvt_pk_bf16_f32 v66, v66, v67
	v_cvt_pk_bf16_f32 v67, v68, v69
	v_mfma_f32_32x32x16_bf16 v[50:65], v[150:153], v[102:105], v[50:65]
	ds_read_b128 v[150:153], v220 offset:33408
	v_cvt_pk_bf16_f32 v68, v70, v71
	v_cvt_pk_bf16_f32 v69, v72, v73
	v_exp_f32_e32 v74, v74
	v_exp_f32_e32 v75, v75
	s_waitcnt lgkmcnt(4)
	v_mfma_f32_32x32x16_bf16 v[34:49], v[154:157], v[106:109], v[34:49]
	ds_read_b128 v[154:157], v220 offset:26784
	v_exp_f32_e32 v76, v76
	v_exp_f32_e32 v77, v77
	v_add_f32_e32 v231, v231, v74
	v_add_f32_e32 v232, v232, v75
	v_mfma_f32_32x32x16_bf16 v[50:65], v[158:161], v[106:109], v[50:65]
	ds_read_b128 v[158:161], v220 offset:33440
	v_exp_f32_e32 v78, v78
	v_exp_f32_e32 v79, v79
	v_add_f32_e32 v240, v240, v76
	v_add_f32_e32 v241, v241, v77
	v_exp_f32_e32 v80, v80
	s_waitcnt lgkmcnt(4)
	v_mfma_f32_32x32x16_bf16 v[34:49], v[138:141], v[110:113], v[34:49]
	ds_read_b128 v[162:165], v221 offset:9216
	v_exp_f32_e32 v81, v81
	v_add_f32_e32 v231, v231, v78
	v_add_f32_e32 v232, v232, v79
	v_add_f32_e32 v240, v240, v80
	v_mfma_f32_32x32x16_bf16 v[50:65], v[142:145], v[110:113], v[50:65]
	ds_read_b128 v[166:169], v221 offset:13824
	v_add_f32_e32 v241, v241, v81
	v_cvt_pk_bf16_f32 v74, v74, v75
	v_cvt_pk_bf16_f32 v75, v76, v77
	v_cvt_pk_bf16_f32 v76, v78, v79
	v_cvt_pk_bf16_f32 v77, v80, v81
	v_exp_f32_e32 v82, v82
	s_waitcnt lgkmcnt(4)
	v_mfma_f32_32x32x16_bf16 v[34:49], v[146:149], v[114:117], v[34:49]
	ds_read_b128 v[170:173], v221 offset:9248
	v_exp_f32_e32 v83, v83
	v_exp_f32_e32 v84, v84
	v_exp_f32_e32 v85, v85
	v_mfma_f32_32x32x16_bf16 v[50:65], v[150:153], v[114:117], v[50:65]
	ds_read_b128 v[174:177], v221 offset:13856
	v_add_f32_e32 v231, v231, v82
	v_add_f32_e32 v232, v232, v83
	v_exp_f32_e32 v86, v86
	v_exp_f32_e32 v87, v87
	s_waitcnt lgkmcnt(4)
	v_mfma_f32_32x32x16_bf16 v[34:49], v[154:157], v[118:121], v[34:49]
	ds_read_b128 v[180:183], v221 offset:9280
	v_add_f32_e32 v240, v240, v84
	v_add_f32_e32 v241, v241, v85
	v_exp_f32_e32 v88, v88
	v_exp_f32_e32 v89, v89
	v_mfma_f32_32x32x16_bf16 v[50:65], v[158:161], v[118:121], v[50:65]
	ds_read_b128 v[184:187], v221 offset:13888
	v_add_f32_e32 v231, v231, v86
	v_add_f32_e32 v232, v232, v87
	v_add_f32_e32 v240, v240, v88
	v_add_f32_e32 v241, v241, v89
	v_cvt_pk_bf16_f32 v82, v82, v83
	v_cvt_pk_bf16_f32 v83, v84, v85
	v_cvt_pk_bf16_f32 v84, v86, v87
	s_waitcnt lgkmcnt(4)
	v_mfma_f32_32x32x16_bf16 v[2:17], v[162:165], v[66:69], v[2:17]
	ds_read_b128 v[188:191], v221 offset:9312
	v_cvt_pk_bf16_f32 v85, v88, v89
	v_exp_f32_e32 v90, v90
	v_exp_f32_e32 v91, v91
	v_exp_f32_e32 v92, v92
	v_mfma_f32_32x32x16_bf16 v[18:33], v[166:169], v[66:69], v[18:33]
	ds_read_b128 v[192:195], v221 offset:13920
	v_exp_f32_e32 v93, v93
	v_add_f32_e32 v231, v231, v90
	v_add_f32_e32 v232, v232, v91
	v_exp_f32_e32 v94, v94
	s_waitcnt lgkmcnt(4)
	v_mfma_f32_32x32x16_bf16 v[2:17], v[170:173], v[74:77], v[2:17]
	v_exp_f32_e32 v95, v95
	v_add_f32_e32 v240, v240, v92
	v_add_f32_e32 v241, v241, v93
	v_exp_f32_e32 v96, v96
	v_mfma_f32_32x32x16_bf16 v[18:33], v[174:177], v[74:77], v[18:33]
	s_waitcnt vmcnt(1)
	ds_write_b128 v222, v[200:203] offset:0
	ds_write_b128 v223, v[204:207] offset:0
	ds_write_b128 v224, v[208:211] offset:0
	ds_write_b64 v225, v[212:213] offset:27648
	ds_write_b64 v225, v[214:215] offset:27664
	v_exp_f32_e32 v97, v97
	v_add_f32_e32 v231, v231, v94
	v_add_f32_e32 v232, v232, v95
	v_add_f32_e32 v240, v240, v96
	v_add_f32_e32 v241, v241, v97
	s_waitcnt lgkmcnt(7)
	v_mfma_f32_32x32x16_bf16 v[2:17], v[180:183], v[82:85], v[2:17]
	v_cvt_pk_bf16_f32 v90, v90, v91
	v_cvt_pk_bf16_f32 v91, v92, v93
	v_cvt_pk_bf16_f32 v92, v94, v95
	v_cvt_pk_bf16_f32 v93, v96, v97
	v_max3_f32 v234, v34, v35, v36
	v_max3_f32 v235, v50, v51, v52
	v_mfma_f32_32x32x16_bf16 v[18:33], v[184:187], v[82:85], v[18:33]
	v_max3_f32 v234, v234, v37, v38
	v_max3_f32 v235, v235, v53, v54
	v_max3_f32 v234, v234, v39, v40
	v_max3_f32 v235, v235, v55, v56
	v_max3_f32 v234, v234, v41, v42
	v_max3_f32 v235, v235, v57, v58
	v_max3_f32 v234, v234, v43, v44
	s_waitcnt lgkmcnt(5)
	v_mfma_f32_32x32x16_bf16 v[2:17], v[188:191], v[90:93], v[2:17]
	v_max3_f32 v235, v235, v59, v60
	v_max3_f32 v234, v234, v45, v46
	v_max3_f32 v235, v235, v61, v62
	v_max3_f32 v234, v234, v47, v48
	v_max3_f32 v235, v235, v63, v64
	v_max3_f32 v234, v234, v49, v65
	v_mfma_f32_32x32x16_bf16 v[18:33], v[192:195], v[90:93], v[18:33]
	v_max_f32_e32 v234, v234, v235
	v_mov_b32_e32 v235, v234
	s_nop 1
	v_permlane32_swap_b32_e32 v234, v235
	v_max_f32_e32 v233, v234, v235
	v_cmp_lt_f32_e32 vcc, 4.0, v233
	s_cbranch_vccz .Lmls_nr_p1
	s_nop 15
	v_max_f32_e32 v234, 0, v233
	v_exp_f32_e64 v235, -v234
	v_add_f32_e32 v230, v230, v234
	v_sub_f32_e32 v34, v34, v234
	v_sub_f32_e32 v35, v35, v234
	v_sub_f32_e32 v36, v36, v234
	v_sub_f32_e32 v37, v37, v234
	v_sub_f32_e32 v38, v38, v234
	v_sub_f32_e32 v39, v39, v234
	v_sub_f32_e32 v40, v40, v234
	v_sub_f32_e32 v41, v41, v234
	v_sub_f32_e32 v42, v42, v234
	v_sub_f32_e32 v43, v43, v234
	v_sub_f32_e32 v44, v44, v234
	v_sub_f32_e32 v45, v45, v234
	v_sub_f32_e32 v46, v46, v234
	v_sub_f32_e32 v47, v47, v234
	v_sub_f32_e32 v48, v48, v234
	v_sub_f32_e32 v49, v49, v234
	v_sub_f32_e32 v50, v50, v234
	v_sub_f32_e32 v51, v51, v234
	v_sub_f32_e32 v52, v52, v234
	v_sub_f32_e32 v53, v53, v234
	v_sub_f32_e32 v54, v54, v234
	v_sub_f32_e32 v55, v55, v234
	v_sub_f32_e32 v56, v56, v234
	v_sub_f32_e32 v57, v57, v234
	v_sub_f32_e32 v58, v58, v234
	v_sub_f32_e32 v59, v59, v234
	v_sub_f32_e32 v60, v60, v234
	v_sub_f32_e32 v61, v61, v234
	v_sub_f32_e32 v62, v62, v234
	v_sub_f32_e32 v63, v63, v234
	v_sub_f32_e32 v64, v64, v234
	v_sub_f32_e32 v65, v65, v234
	v_mul_f32_e32 v231, v231, v235
	v_mul_f32_e32 v232, v232, v235
	v_mul_f32_e32 v240, v240, v235
	v_mul_f32_e32 v241, v241, v235
	v_mul_f32_e32 v2, v2, v235
	v_mul_f32_e32 v3, v3, v235
	v_mul_f32_e32 v4, v4, v235
	v_mul_f32_e32 v5, v5, v235
	v_mul_f32_e32 v6, v6, v235
	v_mul_f32_e32 v7, v7, v235
	v_mul_f32_e32 v8, v8, v235
	v_mul_f32_e32 v9, v9, v235
	v_mul_f32_e32 v10, v10, v235
	v_mul_f32_e32 v11, v11, v235
	v_mul_f32_e32 v12, v12, v235
	v_mul_f32_e32 v13, v13, v235
	v_mul_f32_e32 v14, v14, v235
	v_mul_f32_e32 v15, v15, v235
	v_mul_f32_e32 v16, v16, v235
	v_mul_f32_e32 v17, v17, v235
	v_mul_f32_e32 v18, v18, v235
	v_mul_f32_e32 v19, v19, v235
	v_mul_f32_e32 v20, v20, v235
	v_mul_f32_e32 v21, v21, v235
	v_mul_f32_e32 v22, v22, v235
	v_mul_f32_e32 v23, v23, v235
	v_mul_f32_e32 v24, v24, v235
	v_mul_f32_e32 v25, v25, v235
	v_mul_f32_e32 v26, v26, v235
	v_mul_f32_e32 v27, v27, v235
	v_mul_f32_e32 v28, v28, v235
	v_mul_f32_e32 v29, v29, v235
	v_mul_f32_e32 v30, v30, v235
	v_mul_f32_e32 v31, v31, v235
	v_mul_f32_e32 v32, v32, v235
	v_mul_f32_e32 v33, v33, v235
	v_sub_f32_e32 v122, 0, v230
	v_mov_b32_e32 v123, v122
	v_mov_b32_e32 v124, v122
	v_mov_b32_e32 v125, v122
	v_mov_b32_e32 v126, v122
	v_mov_b32_e32 v127, v122
	v_mov_b32_e32 v128, v122
	v_mov_b32_e32 v129, v122
	v_mov_b32_e32 v130, v122
	v_mov_b32_e32 v131, v122
	v_mov_b32_e32 v132, v122
	v_mov_b32_e32 v133, v122
	v_mov_b32_e32 v134, v122
	v_mov_b32_e32 v135, v122
	v_mov_b32_e32 v136, v122
	v_mov_b32_e32 v137, v122
.Lmls_nr_p1:
	ds_read_b128 v[138:141], v220 offset:39936
	ds_read_b128 v[142:145], v220 offset:46592
	ds_read_b128 v[146:149], v220 offset:39968
	ds_read_b128 v[150:153], v220 offset:46624
	ds_read_b128 v[154:157], v220 offset:40000
	ds_read_b128 v[158:161], v220 offset:46656
	s_waitcnt lgkmcnt(6)
	s_barrier
	v_exp_f32_e32 v34, v34
	v_exp_f32_e32 v35, v35
	v_exp_f32_e32 v36, v36
	v_exp_f32_e32 v37, v37
	s_waitcnt lgkmcnt(4)
	v_mfma_f32_32x32x16_bf16 v[66:81], v[138:141], v[98:101], v[122:137]
	ds_read_b128 v[138:141], v220 offset:40032
	v_add_f32_e32 v231, v231, v34
	v_add_f32_e32 v232, v232, v35
	v_exp_f32_e32 v38, v38
	v_exp_f32_e32 v39, v39
	v_mfma_f32_32x32x16_bf16 v[82:97], v[142:145], v[98:101], v[122:137]
	ds_read_b128 v[142:145], v220 offset:46688
	v_add_f32_e32 v240, v240, v36
	v_add_f32_e32 v241, v241, v37
	v_exp_f32_e32 v40, v40
	v_exp_f32_e32 v41, v41
	s_waitcnt lgkmcnt(4)
	v_mfma_f32_32x32x16_bf16 v[66:81], v[146:149], v[102:105], v[66:81]
	ds_read_b128 v[146:149], v220 offset:40064
	global_load_dwordx4 v[200:203], v226, s[4:5]
	global_load_dwordx4 v[204:207], v227, s[4:5]
	global_load_dwordx4 v[208:211], v228, s[4:5]
	s_add_u32 s4, s4, 0x6000
	s_addc_u32 s5, s5, 0
	global_load_dwordx4 v[212:215], v229, s[10:11]
	s_add_u32 s10, s10, 0x80
	s_addc_u32 s11, s11, 0
	v_add_f32_e32 v231, v231, v38
	v_add_f32_e32 v232, v232, v39
	v_add_f32_e32 v240, v240, v40
	v_add_f32_e32 v241, v241, v41
	v_cvt_pk_bf16_f32 v34, v34, v35
	v_cvt_pk_bf16_f32 v35, v36, v37
	v_mfma_f32_32x32x16_bf16 v[82:97], v[150:153], v[102:105], v[82:97]
	ds_read_b128 v[150:153], v220 offset:46720
	v_cvt_pk_bf16_f32 v36, v38, v39
	v_cvt_pk_bf16_f32 v37, v40, v41
	v_exp_f32_e32 v42, v42
	v_exp_f32_e32 v43, v43
	s_waitcnt lgkmcnt(4)
	v_mfma_f32_32x32x16_bf16 v[66:81], v[154:157], v[106:109], v[66:81]
	ds_read_b128 v[154:157], v220 offset:40096
	v_exp_f32_e32 v44, v44
	v_exp_f32_e32 v45, v45
	v_add_f32_e32 v231, v231, v42
	v_add_f32_e32 v232, v232, v43
	v_mfma_f32_32x32x16_bf16 v[82:97], v[158:161], v[106:109], v[82:97]
	ds_read_b128 v[158:161], v220 offset:46752
	v_exp_f32_e32 v46, v46
	v_exp_f32_e32 v47, v47
	v_add_f32_e32 v240, v240, v44
	v_add_f32_e32 v241, v241, v45
	v_exp_f32_e32 v48, v48
	s_waitcnt lgkmcnt(4)
	v_mfma_f32_32x32x16_bf16 v[66:81], v[138:141], v[110:113], v[66:81]
	ds_read_b128 v[162:165], v221 offset:18432
	v_exp_f32_e32 v49, v49
	v_add_f32_e32 v231, v231, v46
	v_add_f32_e32 v232, v232, v47
	v_add_f32_e32 v240, v240, v48
	v_mfma_f32_32x32x16_bf16 v[82:97], v[142:145], v[110:113], v[82:97]
	ds_read_b128 v[166:169], v221 offset:23040
	v_add_f32_e32 v241, v241, v49
	v_cvt_pk_bf16_f32 v42, v42, v43
	v_cvt_pk_bf16_f32 v43, v44, v45
	v_cvt_pk_bf16_f32 v44, v46, v47
	v_cvt_pk_bf16_f32 v45, v48, v49
	v_exp_f32_e32 v50, v50
	s_waitcnt lgkmcnt(4)
	v_mfma_f32_32x32x16_bf16 v[66:81], v[146:149], v[114:117], v[66:81]
	ds_read_b128 v[170:173], v221 offset:18464
	v_exp_f32_e32 v51, v51
	v_exp_f32_e32 v52, v52
	v_exp_f32_e32 v53, v53
	v_mfma_f32_32x32x16_bf16 v[82:97], v[150:153], v[114:117], v[82:97]
	ds_read_b128 v[174:177], v221 offset:23072
	v_add_f32_e32 v231, v231, v50
	v_add_f32_e32 v232, v232, v51
	v_exp_f32_e32 v54, v54
	v_exp_f32_e32 v55, v55
	s_waitcnt lgkmcnt(4)
	v_mfma_f32_32x32x16_bf16 v[66:81], v[154:157], v[118:121], v[66:81]
	ds_read_b128 v[180:183], v221 offset:18496
	v_add_f32_e32 v240, v240, v52
	v_add_f32_e32 v241, v241, v53
	v_exp_f32_e32 v56, v56
	v_exp_f32_e32 v57, v57
	v_mfma_f32_32x32x16_bf16 v[82:97], v[158:161], v[118:121], v[82:97]
	ds_read_b128 v[184:187], v221 offset:23104
	v_add_f32_e32 v231, v231, v54
	v_add_f32_e32 v232, v232, v55
	v_add_f32_e32 v240, v240, v56
	v_add_f32_e32 v241, v241, v57
	v_cvt_pk_bf16_f32 v50, v50, v51
	v_cvt_pk_bf16_f32 v51, v52, v53
	v_cvt_pk_bf16_f32 v52, v54, v55
	s_waitcnt lgkmcnt(4)
	v_mfma_f32_32x32x16_bf16 v[2:17], v[162:165], v[34:37], v[2:17]
	ds_read_b128 v[188:191], v221 offset:18528
	v_cvt_pk_bf16_f32 v53, v56, v57
	v_exp_f32_e32 v58, v58
	v_exp_f32_e32 v59, v59
	v_exp_f32_e32 v60, v60
	v_mfma_f32_32x32x16_bf16 v[18:33], v[166:169], v[34:37], v[18:33]
	ds_read_b128 v[192:195], v221 offset:23136
	v_exp_f32_e32 v61, v61
	v_add_f32_e32 v231, v231, v58
	v_add_f32_e32 v232, v232, v59
	v_exp_f32_e32 v62, v62
	s_waitcnt lgkmcnt(4)
	v_mfma_f32_32x32x16_bf16 v[2:17], v[170:173], v[42:45], v[2:17]
	v_exp_f32_e32 v63, v63
	v_add_f32_e32 v240, v240, v60
	v_add_f32_e32 v241, v241, v61
	v_exp_f32_e32 v64, v64
	v_mfma_f32_32x32x16_bf16 v[18:33], v[174:177], v[42:45], v[18:33]
	s_waitcnt vmcnt(4)
	ds_write_b64 v225, v[216:217] offset:0
	ds_write_b64 v225, v[218:219] offset:16
	v_exp_f32_e32 v65, v65
	v_add_f32_e32 v231, v231, v62
	v_add_f32_e32 v232, v232, v63
	v_add_f32_e32 v240, v240, v64
	v_add_f32_e32 v241, v241, v65
	s_waitcnt lgkmcnt(4)
	v_mfma_f32_32x32x16_bf16 v[2:17], v[180:183], v[50:53], v[2:17]
	v_cvt_pk_bf16_f32 v58, v58, v59
	v_cvt_pk_bf16_f32 v59, v60, v61
	v_cvt_pk_bf16_f32 v60, v62, v63
	v_cvt_pk_bf16_f32 v61, v64, v65
	v_max3_f32 v234, v66, v67, v68
	v_max3_f32 v235, v82, v83, v84
	v_mfma_f32_32x32x16_bf16 v[18:33], v[184:187], v[50:53], v[18:33]
	v_max3_f32 v234, v234, v69, v70
	v_max3_f32 v235, v235, v85, v86
	v_max3_f32 v234, v234, v71, v72
	v_max3_f32 v235, v235, v87, v88
	v_max3_f32 v234, v234, v73, v74
	v_max3_f32 v235, v235, v89, v90
	v_max3_f32 v234, v234, v75, v76
	s_waitcnt lgkmcnt(2)
	v_mfma_f32_32x32x16_bf16 v[2:17], v[188:191], v[58:61], v[2:17]
	v_max3_f32 v235, v235, v91, v92
	v_max3_f32 v234, v234, v77, v78
	v_max3_f32 v235, v235, v93, v94
	v_max3_f32 v234, v234, v79, v80
	v_max3_f32 v235, v235, v95, v96
	v_max3_f32 v234, v234, v81, v97
	v_mfma_f32_32x32x16_bf16 v[18:33], v[192:195], v[58:61], v[18:33]
	v_max_f32_e32 v234, v234, v235
	v_mov_b32_e32 v235, v234
	s_nop 1
	v_permlane32_swap_b32_e32 v234, v235
	v_max_f32_e32 v233, v234, v235
	v_cmp_lt_f32_e32 vcc, 4.0, v233
	s_cbranch_vccz .Lmls_nr_p2
	s_nop 15
	v_max_f32_e32 v234, 0, v233
	v_exp_f32_e64 v235, -v234
	v_add_f32_e32 v230, v230, v234
	v_sub_f32_e32 v66, v66, v234
	v_sub_f32_e32 v67, v67, v234
	v_sub_f32_e32 v68, v68, v234
	v_sub_f32_e32 v69, v69, v234
	v_sub_f32_e32 v70, v70, v234
	v_sub_f32_e32 v71, v71, v234
	v_sub_f32_e32 v72, v72, v234
	v_sub_f32_e32 v73, v73, v234
	v_sub_f32_e32 v74, v74, v234
	v_sub_f32_e32 v75, v75, v234
	v_sub_f32_e32 v76, v76, v234
	v_sub_f32_e32 v77, v77, v234
	v_sub_f32_e32 v78, v78, v234
	v_sub_f32_e32 v79, v79, v234
	v_sub_f32_e32 v80, v80, v234
	v_sub_f32_e32 v81, v81, v234
	v_sub_f32_e32 v82, v82, v234
	v_sub_f32_e32 v83, v83, v234
	v_sub_f32_e32 v84, v84, v234
	v_sub_f32_e32 v85, v85, v234
	v_sub_f32_e32 v86, v86, v234
	v_sub_f32_e32 v87, v87, v234
	v_sub_f32_e32 v88, v88, v234
	v_sub_f32_e32 v89, v89, v234
	v_sub_f32_e32 v90, v90, v234
	v_sub_f32_e32 v91, v91, v234
	v_sub_f32_e32 v92, v92, v234
	v_sub_f32_e32 v93, v93, v234
	v_sub_f32_e32 v94, v94, v234
	v_sub_f32_e32 v95, v95, v234
	v_sub_f32_e32 v96, v96, v234
	v_sub_f32_e32 v97, v97, v234
	v_mul_f32_e32 v231, v231, v235
	v_mul_f32_e32 v232, v232, v235
	v_mul_f32_e32 v240, v240, v235
	v_mul_f32_e32 v241, v241, v235
	v_mul_f32_e32 v2, v2, v235
	v_mul_f32_e32 v3, v3, v235
	v_mul_f32_e32 v4, v4, v235
	v_mul_f32_e32 v5, v5, v235
	v_mul_f32_e32 v6, v6, v235
	v_mul_f32_e32 v7, v7, v235
	v_mul_f32_e32 v8, v8, v235
	v_mul_f32_e32 v9, v9, v235
	v_mul_f32_e32 v10, v10, v235
	v_mul_f32_e32 v11, v11, v235
	v_mul_f32_e32 v12, v12, v235
	v_mul_f32_e32 v13, v13, v235
	v_mul_f32_e32 v14, v14, v235
	v_mul_f32_e32 v15, v15, v235
	v_mul_f32_e32 v16, v16, v235
	v_mul_f32_e32 v17, v17, v235
	v_mul_f32_e32 v18, v18, v235
	v_mul_f32_e32 v19, v19, v235
	v_mul_f32_e32 v20, v20, v235
	v_mul_f32_e32 v21, v21, v235
	v_mul_f32_e32 v22, v22, v235
	v_mul_f32_e32 v23, v23, v235
	v_mul_f32_e32 v24, v24, v235
	v_mul_f32_e32 v25, v25, v235
	v_mul_f32_e32 v26, v26, v235
	v_mul_f32_e32 v27, v27, v235
	v_mul_f32_e32 v28, v28, v235
	v_mul_f32_e32 v29, v29, v235
	v_mul_f32_e32 v30, v30, v235
	v_mul_f32_e32 v31, v31, v235
	v_mul_f32_e32 v32, v32, v235
	v_mul_f32_e32 v33, v33, v235
	v_sub_f32_e32 v122, 0, v230
	v_mov_b32_e32 v123, v122
	v_mov_b32_e32 v124, v122
	v_mov_b32_e32 v125, v122
	v_mov_b32_e32 v126, v122
	v_mov_b32_e32 v127, v122
	v_mov_b32_e32 v128, v122
	v_mov_b32_e32 v129, v122
	v_mov_b32_e32 v130, v122
	v_mov_b32_e32 v131, v122
	v_mov_b32_e32 v132, v122
	v_mov_b32_e32 v133, v122
	v_mov_b32_e32 v134, v122
	v_mov_b32_e32 v135, v122
	v_mov_b32_e32 v136, v122
	v_mov_b32_e32 v137, v122
.Lmls_nr_p2:
	ds_read_b128 v[138:141], v220 offset:0
	ds_read_b128 v[142:145], v220 offset:6656
	ds_read_b128 v[146:149], v220 offset:32
	ds_read_b128 v[150:153], v220 offset:6688
	ds_read_b128 v[154:157], v220 offset:64
	ds_read_b128 v[158:161], v220 offset:6720
	s_waitcnt lgkmcnt(6)
	s_barrier
	v_exp_f32_e32 v66, v66
	v_exp_f32_e32 v67, v67
	v_exp_f32_e32 v68, v68
	v_exp_f32_e32 v69, v69
	s_waitcnt lgkmcnt(4)
	v_mfma_f32_32x32x16_bf16 v[34:49], v[138:141], v[98:101], v[122:137]
	ds_read_b128 v[138:141], v220 offset:96
	v_add_f32_e32 v231, v231, v66
	v_add_f32_e32 v232, v232, v67
	v_exp_f32_e32 v70, v70
	v_exp_f32_e32 v71, v71
	v_mfma_f32_32x32x16_bf16 v[50:65], v[142:145], v[98:101], v[122:137]
	ds_read_b128 v[142:145], v220 offset:6752
	v_add_f32_e32 v240, v240, v68
	v_add_f32_e32 v241, v241, v69
	v_exp_f32_e32 v72, v72
	v_exp_f32_e32 v73, v73
	s_waitcnt lgkmcnt(4)
	v_mfma_f32_32x32x16_bf16 v[34:49], v[146:149], v[102:105], v[34:49]
	ds_read_b128 v[146:149], v220 offset:128
	global_load_dwordx4 v[216:219], v229, s[10:11]
	s_add_u32 s10, s10, 0x80
	s_addc_u32 s11, s11, 0
	v_add_f32_e32 v231, v231, v70
	v_add_f32_e32 v232, v232, v71
	v_add_f32_e32 v240, v240, v72
	v_add_f32_e32 v241, v241, v73
	v_cvt_pk_bf16_f32 v66, v66, v67
	v_cvt_pk_bf16_f32 v67, v68, v69
	v_mfma_f32_32x32x16_bf16 v[50:65], v[150:153], v[102:105], v[50:65]
	ds_read_b128 v[150:153], v220 offset:6784
	v_cvt_pk_bf16_f32 v68, v70, v71
	v_cvt_pk_bf16_f32 v69, v72, v73
	v_exp_f32_e32 v74, v74
	v_exp_f32_e32 v75, v75
	s_waitcnt lgkmcnt(4)
	v_mfma_f32_32x32x16_bf16 v[34:49], v[154:157], v[106:109], v[34:49]
	ds_read_b128 v[154:157], v220 offset:160
	v_exp_f32_e32 v76, v76
	v_exp_f32_e32 v77, v77
	v_add_f32_e32 v231, v231, v74
	v_add_f32_e32 v232, v232, v75
	v_mfma_f32_32x32x16_bf16 v[50:65], v[158:161], v[106:109], v[50:65]
	ds_read_b128 v[158:161], v220 offset:6816
	v_exp_f32_e32 v78, v78
	v_exp_f32_e32 v79, v79
	v_add_f32_e32 v240, v240, v76
	v_add_f32_e32 v241, v241, v77
	v_exp_f32_e32 v80, v80
	s_waitcnt lgkmcnt(4)
	v_mfma_f32_32x32x16_bf16 v[34:49], v[138:141], v[110:113], v[34:49]
	ds_read_b128 v[162:165], v221 offset:27648
	v_exp_f32_e32 v81, v81
	v_add_f32_e32 v231, v231, v78
	v_add_f32_e32 v232, v232, v79
	v_add_f32_e32 v240, v240, v80
	v_mfma_f32_32x32x16_bf16 v[50:65], v[142:145], v[110:113], v[50:65]
	ds_read_b128 v[166:169], v221 offset:32256
	v_add_f32_e32 v241, v241, v81
	v_cvt_pk_bf16_f32 v74, v74, v75
	v_cvt_pk_bf16_f32 v75, v76, v77
	v_cvt_pk_bf16_f32 v76, v78, v79
	v_cvt_pk_bf16_f32 v77, v80, v81
	v_exp_f32_e32 v82, v82
	s_waitcnt lgkmcnt(4)
	v_mfma_f32_32x32x16_bf16 v[34:49], v[146:149], v[114:117], v[34:49]
	ds_read_b128 v[170:173], v221 offset:27680
	v_exp_f32_e32 v83, v83
	v_exp_f32_e32 v84, v84
	v_exp_f32_e32 v85, v85
	v_mfma_f32_32x32x16_bf16 v[50:65], v[150:153], v[114:117], v[50:65]
	ds_read_b128 v[174:177], v221 offset:32288
	v_add_f32_e32 v231, v231, v82
	v_add_f32_e32 v232, v232, v83
	v_exp_f32_e32 v86, v86
	v_exp_f32_e32 v87, v87
	s_waitcnt lgkmcnt(4)
	v_mfma_f32_32x32x16_bf16 v[34:49], v[154:157], v[118:121], v[34:49]
	ds_read_b128 v[180:183], v221 offset:27712
	v_add_f32_e32 v240, v240, v84
	v_add_f32_e32 v241, v241, v85
	v_exp_f32_e32 v88, v88
	v_exp_f32_e32 v89, v89
	v_mfma_f32_32x32x16_bf16 v[50:65], v[158:161], v[118:121], v[50:65]
	ds_read_b128 v[184:187], v221 offset:32320
	v_add_f32_e32 v231, v231, v86
	v_add_f32_e32 v232, v232, v87
	v_add_f32_e32 v240, v240, v88
	v_add_f32_e32 v241, v241, v89
	v_cvt_pk_bf16_f32 v82, v82, v83
	v_cvt_pk_bf16_f32 v83, v84, v85
	v_cvt_pk_bf16_f32 v84, v86, v87
	s_waitcnt lgkmcnt(4)
	v_mfma_f32_32x32x16_bf16 v[2:17], v[162:165], v[66:69], v[2:17]
	ds_read_b128 v[188:191], v221 offset:27744
	v_cvt_pk_bf16_f32 v85, v88, v89
	v_exp_f32_e32 v90, v90
	v_exp_f32_e32 v91, v91
	v_exp_f32_e32 v92, v92
	v_mfma_f32_32x32x16_bf16 v[18:33], v[166:169], v[66:69], v[18:33]
	ds_read_b128 v[192:195], v221 offset:32352
	v_exp_f32_e32 v93, v93
	v_add_f32_e32 v231, v231, v90
	v_add_f32_e32 v232, v232, v91
	v_exp_f32_e32 v94, v94
	s_waitcnt lgkmcnt(4)
	v_mfma_f32_32x32x16_bf16 v[2:17], v[170:173], v[74:77], v[2:17]
	v_exp_f32_e32 v95, v95
	v_add_f32_e32 v240, v240, v92
	v_add_f32_e32 v241, v241, v93
	v_exp_f32_e32 v96, v96
	v_mfma_f32_32x32x16_bf16 v[18:33], v[174:177], v[74:77], v[18:33]
	s_waitcnt vmcnt(1)
	ds_write_b128 v222, v[200:203] offset:26624
	ds_write_b128 v223, v[204:207] offset:26624
	ds_write_b128 v224, v[208:211] offset:26624
	ds_write_b64 v225, v[212:213] offset:9216
	ds_write_b64 v225, v[214:215] offset:9232
	v_exp_f32_e32 v97, v97
	v_add_f32_e32 v231, v231, v94
	v_add_f32_e32 v232, v232, v95
	v_add_f32_e32 v240, v240, v96
	v_add_f32_e32 v241, v241, v97
	s_waitcnt lgkmcnt(7)
	v_mfma_f32_32x32x16_bf16 v[2:17], v[180:183], v[82:85], v[2:17]
	v_cvt_pk_bf16_f32 v90, v90, v91
	v_cvt_pk_bf16_f32 v91, v92, v93
	v_cvt_pk_bf16_f32 v92, v94, v95
	v_cvt_pk_bf16_f32 v93, v96, v97
	v_max3_f32 v234, v34, v35, v36
	v_max3_f32 v235, v50, v51, v52
	v_mfma_f32_32x32x16_bf16 v[18:33], v[184:187], v[82:85], v[18:33]
	v_max3_f32 v234, v234, v37, v38
	v_max3_f32 v235, v235, v53, v54
	v_max3_f32 v234, v234, v39, v40
	v_max3_f32 v235, v235, v55, v56
	v_max3_f32 v234, v234, v41, v42
	v_max3_f32 v235, v235, v57, v58
	v_max3_f32 v234, v234, v43, v44
	s_waitcnt lgkmcnt(5)
	v_mfma_f32_32x32x16_bf16 v[2:17], v[188:191], v[90:93], v[2:17]
	v_max3_f32 v235, v235, v59, v60
	v_max3_f32 v234, v234, v45, v46
	v_max3_f32 v235, v235, v61, v62
	v_max3_f32 v234, v234, v47, v48
	v_max3_f32 v235, v235, v63, v64
	v_max3_f32 v234, v234, v49, v65
	v_mfma_f32_32x32x16_bf16 v[18:33], v[192:195], v[90:93], v[18:33]
	v_max_f32_e32 v234, v234, v235
	v_mov_b32_e32 v235, v234
	s_nop 1
	v_permlane32_swap_b32_e32 v234, v235
	v_max_f32_e32 v233, v234, v235
	v_cmp_lt_f32_e32 vcc, 4.0, v233
	s_cbranch_vccz .Lmls_nr_p3
	s_nop 15
	v_max_f32_e32 v234, 0, v233
	v_exp_f32_e64 v235, -v234
	v_add_f32_e32 v230, v230, v234
	v_sub_f32_e32 v34, v34, v234
	v_sub_f32_e32 v35, v35, v234
	v_sub_f32_e32 v36, v36, v234
	v_sub_f32_e32 v37, v37, v234
	v_sub_f32_e32 v38, v38, v234
	v_sub_f32_e32 v39, v39, v234
	v_sub_f32_e32 v40, v40, v234
	v_sub_f32_e32 v41, v41, v234
	v_sub_f32_e32 v42, v42, v234
	v_sub_f32_e32 v43, v43, v234
	v_sub_f32_e32 v44, v44, v234
	v_sub_f32_e32 v45, v45, v234
	v_sub_f32_e32 v46, v46, v234
	v_sub_f32_e32 v47, v47, v234
	v_sub_f32_e32 v48, v48, v234
	v_sub_f32_e32 v49, v49, v234
	v_sub_f32_e32 v50, v50, v234
	v_sub_f32_e32 v51, v51, v234
	v_sub_f32_e32 v52, v52, v234
	v_sub_f32_e32 v53, v53, v234
	v_sub_f32_e32 v54, v54, v234
	v_sub_f32_e32 v55, v55, v234
	v_sub_f32_e32 v56, v56, v234
	v_sub_f32_e32 v57, v57, v234
	v_sub_f32_e32 v58, v58, v234
	v_sub_f32_e32 v59, v59, v234
	v_sub_f32_e32 v60, v60, v234
	v_sub_f32_e32 v61, v61, v234
	v_sub_f32_e32 v62, v62, v234
	v_sub_f32_e32 v63, v63, v234
	v_sub_f32_e32 v64, v64, v234
	v_sub_f32_e32 v65, v65, v234
	v_mul_f32_e32 v231, v231, v235
	v_mul_f32_e32 v232, v232, v235
	v_mul_f32_e32 v240, v240, v235
	v_mul_f32_e32 v241, v241, v235
	v_mul_f32_e32 v2, v2, v235
	v_mul_f32_e32 v3, v3, v235
	v_mul_f32_e32 v4, v4, v235
	v_mul_f32_e32 v5, v5, v235
	v_mul_f32_e32 v6, v6, v235
	v_mul_f32_e32 v7, v7, v235
	v_mul_f32_e32 v8, v8, v235
	v_mul_f32_e32 v9, v9, v235
	v_mul_f32_e32 v10, v10, v235
	v_mul_f32_e32 v11, v11, v235
	v_mul_f32_e32 v12, v12, v235
	v_mul_f32_e32 v13, v13, v235
	v_mul_f32_e32 v14, v14, v235
	v_mul_f32_e32 v15, v15, v235
	v_mul_f32_e32 v16, v16, v235
	v_mul_f32_e32 v17, v17, v235
	v_mul_f32_e32 v18, v18, v235
	v_mul_f32_e32 v19, v19, v235
	v_mul_f32_e32 v20, v20, v235
	v_mul_f32_e32 v21, v21, v235
	v_mul_f32_e32 v22, v22, v235
	v_mul_f32_e32 v23, v23, v235
	v_mul_f32_e32 v24, v24, v235
	v_mul_f32_e32 v25, v25, v235
	v_mul_f32_e32 v26, v26, v235
	v_mul_f32_e32 v27, v27, v235
	v_mul_f32_e32 v28, v28, v235
	v_mul_f32_e32 v29, v29, v235
	v_mul_f32_e32 v30, v30, v235
	v_mul_f32_e32 v31, v31, v235
	v_mul_f32_e32 v32, v32, v235
	v_mul_f32_e32 v33, v33, v235
	v_sub_f32_e32 v122, 0, v230
	v_mov_b32_e32 v123, v122
	v_mov_b32_e32 v124, v122
	v_mov_b32_e32 v125, v122
	v_mov_b32_e32 v126, v122
	v_mov_b32_e32 v127, v122
	v_mov_b32_e32 v128, v122
	v_mov_b32_e32 v129, v122
	v_mov_b32_e32 v130, v122
	v_mov_b32_e32 v131, v122
	v_mov_b32_e32 v132, v122
	v_mov_b32_e32 v133, v122
	v_mov_b32_e32 v134, v122
	v_mov_b32_e32 v135, v122
	v_mov_b32_e32 v136, v122
	v_mov_b32_e32 v137, v122
.Lmls_nr_p3:
	ds_read_b128 v[138:141], v220 offset:13312
	ds_read_b128 v[142:145], v220 offset:19968
	ds_read_b128 v[146:149], v220 offset:13344
	ds_read_b128 v[150:153], v220 offset:20000
	ds_read_b128 v[154:157], v220 offset:13376
	ds_read_b128 v[158:161], v220 offset:20032
	s_waitcnt lgkmcnt(6)
	s_barrier
	s_add_i32 s16, s16, -1
	s_cmp_lg_u32 s16, 0
	s_cbranch_scc1 .Lmls_loop
	v_exp_f32_e32 v34, v34
	v_exp_f32_e32 v35, v35
	v_exp_f32_e32 v36, v36
	v_exp_f32_e32 v37, v37
	s_waitcnt lgkmcnt(4)
	v_mfma_f32_32x32x16_bf16 v[66:81], v[138:141], v[98:101], v[122:137]
	ds_read_b128 v[138:141], v220 offset:13408
	v_add_f32_e32 v231, v231, v34
	v_add_f32_e32 v232, v232, v35
	v_exp_f32_e32 v38, v38
	v_exp_f32_e32 v39, v39
	v_mfma_f32_32x32x16_bf16 v[82:97], v[142:145], v[98:101], v[122:137]
	ds_read_b128 v[142:145], v220 offset:20064
	v_add_f32_e32 v240, v240, v36
	v_add_f32_e32 v241, v241, v37
	v_exp_f32_e32 v40, v40
	v_exp_f32_e32 v41, v41
	s_waitcnt lgkmcnt(4)
	v_mfma_f32_32x32x16_bf16 v[66:81], v[146:149], v[102:105], v[66:81]
	ds_read_b128 v[146:149], v220 offset:13440
	global_load_dwordx4 v[212:215], v229, s[10:11]
	s_add_u32 s10, s10, 0x80
	s_addc_u32 s11, s11, 0
	v_add_f32_e32 v231, v231, v38
	v_add_f32_e32 v232, v232, v39
	v_add_f32_e32 v240, v240, v40
	v_add_f32_e32 v241, v241, v41
	v_cvt_pk_bf16_f32 v34, v34, v35
	v_cvt_pk_bf16_f32 v35, v36, v37
	v_mfma_f32_32x32x16_bf16 v[82:97], v[150:153], v[102:105], v[82:97]
	ds_read_b128 v[150:153], v220 offset:20096
	v_cvt_pk_bf16_f32 v36, v38, v39
	v_cvt_pk_bf16_f32 v37, v40, v41
	v_exp_f32_e32 v42, v42
	v_exp_f32_e32 v43, v43
	s_waitcnt lgkmcnt(4)
	v_mfma_f32_32x32x16_bf16 v[66:81], v[154:157], v[106:109], v[66:81]
	ds_read_b128 v[154:157], v220 offset:13472
	v_exp_f32_e32 v44, v44
	v_exp_f32_e32 v45, v45
	v_add_f32_e32 v231, v231, v42
	v_add_f32_e32 v232, v232, v43
	v_mfma_f32_32x32x16_bf16 v[82:97], v[158:161], v[106:109], v[82:97]
	ds_read_b128 v[158:161], v220 offset:20128
	v_exp_f32_e32 v46, v46
	v_exp_f32_e32 v47, v47
	v_add_f32_e32 v240, v240, v44
	v_add_f32_e32 v241, v241, v45
	v_exp_f32_e32 v48, v48
	s_waitcnt lgkmcnt(4)
	v_mfma_f32_32x32x16_bf16 v[66:81], v[138:141], v[110:113], v[66:81]
	ds_read_b128 v[162:165], v221 offset:0
	v_exp_f32_e32 v49, v49
	v_add_f32_e32 v231, v231, v46
	v_add_f32_e32 v232, v232, v47
	v_add_f32_e32 v240, v240, v48
	v_mfma_f32_32x32x16_bf16 v[82:97], v[142:145], v[110:113], v[82:97]
	ds_read_b128 v[166:169], v221 offset:4608
	v_add_f32_e32 v241, v241, v49
	v_cvt_pk_bf16_f32 v42, v42, v43
	v_cvt_pk_bf16_f32 v43, v44, v45
	v_cvt_pk_bf16_f32 v44, v46, v47
	v_cvt_pk_bf16_f32 v45, v48, v49
	v_exp_f32_e32 v50, v50
	s_waitcnt lgkmcnt(4)
	v_mfma_f32_32x32x16_bf16 v[66:81], v[146:149], v[114:117], v[66:81]
	ds_read_b128 v[170:173], v221 offset:32
	v_exp_f32_e32 v51, v51
	v_exp_f32_e32 v52, v52
	v_exp_f32_e32 v53, v53
	v_mfma_f32_32x32x16_bf16 v[82:97], v[150:153], v[114:117], v[82:97]
	ds_read_b128 v[174:177], v221 offset:4640
	v_add_f32_e32 v231, v231, v50
	v_add_f32_e32 v232, v232, v51
	v_exp_f32_e32 v54, v54
	v_exp_f32_e32 v55, v55
	s_waitcnt lgkmcnt(4)
	v_mfma_f32_32x32x16_bf16 v[66:81], v[154:157], v[118:121], v[66:81]
	ds_read_b128 v[180:183], v221 offset:64
	v_add_f32_e32 v240, v240, v52
	v_add_f32_e32 v241, v241, v53
	v_exp_f32_e32 v56, v56
	v_exp_f32_e32 v57, v57
	v_mfma_f32_32x32x16_bf16 v[82:97], v[158:161], v[118:121], v[82:97]
	ds_read_b128 v[184:187], v221 offset:4672
	v_add_f32_e32 v231, v231, v54
	v_add_f32_e32 v232, v232, v55
	v_add_f32_e32 v240, v240, v56
	v_add_f32_e32 v241, v241, v57
	v_cvt_pk_bf16_f32 v50, v50, v51
	v_cvt_pk_bf16_f32 v51, v52, v53
	v_cvt_pk_bf16_f32 v52, v54, v55
	s_waitcnt lgkmcnt(4)
	v_mfma_f32_32x32x16_bf16 v[2:17], v[162:165], v[34:37], v[2:17]
	ds_read_b128 v[188:191], v221 offset:96
	v_cvt_pk_bf16_f32 v53, v56, v57
	v_exp_f32_e32 v58, v58
	v_exp_f32_e32 v59, v59
	v_exp_f32_e32 v60, v60
	v_mfma_f32_32x32x16_bf16 v[18:33], v[166:169], v[34:37], v[18:33]
	ds_read_b128 v[192:195], v221 offset:4704
	v_exp_f32_e32 v61, v61
	v_add_f32_e32 v231, v231, v58
	v_add_f32_e32 v232, v232, v59
	v_exp_f32_e32 v62, v62
	s_waitcnt lgkmcnt(4)
	v_mfma_f32_32x32x16_bf16 v[2:17], v[170:173], v[42:45], v[2:17]
	v_exp_f32_e32 v63, v63
	v_add_f32_e32 v240, v240, v60
	v_add_f32_e32 v241, v241, v61
	v_exp_f32_e32 v64, v64
	v_mfma_f32_32x32x16_bf16 v[18:33], v[174:177], v[42:45], v[18:33]
	s_waitcnt vmcnt(1)
	ds_write_b64 v225, v[216:217] offset:18432
	ds_write_b64 v225, v[218:219] offset:18448
	v_exp_f32_e32 v65, v65
	v_add_f32_e32 v231, v231, v62
	v_add_f32_e32 v232, v232, v63
	v_add_f32_e32 v240, v240, v64
	v_add_f32_e32 v241, v241, v65
	s_waitcnt lgkmcnt(4)
	v_mfma_f32_32x32x16_bf16 v[2:17], v[180:183], v[50:53], v[2:17]
	v_cvt_pk_bf16_f32 v58, v58, v59
	v_cvt_pk_bf16_f32 v59, v60, v61
	v_cvt_pk_bf16_f32 v60, v62, v63
	v_cvt_pk_bf16_f32 v61, v64, v65
	v_max3_f32 v234, v66, v67, v68
	v_max3_f32 v235, v82, v83, v84
	v_mfma_f32_32x32x16_bf16 v[18:33], v[184:187], v[50:53], v[18:33]
	v_max3_f32 v234, v234, v69, v70
	v_max3_f32 v235, v235, v85, v86
	v_max3_f32 v234, v234, v71, v72
	v_max3_f32 v235, v235, v87, v88
	v_max3_f32 v234, v234, v73, v74
	v_max3_f32 v235, v235, v89, v90
	v_max3_f32 v234, v234, v75, v76
	s_waitcnt lgkmcnt(2)
	v_mfma_f32_32x32x16_bf16 v[2:17], v[188:191], v[58:61], v[2:17]
	v_max3_f32 v235, v235, v91, v92
	v_max3_f32 v234, v234, v77, v78
	v_max3_f32 v235, v235, v93, v94
	v_max3_f32 v234, v234, v79, v80
	v_max3_f32 v235, v235, v95, v96
	v_max3_f32 v234, v234, v81, v97
	v_mfma_f32_32x32x16_bf16 v[18:33], v[192:195], v[58:61], v[18:33]
	v_max_f32_e32 v234, v234, v235
	v_mov_b32_e32 v235, v234
	s_nop 1
	v_permlane32_swap_b32_e32 v234, v235
	v_max_f32_e32 v233, v234, v235
	v_cmp_lt_f32_e32 vcc, 4.0, v233
	s_cbranch_vccz .Lmls_nr_t0
	s_nop 15
	v_max_f32_e32 v234, 0, v233
	v_exp_f32_e64 v235, -v234
	v_add_f32_e32 v230, v230, v234
	v_sub_f32_e32 v66, v66, v234
	v_sub_f32_e32 v67, v67, v234
	v_sub_f32_e32 v68, v68, v234
	v_sub_f32_e32 v69, v69, v234
	v_sub_f32_e32 v70, v70, v234
	v_sub_f32_e32 v71, v71, v234
	v_sub_f32_e32 v72, v72, v234
	v_sub_f32_e32 v73, v73, v234
	v_sub_f32_e32 v74, v74, v234
	v_sub_f32_e32 v75, v75, v234
	v_sub_f32_e32 v76, v76, v234
	v_sub_f32_e32 v77, v77, v234
	v_sub_f32_e32 v78, v78, v234
	v_sub_f32_e32 v79, v79, v234
	v_sub_f32_e32 v80, v80, v234
	v_sub_f32_e32 v81, v81, v234
	v_sub_f32_e32 v82, v82, v234
	v_sub_f32_e32 v83, v83, v234
	v_sub_f32_e32 v84, v84, v234
	v_sub_f32_e32 v85, v85, v234
	v_sub_f32_e32 v86, v86, v234
	v_sub_f32_e32 v87, v87, v234
	v_sub_f32_e32 v88, v88, v234
	v_sub_f32_e32 v89, v89, v234
	v_sub_f32_e32 v90, v90, v234
	v_sub_f32_e32 v91, v91, v234
	v_sub_f32_e32 v92, v92, v234
	v_sub_f32_e32 v93, v93, v234
	v_sub_f32_e32 v94, v94, v234
	v_sub_f32_e32 v95, v95, v234
	v_sub_f32_e32 v96, v96, v234
	v_sub_f32_e32 v97, v97, v234
	v_mul_f32_e32 v231, v231, v235
	v_mul_f32_e32 v232, v232, v235
	v_mul_f32_e32 v240, v240, v235
	v_mul_f32_e32 v241, v241, v235
	v_mul_f32_e32 v2, v2, v235
	v_mul_f32_e32 v3, v3, v235
	v_mul_f32_e32 v4, v4, v235
	v_mul_f32_e32 v5, v5, v235
	v_mul_f32_e32 v6, v6, v235
	v_mul_f32_e32 v7, v7, v235
	v_mul_f32_e32 v8, v8, v235
	v_mul_f32_e32 v9, v9, v235
	v_mul_f32_e32 v10, v10, v235
	v_mul_f32_e32 v11, v11, v235
	v_mul_f32_e32 v12, v12, v235
	v_mul_f32_e32 v13, v13, v235
	v_mul_f32_e32 v14, v14, v235
	v_mul_f32_e32 v15, v15, v235
	v_mul_f32_e32 v16, v16, v235
	v_mul_f32_e32 v17, v17, v235
	v_mul_f32_e32 v18, v18, v235
	v_mul_f32_e32 v19, v19, v235
	v_mul_f32_e32 v20, v20, v235
	v_mul_f32_e32 v21, v21, v235
	v_mul_f32_e32 v22, v22, v235
	v_mul_f32_e32 v23, v23, v235
	v_mul_f32_e32 v24, v24, v235
	v_mul_f32_e32 v25, v25, v235
	v_mul_f32_e32 v26, v26, v235
	v_mul_f32_e32 v27, v27, v235
	v_mul_f32_e32 v28, v28, v235
	v_mul_f32_e32 v29, v29, v235
	v_mul_f32_e32 v30, v30, v235
	v_mul_f32_e32 v31, v31, v235
	v_mul_f32_e32 v32, v32, v235
	v_mul_f32_e32 v33, v33, v235
	v_sub_f32_e32 v122, 0, v230
	v_mov_b32_e32 v123, v122
	v_mov_b32_e32 v124, v122
	v_mov_b32_e32 v125, v122
	v_mov_b32_e32 v126, v122
	v_mov_b32_e32 v127, v122
	v_mov_b32_e32 v128, v122
	v_mov_b32_e32 v129, v122
	v_mov_b32_e32 v130, v122
	v_mov_b32_e32 v131, v122
	v_mov_b32_e32 v132, v122
	v_mov_b32_e32 v133, v122
	v_mov_b32_e32 v134, v122
	v_mov_b32_e32 v135, v122
	v_mov_b32_e32 v136, v122
	v_mov_b32_e32 v137, v122
.Lmls_nr_t0:
	ds_read_b128 v[138:141], v220 offset:26624
	ds_read_b128 v[142:145], v220 offset:33280
	ds_read_b128 v[146:149], v220 offset:26656
	ds_read_b128 v[150:153], v220 offset:33312
	ds_read_b128 v[154:157], v220 offset:26688
	ds_read_b128 v[158:161], v220 offset:33344
	s_waitcnt lgkmcnt(6)
	s_barrier
	v_exp_f32_e32 v66, v66
	v_exp_f32_e32 v67, v67
	v_exp_f32_e32 v68, v68
	v_exp_f32_e32 v69, v69
	s_waitcnt lgkmcnt(4)
	v_mfma_f32_32x32x16_bf16 v[34:49], v[138:141], v[98:101], v[122:137]
	ds_read_b128 v[138:141], v220 offset:26720
	v_add_f32_e32 v231, v231, v66
	v_add_f32_e32 v232, v232, v67
	v_exp_f32_e32 v70, v70
	v_exp_f32_e32 v71, v71
	v_mfma_f32_32x32x16_bf16 v[50:65], v[142:145], v[98:101], v[122:137]
	ds_read_b128 v[142:145], v220 offset:33376
	v_add_f32_e32 v240, v240, v68
	v_add_f32_e32 v241, v241, v69
	v_exp_f32_e32 v72, v72
	v_exp_f32_e32 v73, v73
	s_waitcnt lgkmcnt(4)
	v_mfma_f32_32x32x16_bf16 v[34:49], v[146:149], v[102:105], v[34:49]
	ds_read_b128 v[146:149], v220 offset:26752
	v_add_f32_e32 v231, v231, v70
	v_add_f32_e32 v232, v232, v71
	v_add_f32_e32 v240, v240, v72
	v_add_f32_e32 v241, v241, v73
	v_cvt_pk_bf16_f32 v66, v66, v67
	v_cvt_pk_bf16_f32 v67, v68, v69
	v_mfma_f32_32x32x16_bf16 v[50:65], v[150:153], v[102:105], v[50:65]
	ds_read_b128 v[150:153], v220 offset:33408
	v_cvt_pk_bf16_f32 v68, v70, v71
	v_cvt_pk_bf16_f32 v69, v72, v73
	v_exp_f32_e32 v74, v74
	v_exp_f32_e32 v75, v75
	s_waitcnt lgkmcnt(4)
	v_mfma_f32_32x32x16_bf16 v[34:49], v[154:157], v[106:109], v[34:49]
	ds_read_b128 v[154:157], v220 offset:26784
	v_exp_f32_e32 v76, v76
	v_exp_f32_e32 v77, v77
	v_add_f32_e32 v231, v231, v74
	v_add_f32_e32 v232, v232, v75
	v_mfma_f32_32x32x16_bf16 v[50:65], v[158:161], v[106:109], v[50:65]
	ds_read_b128 v[158:161], v220 offset:33440
	v_exp_f32_e32 v78, v78
	v_exp_f32_e32 v79, v79
	v_add_f32_e32 v240, v240, v76
	v_add_f32_e32 v241, v241, v77
	v_exp_f32_e32 v80, v80
	s_waitcnt lgkmcnt(4)
	v_mfma_f32_32x32x16_bf16 v[34:49], v[138:141], v[110:113], v[34:49]
	ds_read_b128 v[162:165], v221 offset:9216
	v_exp_f32_e32 v81, v81
	v_add_f32_e32 v231, v231, v78
	v_add_f32_e32 v232, v232, v79
	v_add_f32_e32 v240, v240, v80
	v_mfma_f32_32x32x16_bf16 v[50:65], v[142:145], v[110:113], v[50:65]
	ds_read_b128 v[166:169], v221 offset:13824
	v_add_f32_e32 v241, v241, v81
	v_cvt_pk_bf16_f32 v74, v74, v75
	v_cvt_pk_bf16_f32 v75, v76, v77
	v_cvt_pk_bf16_f32 v76, v78, v79
	v_cvt_pk_bf16_f32 v77, v80, v81
	v_exp_f32_e32 v82, v82
	s_waitcnt lgkmcnt(4)
	v_mfma_f32_32x32x16_bf16 v[34:49], v[146:149], v[114:117], v[34:49]
	ds_read_b128 v[170:173], v221 offset:9248
	v_exp_f32_e32 v83, v83
	v_exp_f32_e32 v84, v84
	v_exp_f32_e32 v85, v85
	v_mfma_f32_32x32x16_bf16 v[50:65], v[150:153], v[114:117], v[50:65]
	ds_read_b128 v[174:177], v221 offset:13856
	v_add_f32_e32 v231, v231, v82
	v_add_f32_e32 v232, v232, v83
	v_exp_f32_e32 v86, v86
	v_exp_f32_e32 v87, v87
	s_waitcnt lgkmcnt(4)
	v_mfma_f32_32x32x16_bf16 v[34:49], v[154:157], v[118:121], v[34:49]
	ds_read_b128 v[180:183], v221 offset:9280
	v_add_f32_e32 v240, v240, v84
	v_add_f32_e32 v241, v241, v85
	v_exp_f32_e32 v88, v88
	v_exp_f32_e32 v89, v89
	v_mfma_f32_32x32x16_bf16 v[50:65], v[158:161], v[118:121], v[50:65]
	ds_read_b128 v[184:187], v221 offset:13888
	v_add_f32_e32 v231, v231, v86
	v_add_f32_e32 v232, v232, v87
	v_add_f32_e32 v240, v240, v88
	v_add_f32_e32 v241, v241, v89
	v_cvt_pk_bf16_f32 v82, v82, v83
	v_cvt_pk_bf16_f32 v83, v84, v85
	v_cvt_pk_bf16_f32 v84, v86, v87
	s_waitcnt lgkmcnt(4)
	v_mfma_f32_32x32x16_bf16 v[2:17], v[162:165], v[66:69], v[2:17]
	ds_read_b128 v[188:191], v221 offset:9312
	v_cvt_pk_bf16_f32 v85, v88, v89
	v_exp_f32_e32 v90, v90
	v_exp_f32_e32 v91, v91
	v_exp_f32_e32 v92, v92
	v_mfma_f32_32x32x16_bf16 v[18:33], v[166:169], v[66:69], v[18:33]
	ds_read_b128 v[192:195], v221 offset:13920
	v_exp_f32_e32 v93, v93
	v_add_f32_e32 v231, v231, v90
	v_add_f32_e32 v232, v232, v91
	v_exp_f32_e32 v94, v94
	s_waitcnt lgkmcnt(4)
	v_mfma_f32_32x32x16_bf16 v[2:17], v[170:173], v[74:77], v[2:17]
	v_exp_f32_e32 v95, v95
	v_add_f32_e32 v240, v240, v92
	v_add_f32_e32 v241, v241, v93
	v_exp_f32_e32 v96, v96
	v_mfma_f32_32x32x16_bf16 v[18:33], v[174:177], v[74:77], v[18:33]
	s_waitcnt vmcnt(0)
	ds_write_b64 v225, v[212:213] offset:27648
	ds_write_b64 v225, v[214:215] offset:27664
	v_exp_f32_e32 v97, v97
	v_add_f32_e32 v231, v231, v94
	v_add_f32_e32 v232, v232, v95
	v_add_f32_e32 v240, v240, v96
	v_add_f32_e32 v241, v241, v97
	s_waitcnt lgkmcnt(4)
	v_mfma_f32_32x32x16_bf16 v[2:17], v[180:183], v[82:85], v[2:17]
	v_cvt_pk_bf16_f32 v90, v90, v91
	v_cvt_pk_bf16_f32 v91, v92, v93
	v_cvt_pk_bf16_f32 v92, v94, v95
	v_cvt_pk_bf16_f32 v93, v96, v97
	v_max3_f32 v234, v34, v35, v36
	v_max3_f32 v235, v50, v51, v52
	v_mfma_f32_32x32x16_bf16 v[18:33], v[184:187], v[82:85], v[18:33]
	v_max3_f32 v234, v234, v37, v38
	v_max3_f32 v235, v235, v53, v54
	v_max3_f32 v234, v234, v39, v40
	v_max3_f32 v235, v235, v55, v56
	v_max3_f32 v234, v234, v41, v42
	v_max3_f32 v235, v235, v57, v58
	v_max3_f32 v234, v234, v43, v44
	s_waitcnt lgkmcnt(2)
	v_mfma_f32_32x32x16_bf16 v[2:17], v[188:191], v[90:93], v[2:17]
	v_max3_f32 v235, v235, v59, v60
	v_max3_f32 v234, v234, v45, v46
	v_max3_f32 v235, v235, v61, v62
	v_max3_f32 v234, v234, v47, v48
	v_max3_f32 v235, v235, v63, v64
	v_max3_f32 v234, v234, v49, v65
	v_mfma_f32_32x32x16_bf16 v[18:33], v[192:195], v[90:93], v[18:33]
	v_max_f32_e32 v234, v234, v235
	v_mov_b32_e32 v235, v234
	s_nop 1
	v_permlane32_swap_b32_e32 v234, v235
	v_max_f32_e32 v233, v234, v235
	v_cmp_lt_f32_e32 vcc, 4.0, v233
	s_cbranch_vccz .Lmls_nr_t1
	s_nop 15
	v_max_f32_e32 v234, 0, v233
	v_exp_f32_e64 v235, -v234
	v_add_f32_e32 v230, v230, v234
	v_sub_f32_e32 v34, v34, v234
	v_sub_f32_e32 v35, v35, v234
	v_sub_f32_e32 v36, v36, v234
	v_sub_f32_e32 v37, v37, v234
	v_sub_f32_e32 v38, v38, v234
	v_sub_f32_e32 v39, v39, v234
	v_sub_f32_e32 v40, v40, v234
	v_sub_f32_e32 v41, v41, v234
	v_sub_f32_e32 v42, v42, v234
	v_sub_f32_e32 v43, v43, v234
	v_sub_f32_e32 v44, v44, v234
	v_sub_f32_e32 v45, v45, v234
	v_sub_f32_e32 v46, v46, v234
	v_sub_f32_e32 v47, v47, v234
	v_sub_f32_e32 v48, v48, v234
	v_sub_f32_e32 v49, v49, v234
	v_sub_f32_e32 v50, v50, v234
	v_sub_f32_e32 v51, v51, v234
	v_sub_f32_e32 v52, v52, v234
	v_sub_f32_e32 v53, v53, v234
	v_sub_f32_e32 v54, v54, v234
	v_sub_f32_e32 v55, v55, v234
	v_sub_f32_e32 v56, v56, v234
	v_sub_f32_e32 v57, v57, v234
	v_sub_f32_e32 v58, v58, v234
	v_sub_f32_e32 v59, v59, v234
	v_sub_f32_e32 v60, v60, v234
	v_sub_f32_e32 v61, v61, v234
	v_sub_f32_e32 v62, v62, v234
	v_sub_f32_e32 v63, v63, v234
	v_sub_f32_e32 v64, v64, v234
	v_sub_f32_e32 v65, v65, v234
	v_mul_f32_e32 v231, v231, v235
	v_mul_f32_e32 v232, v232, v235
	v_mul_f32_e32 v240, v240, v235
	v_mul_f32_e32 v241, v241, v235
	v_mul_f32_e32 v2, v2, v235
	v_mul_f32_e32 v3, v3, v235
	v_mul_f32_e32 v4, v4, v235
	v_mul_f32_e32 v5, v5, v235
	v_mul_f32_e32 v6, v6, v235
	v_mul_f32_e32 v7, v7, v235
	v_mul_f32_e32 v8, v8, v235
	v_mul_f32_e32 v9, v9, v235
	v_mul_f32_e32 v10, v10, v235
	v_mul_f32_e32 v11, v11, v235
	v_mul_f32_e32 v12, v12, v235
	v_mul_f32_e32 v13, v13, v235
	v_mul_f32_e32 v14, v14, v235
	v_mul_f32_e32 v15, v15, v235
	v_mul_f32_e32 v16, v16, v235
	v_mul_f32_e32 v17, v17, v235
	v_mul_f32_e32 v18, v18, v235
	v_mul_f32_e32 v19, v19, v235
	v_mul_f32_e32 v20, v20, v235
	v_mul_f32_e32 v21, v21, v235
	v_mul_f32_e32 v22, v22, v235
	v_mul_f32_e32 v23, v23, v235
	v_mul_f32_e32 v24, v24, v235
	v_mul_f32_e32 v25, v25, v235
	v_mul_f32_e32 v26, v26, v235
	v_mul_f32_e32 v27, v27, v235
	v_mul_f32_e32 v28, v28, v235
	v_mul_f32_e32 v29, v29, v235
	v_mul_f32_e32 v30, v30, v235
	v_mul_f32_e32 v31, v31, v235
	v_mul_f32_e32 v32, v32, v235
	v_mul_f32_e32 v33, v33, v235
	v_sub_f32_e32 v122, 0, v230
	v_mov_b32_e32 v123, v122
	v_mov_b32_e32 v124, v122
	v_mov_b32_e32 v125, v122
	v_mov_b32_e32 v126, v122
	v_mov_b32_e32 v127, v122
	v_mov_b32_e32 v128, v122
	v_mov_b32_e32 v129, v122
	v_mov_b32_e32 v130, v122
	v_mov_b32_e32 v131, v122
	v_mov_b32_e32 v132, v122
	v_mov_b32_e32 v133, v122
	v_mov_b32_e32 v134, v122
	v_mov_b32_e32 v135, v122
	v_mov_b32_e32 v136, v122
	v_mov_b32_e32 v137, v122
.Lmls_nr_t1:
	ds_read_b128 v[138:141], v220 offset:39936
	ds_read_b128 v[142:145], v220 offset:46592
	ds_read_b128 v[146:149], v220 offset:39968
	ds_read_b128 v[150:153], v220 offset:46624
	ds_read_b128 v[154:157], v220 offset:40000
	ds_read_b128 v[158:161], v220 offset:46656
	s_waitcnt lgkmcnt(6)
	s_barrier
	global_load_dwordx2 v[200:201], v236, s[14:15] offset:0
	global_load_dwordx2 v[202:203], v236, s[14:15] offset:16
	global_load_dwordx2 v[204:205], v236, s[14:15] offset:32
	global_load_dwordx2 v[206:207], v236, s[14:15] offset:48
	global_load_dwordx2 v[208:209], v236, s[14:15] offset:64
	global_load_dwordx2 v[210:211], v236, s[14:15] offset:80
	global_load_dwordx2 v[212:213], v236, s[14:15] offset:96
	global_load_dwordx2 v[214:215], v236, s[14:15] offset:112
	v_exp_f32_e32 v34, v34
	v_exp_f32_e32 v35, v35
	v_exp_f32_e32 v36, v36
	v_exp_f32_e32 v37, v37
	s_waitcnt lgkmcnt(4)
	v_mfma_f32_32x32x16_bf16 v[66:81], v[138:141], v[98:101], v[122:137]
	ds_read_b128 v[138:141], v220 offset:40032
	v_add_f32_e32 v231, v231, v34
	v_add_f32_e32 v232, v232, v35
	v_exp_f32_e32 v38, v38
	v_exp_f32_e32 v39, v39
	v_mfma_f32_32x32x16_bf16 v[82:97], v[142:145], v[98:101], v[122:137]
	ds_read_b128 v[142:145], v220 offset:46688
	v_add_f32_e32 v240, v240, v36
	v_add_f32_e32 v241, v241, v37
	v_exp_f32_e32 v40, v40
	v_exp_f32_e32 v41, v41
	s_waitcnt lgkmcnt(4)
	v_mfma_f32_32x32x16_bf16 v[66:81], v[146:149], v[102:105], v[66:81]
	ds_read_b128 v[146:149], v220 offset:40064
	v_add_f32_e32 v231, v231, v38
	v_add_f32_e32 v232, v232, v39
	v_add_f32_e32 v240, v240, v40
	v_add_f32_e32 v241, v241, v41
	v_cvt_pk_bf16_f32 v34, v34, v35
	v_cvt_pk_bf16_f32 v35, v36, v37
	v_mfma_f32_32x32x16_bf16 v[82:97], v[150:153], v[102:105], v[82:97]
	ds_read_b128 v[150:153], v220 offset:46720
	v_cvt_pk_bf16_f32 v36, v38, v39
	v_cvt_pk_bf16_f32 v37, v40, v41
	v_exp_f32_e32 v42, v42
	v_exp_f32_e32 v43, v43
	s_waitcnt lgkmcnt(4)
	v_mfma_f32_32x32x16_bf16 v[66:81], v[154:157], v[106:109], v[66:81]
	ds_read_b128 v[154:157], v220 offset:40096
	v_exp_f32_e32 v44, v44
	v_exp_f32_e32 v45, v45
	v_add_f32_e32 v231, v231, v42
	v_add_f32_e32 v232, v232, v43
	v_mfma_f32_32x32x16_bf16 v[82:97], v[158:161], v[106:109], v[82:97]
	ds_read_b128 v[158:161], v220 offset:46752
	v_exp_f32_e32 v46, v46
	v_exp_f32_e32 v47, v47
	v_add_f32_e32 v240, v240, v44
	v_add_f32_e32 v241, v241, v45
	v_exp_f32_e32 v48, v48
	s_waitcnt lgkmcnt(4)
	v_mfma_f32_32x32x16_bf16 v[66:81], v[138:141], v[110:113], v[66:81]
	ds_read_b128 v[162:165], v221 offset:18432
	v_exp_f32_e32 v49, v49
	v_add_f32_e32 v231, v231, v46
	v_add_f32_e32 v232, v232, v47
	v_add_f32_e32 v240, v240, v48
	v_mfma_f32_32x32x16_bf16 v[82:97], v[142:145], v[110:113], v[82:97]
	ds_read_b128 v[166:169], v221 offset:23040
	v_add_f32_e32 v241, v241, v49
	v_cvt_pk_bf16_f32 v42, v42, v43
	v_cvt_pk_bf16_f32 v43, v44, v45
	v_cvt_pk_bf16_f32 v44, v46, v47
	v_cvt_pk_bf16_f32 v45, v48, v49
	v_exp_f32_e32 v50, v50
	s_waitcnt lgkmcnt(4)
	v_mfma_f32_32x32x16_bf16 v[66:81], v[146:149], v[114:117], v[66:81]
	ds_read_b128 v[170:173], v221 offset:18464
	v_exp_f32_e32 v51, v51
	v_exp_f32_e32 v52, v52
	v_exp_f32_e32 v53, v53
	v_mfma_f32_32x32x16_bf16 v[82:97], v[150:153], v[114:117], v[82:97]
	ds_read_b128 v[174:177], v221 offset:23072
	v_add_f32_e32 v231, v231, v50
	v_add_f32_e32 v232, v232, v51
	v_exp_f32_e32 v54, v54
	v_exp_f32_e32 v55, v55
	s_waitcnt lgkmcnt(4)
	v_mfma_f32_32x32x16_bf16 v[66:81], v[154:157], v[118:121], v[66:81]
	ds_read_b128 v[180:183], v221 offset:18496
	v_add_f32_e32 v240, v240, v52
	v_add_f32_e32 v241, v241, v53
	v_exp_f32_e32 v56, v56
	v_exp_f32_e32 v57, v57
	v_mfma_f32_32x32x16_bf16 v[82:97], v[158:161], v[118:121], v[82:97]
	ds_read_b128 v[184:187], v221 offset:23104
	v_add_f32_e32 v231, v231, v54
	v_add_f32_e32 v232, v232, v55
	v_add_f32_e32 v240, v240, v56
	v_add_f32_e32 v241, v241, v57
	v_cvt_pk_bf16_f32 v50, v50, v51
	v_cvt_pk_bf16_f32 v51, v52, v53
	v_cvt_pk_bf16_f32 v52, v54, v55
	s_waitcnt lgkmcnt(4)
	v_mfma_f32_32x32x16_bf16 v[2:17], v[162:165], v[34:37], v[2:17]
	ds_read_b128 v[188:191], v221 offset:18528
	v_cvt_pk_bf16_f32 v53, v56, v57
	v_exp_f32_e32 v58, v58
	v_exp_f32_e32 v59, v59
	v_exp_f32_e32 v60, v60
	v_mfma_f32_32x32x16_bf16 v[18:33], v[166:169], v[34:37], v[18:33]
	ds_read_b128 v[192:195], v221 offset:23136
	v_exp_f32_e32 v61, v61
	v_add_f32_e32 v231, v231, v58
	v_add_f32_e32 v232, v232, v59
	v_exp_f32_e32 v62, v62
	s_waitcnt lgkmcnt(4)
	v_mfma_f32_32x32x16_bf16 v[2:17], v[170:173], v[42:45], v[2:17]
	v_exp_f32_e32 v63, v63
	v_add_f32_e32 v240, v240, v60
	v_add_f32_e32 v241, v241, v61
	v_exp_f32_e32 v64, v64
	v_mfma_f32_32x32x16_bf16 v[18:33], v[174:177], v[42:45], v[18:33]
	v_exp_f32_e32 v65, v65
	v_add_f32_e32 v231, v231, v62
	v_add_f32_e32 v232, v232, v63
	v_add_f32_e32 v240, v240, v64
	v_add_f32_e32 v241, v241, v65
	s_waitcnt lgkmcnt(2)
	v_mfma_f32_32x32x16_bf16 v[2:17], v[180:183], v[50:53], v[2:17]
	v_cvt_pk_bf16_f32 v58, v58, v59
	v_cvt_pk_bf16_f32 v59, v60, v61
	v_cvt_pk_bf16_f32 v60, v62, v63
	v_cvt_pk_bf16_f32 v61, v64, v65
	v_max3_f32 v234, v66, v67, v68
	v_max3_f32 v235, v82, v83, v84
	v_mfma_f32_32x32x16_bf16 v[18:33], v[184:187], v[50:53], v[18:33]
	v_max3_f32 v234, v234, v69, v70
	v_max3_f32 v235, v235, v85, v86
	v_max3_f32 v234, v234, v71, v72
	v_max3_f32 v235, v235, v87, v88
	v_max3_f32 v234, v234, v73, v74
	v_max3_f32 v235, v235, v89, v90
	v_max3_f32 v234, v234, v75, v76
	s_waitcnt lgkmcnt(0)
	v_mfma_f32_32x32x16_bf16 v[2:17], v[188:191], v[58:61], v[2:17]
	v_max3_f32 v235, v235, v91, v92
	v_max3_f32 v234, v234, v77, v78
	v_max3_f32 v235, v235, v93, v94
	v_max3_f32 v234, v234, v79, v80
	v_max3_f32 v235, v235, v95, v96
	v_max3_f32 v234, v234, v81, v97
	v_mfma_f32_32x32x16_bf16 v[18:33], v[192:195], v[58:61], v[18:33]
	v_max_f32_e32 v234, v234, v235
	v_mov_b32_e32 v235, v234
	s_nop 1
	v_permlane32_swap_b32_e32 v234, v235
	v_max_f32_e32 v233, v234, v235
	v_cmp_lt_f32_e32 vcc, 4.0, v233
	s_cbranch_vccz .Lmls_nr_t2
	s_nop 15
	v_max_f32_e32 v234, 0, v233
	v_exp_f32_e64 v235, -v234
	v_add_f32_e32 v230, v230, v234
	v_sub_f32_e32 v66, v66, v234
	v_sub_f32_e32 v67, v67, v234
	v_sub_f32_e32 v68, v68, v234
	v_sub_f32_e32 v69, v69, v234
	v_sub_f32_e32 v70, v70, v234
	v_sub_f32_e32 v71, v71, v234
	v_sub_f32_e32 v72, v72, v234
	v_sub_f32_e32 v73, v73, v234
	v_sub_f32_e32 v74, v74, v234
	v_sub_f32_e32 v75, v75, v234
	v_sub_f32_e32 v76, v76, v234
	v_sub_f32_e32 v77, v77, v234
	v_sub_f32_e32 v78, v78, v234
	v_sub_f32_e32 v79, v79, v234
	v_sub_f32_e32 v80, v80, v234
	v_sub_f32_e32 v81, v81, v234
	v_sub_f32_e32 v82, v82, v234
	v_sub_f32_e32 v83, v83, v234
	v_sub_f32_e32 v84, v84, v234
	v_sub_f32_e32 v85, v85, v234
	v_sub_f32_e32 v86, v86, v234
	v_sub_f32_e32 v87, v87, v234
	v_sub_f32_e32 v88, v88, v234
	v_sub_f32_e32 v89, v89, v234
	v_sub_f32_e32 v90, v90, v234
	v_sub_f32_e32 v91, v91, v234
	v_sub_f32_e32 v92, v92, v234
	v_sub_f32_e32 v93, v93, v234
	v_sub_f32_e32 v94, v94, v234
	v_sub_f32_e32 v95, v95, v234
	v_sub_f32_e32 v96, v96, v234
	v_sub_f32_e32 v97, v97, v234
	v_mul_f32_e32 v231, v231, v235
	v_mul_f32_e32 v232, v232, v235
	v_mul_f32_e32 v240, v240, v235
	v_mul_f32_e32 v241, v241, v235
	v_mul_f32_e32 v2, v2, v235
	v_mul_f32_e32 v3, v3, v235
	v_mul_f32_e32 v4, v4, v235
	v_mul_f32_e32 v5, v5, v235
	v_mul_f32_e32 v6, v6, v235
	v_mul_f32_e32 v7, v7, v235
	v_mul_f32_e32 v8, v8, v235
	v_mul_f32_e32 v9, v9, v235
	v_mul_f32_e32 v10, v10, v235
	v_mul_f32_e32 v11, v11, v235
	v_mul_f32_e32 v12, v12, v235
	v_mul_f32_e32 v13, v13, v235
	v_mul_f32_e32 v14, v14, v235
	v_mul_f32_e32 v15, v15, v235
	v_mul_f32_e32 v16, v16, v235
	v_mul_f32_e32 v17, v17, v235
	v_mul_f32_e32 v18, v18, v235
	v_mul_f32_e32 v19, v19, v235
	v_mul_f32_e32 v20, v20, v235
	v_mul_f32_e32 v21, v21, v235
	v_mul_f32_e32 v22, v22, v235
	v_mul_f32_e32 v23, v23, v235
	v_mul_f32_e32 v24, v24, v235
	v_mul_f32_e32 v25, v25, v235
	v_mul_f32_e32 v26, v26, v235
	v_mul_f32_e32 v27, v27, v235
	v_mul_f32_e32 v28, v28, v235
	v_mul_f32_e32 v29, v29, v235
	v_mul_f32_e32 v30, v30, v235
	v_mul_f32_e32 v31, v31, v235
	v_mul_f32_e32 v32, v32, v235
	v_mul_f32_e32 v33, v33, v235
	v_sub_f32_e32 v122, 0, v230
	v_mov_b32_e32 v123, v122
	v_mov_b32_e32 v124, v122
	v_mov_b32_e32 v125, v122
	v_mov_b32_e32 v126, v122
	v_mov_b32_e32 v127, v122
	v_mov_b32_e32 v128, v122
	v_mov_b32_e32 v129, v122
	v_mov_b32_e32 v130, v122
	v_mov_b32_e32 v131, v122
	v_mov_b32_e32 v132, v122
	v_mov_b32_e32 v133, v122
	v_mov_b32_e32 v134, v122
	v_mov_b32_e32 v135, v122
	v_mov_b32_e32 v136, v122
	v_mov_b32_e32 v137, v122
.Lmls_nr_t2:
	s_waitcnt lgkmcnt(0)
	s_barrier
	ds_read_b128 v[162:165], v221 offset:27648
	ds_read_b128 v[166:169], v221 offset:32256
	ds_read_b128 v[170:173], v221 offset:27680
	v_exp_f32_e32 v66, v66
	v_exp_f32_e32 v67, v67
	v_exp_f32_e32 v68, v68
	v_exp_f32_e32 v69, v69
	v_add_f32_e32 v231, v231, v66
	v_add_f32_e32 v232, v232, v67
	v_exp_f32_e32 v70, v70
	v_exp_f32_e32 v71, v71
	v_add_f32_e32 v240, v240, v68
	v_add_f32_e32 v241, v241, v69
	v_exp_f32_e32 v72, v72
	v_exp_f32_e32 v73, v73
	v_add_f32_e32 v231, v231, v70
	v_add_f32_e32 v232, v232, v71
	v_add_f32_e32 v240, v240, v72
	v_add_f32_e32 v241, v241, v73
	v_cvt_pk_bf16_f32 v66, v66, v67
	v_cvt_pk_bf16_f32 v67, v68, v69
	v_cvt_pk_bf16_f32 v68, v70, v71
	v_cvt_pk_bf16_f32 v69, v72, v73
	s_waitcnt lgkmcnt(1)
	s_nop 0
	v_mfma_f32_32x32x16_bf16 v[2:17], v[162:165], v[66:69], v[2:17]
	ds_read_b128 v[174:177], v221 offset:32288
	v_mfma_f32_32x32x16_bf16 v[18:33], v[166:169], v[66:69], v[18:33]
	ds_read_b128 v[180:183], v221 offset:27712
	v_exp_f32_e32 v74, v74
	v_exp_f32_e32 v75, v75
	v_exp_f32_e32 v76, v76
	v_exp_f32_e32 v77, v77
	v_add_f32_e32 v231, v231, v74
	v_add_f32_e32 v232, v232, v75
	v_exp_f32_e32 v78, v78
	v_exp_f32_e32 v79, v79
	v_add_f32_e32 v240, v240, v76
	v_add_f32_e32 v241, v241, v77
	v_exp_f32_e32 v80, v80
	v_exp_f32_e32 v81, v81
	v_add_f32_e32 v231, v231, v78
	v_add_f32_e32 v232, v232, v79
	v_add_f32_e32 v240, v240, v80
	v_add_f32_e32 v241, v241, v81
	v_cvt_pk_bf16_f32 v74, v74, v75
	v_cvt_pk_bf16_f32 v75, v76, v77
	v_cvt_pk_bf16_f32 v76, v78, v79
	v_cvt_pk_bf16_f32 v77, v80, v81
	s_waitcnt lgkmcnt(1)
	s_nop 0
	v_mfma_f32_32x32x16_bf16 v[2:17], v[170:173], v[74:77], v[2:17]
	ds_read_b128 v[184:187], v221 offset:32320
	v_mfma_f32_32x32x16_bf16 v[18:33], v[174:177], v[74:77], v[18:33]
	ds_read_b128 v[188:191], v221 offset:27744
	v_exp_f32_e32 v82, v82
	v_exp_f32_e32 v83, v83
	v_exp_f32_e32 v84, v84
	v_exp_f32_e32 v85, v85
	v_add_f32_e32 v231, v231, v82
	v_add_f32_e32 v232, v232, v83
	v_exp_f32_e32 v86, v86
	v_exp_f32_e32 v87, v87
	v_add_f32_e32 v240, v240, v84
	v_add_f32_e32 v241, v241, v85
	v_exp_f32_e32 v88, v88
	v_exp_f32_e32 v89, v89
	v_add_f32_e32 v231, v231, v86
	v_add_f32_e32 v232, v232, v87
	v_add_f32_e32 v240, v240, v88
	v_add_f32_e32 v241, v241, v89
	v_cvt_pk_bf16_f32 v82, v82, v83
	v_cvt_pk_bf16_f32 v83, v84, v85
	v_cvt_pk_bf16_f32 v84, v86, v87
	v_cvt_pk_bf16_f32 v85, v88, v89
	s_waitcnt lgkmcnt(1)
	s_nop 0
	v_mfma_f32_32x32x16_bf16 v[2:17], v[180:183], v[82:85], v[2:17]
	ds_read_b128 v[192:195], v221 offset:32352
	v_mfma_f32_32x32x16_bf16 v[18:33], v[184:187], v[82:85], v[18:33]
	v_exp_f32_e32 v90, v90
	v_exp_f32_e32 v91, v91
	v_exp_f32_e32 v92, v92
	v_exp_f32_e32 v93, v93
	v_add_f32_e32 v231, v231, v90
	v_add_f32_e32 v232, v232, v91
	v_exp_f32_e32 v94, v94
	v_exp_f32_e32 v95, v95
	v_add_f32_e32 v240, v240, v92
	v_add_f32_e32 v241, v241, v93
	v_exp_f32_e32 v96, v96
	v_exp_f32_e32 v97, v97
	v_add_f32_e32 v231, v231, v94
	v_add_f32_e32 v232, v232, v95
	v_add_f32_e32 v240, v240, v96
	v_add_f32_e32 v241, v241, v97
	v_cvt_pk_bf16_f32 v90, v90, v91
	v_cvt_pk_bf16_f32 v91, v92, v93
	v_cvt_pk_bf16_f32 v92, v94, v95
	v_cvt_pk_bf16_f32 v93, v96, v97
	s_waitcnt lgkmcnt(0)
	s_nop 0
	v_mfma_f32_32x32x16_bf16 v[2:17], v[188:191], v[90:93], v[2:17]
	v_mfma_f32_32x32x16_bf16 v[18:33], v[192:195], v[90:93], v[18:33]
	s_waitcnt lgkmcnt(0)
	s_barrier
	v_add_f32_e32 v231, v231, v240
	v_add_f32_e32 v232, v232, v241
	v_add_f32_e32 v231, v231, v232
	v_mov_b32_e32 v235, v231
	s_nop 1
	v_permlane32_swap_b32_e32 v231, v235
	v_add_f32_e32 v234, v231, v235
	v_div_scale_f32 v235, s[22:23], v234, v234, 1.0
	v_rcp_f32_e32 v179, v235
	v_div_scale_f32 v196, vcc, 1.0, v234, 1.0
	v_fma_f32 v197, -v235, v179, 1.0
	v_fmac_f32_e32 v179, v197, v179
	v_mul_f32_e32 v197, v196, v179
	v_fma_f32 v199, -v235, v197, v196
	v_fmac_f32_e32 v197, v199, v179
	v_fma_f32 v235, -v235, v197, v196
	v_div_fmas_f32 v235, v235, v179, v197
	v_div_fixup_f32 v234, v235, v234, 1.0
	s_nop 15
	v_mul_f32_e32 v2, v2, v234
	v_mul_f32_e32 v3, v3, v234
	v_mul_f32_e32 v4, v4, v234
	v_mul_f32_e32 v5, v5, v234
	v_mul_f32_e32 v6, v6, v234
	v_mul_f32_e32 v7, v7, v234
	v_mul_f32_e32 v8, v8, v234
	v_mul_f32_e32 v9, v9, v234
	v_mul_f32_e32 v10, v10, v234
	v_mul_f32_e32 v11, v11, v234
	v_mul_f32_e32 v12, v12, v234
	v_mul_f32_e32 v13, v13, v234
	v_mul_f32_e32 v14, v14, v234
	v_mul_f32_e32 v15, v15, v234
	v_mul_f32_e32 v16, v16, v234
	v_mul_f32_e32 v17, v17, v234
	v_mul_f32_e32 v18, v18, v234
	v_mul_f32_e32 v19, v19, v234
	v_mul_f32_e32 v20, v20, v234
	v_mul_f32_e32 v21, v21, v234
	v_mul_f32_e32 v22, v22, v234
	v_mul_f32_e32 v23, v23, v234
	v_mul_f32_e32 v24, v24, v234
	v_mul_f32_e32 v25, v25, v234
	v_mul_f32_e32 v26, v26, v234
	v_mul_f32_e32 v27, v27, v234
	v_mul_f32_e32 v28, v28, v234
	v_mul_f32_e32 v29, v29, v234
	v_mul_f32_e32 v30, v30, v234
	v_mul_f32_e32 v31, v31, v234
	v_mul_f32_e32 v32, v32, v234
	v_mul_f32_e32 v33, v33, v234
	s_waitcnt vmcnt(0)
	v_lshlrev_b32_e32 v179, 16, v200
	v_and_b32_e32 v196, 0xffff0000, v200
	v_lshlrev_b32_e32 v197, 16, v201
	v_and_b32_e32 v199, 0xffff0000, v201
	v_mul_f32_e32 v2, v2, v179
	v_mul_f32_e32 v3, v3, v196
	v_mul_f32_e32 v4, v4, v197
	v_mul_f32_e32 v5, v5, v199
	v_cvt_pk_bf16_f32 v200, v2, v3
	v_cvt_pk_bf16_f32 v201, v4, v5
	global_store_dwordx2 v236, v[200:201], s[14:15] offset:0
	v_lshlrev_b32_e32 v179, 16, v202
	v_and_b32_e32 v196, 0xffff0000, v202
	v_lshlrev_b32_e32 v197, 16, v203
	v_and_b32_e32 v199, 0xffff0000, v203
	v_mul_f32_e32 v6, v6, v179
	v_mul_f32_e32 v7, v7, v196
	v_mul_f32_e32 v8, v8, v197
	v_mul_f32_e32 v9, v9, v199
	v_cvt_pk_bf16_f32 v202, v6, v7
	v_cvt_pk_bf16_f32 v203, v8, v9
	global_store_dwordx2 v236, v[202:203], s[14:15] offset:16
	v_lshlrev_b32_e32 v179, 16, v204
	v_and_b32_e32 v196, 0xffff0000, v204
	v_lshlrev_b32_e32 v197, 16, v205
	v_and_b32_e32 v199, 0xffff0000, v205
	v_mul_f32_e32 v10, v10, v179
	v_mul_f32_e32 v11, v11, v196
	v_mul_f32_e32 v12, v12, v197
	v_mul_f32_e32 v13, v13, v199
	v_cvt_pk_bf16_f32 v204, v10, v11
	v_cvt_pk_bf16_f32 v205, v12, v13
	global_store_dwordx2 v236, v[204:205], s[14:15] offset:32
	v_lshlrev_b32_e32 v179, 16, v206
	v_and_b32_e32 v196, 0xffff0000, v206
	v_lshlrev_b32_e32 v197, 16, v207
	v_and_b32_e32 v199, 0xffff0000, v207
	v_mul_f32_e32 v14, v14, v179
	v_mul_f32_e32 v15, v15, v196
	v_mul_f32_e32 v16, v16, v197
	v_mul_f32_e32 v17, v17, v199
	v_cvt_pk_bf16_f32 v206, v14, v15
	v_cvt_pk_bf16_f32 v207, v16, v17
	global_store_dwordx2 v236, v[206:207], s[14:15] offset:48
	v_lshlrev_b32_e32 v179, 16, v208
	v_and_b32_e32 v196, 0xffff0000, v208
	v_lshlrev_b32_e32 v197, 16, v209
	v_and_b32_e32 v199, 0xffff0000, v209
	v_mul_f32_e32 v18, v18, v179
	v_mul_f32_e32 v19, v19, v196
	v_mul_f32_e32 v20, v20, v197
	v_mul_f32_e32 v21, v21, v199
	v_cvt_pk_bf16_f32 v208, v18, v19
	v_cvt_pk_bf16_f32 v209, v20, v21
	global_store_dwordx2 v236, v[208:209], s[14:15] offset:64
	v_lshlrev_b32_e32 v179, 16, v210
	v_and_b32_e32 v196, 0xffff0000, v210
	v_lshlrev_b32_e32 v197, 16, v211
	v_and_b32_e32 v199, 0xffff0000, v211
	v_mul_f32_e32 v22, v22, v179
	v_mul_f32_e32 v23, v23, v196
	v_mul_f32_e32 v24, v24, v197
	v_mul_f32_e32 v25, v25, v199
	v_cvt_pk_bf16_f32 v210, v22, v23
	v_cvt_pk_bf16_f32 v211, v24, v25
	global_store_dwordx2 v236, v[210:211], s[14:15] offset:80
	v_lshlrev_b32_e32 v179, 16, v212
	v_and_b32_e32 v196, 0xffff0000, v212
	v_lshlrev_b32_e32 v197, 16, v213
	v_and_b32_e32 v199, 0xffff0000, v213
	v_mul_f32_e32 v26, v26, v179
	v_mul_f32_e32 v27, v27, v196
	v_mul_f32_e32 v28, v28, v197
	v_mul_f32_e32 v29, v29, v199
	v_cvt_pk_bf16_f32 v212, v26, v27
	v_cvt_pk_bf16_f32 v213, v28, v29
	global_store_dwordx2 v236, v[212:213], s[14:15] offset:96
	v_lshlrev_b32_e32 v179, 16, v214
	v_and_b32_e32 v196, 0xffff0000, v214
	v_lshlrev_b32_e32 v197, 16, v215
	v_and_b32_e32 v199, 0xffff0000, v215
	v_mul_f32_e32 v30, v30, v179
	v_mul_f32_e32 v31, v31, v196
	v_mul_f32_e32 v32, v32, v197
	v_mul_f32_e32 v33, v33, v199
	v_cvt_pk_bf16_f32 v214, v30, v31
	v_cvt_pk_bf16_f32 v215, v32, v33
	global_store_dwordx2 v236, v[214:215], s[14:15] offset:112
	s_add_i32 s2, s2, s88
	s_cmpk_lt_i32 s2, 0x200
	s_cbranch_scc1 .Lmla_restart
